# combo9: saddr DMA + barrier hand-off trims + tail move, WITHOUT the early B0 reads (simpler variant A/B)
# speedup vs baseline: 1.0033x; 1.0033x over previous
; #define PG8_STAGE(bufoff, gbase, voff) do { _Pragma("unroll") for (int _i = 0; _i < 2; ++_i) \
;     __builtin_amdgcn_global_load_lds((const unsigned*)((const char*)(gbase) + (voff)[_i]), (LAS unsigned*)(lds + (bufoff) + ldsw + _i * 8192), 16, 0, 0); } while (0)
; #define PG8_LDA(dst, b, h) do { _Pragma("unroll") for (int m = 0; m < 4; ++m) _Pragma("unroll") for (int k = 0; k < 2; ++k) dst[m][k] = *(const LAS bf16x8*)(lds + PG8_SA(b, h) + aoff + m * 2048 + k * 1024); } while (0)
; #define PG8_LDB(dst, b, h) do { _Pragma("unroll") for (int n = 0; n < 2; ++n) _Pragma("unroll") for (int k = 0; k < 2; ++k) dst[n][k] = *(const LAS bf16x8*)(lds + PG8_SB(b, h) + boff + n * 2048 + k * 1024); } while (0)
; #define PG8_MMA(ai, bj, At, Bt) do { __builtin_amdgcn_s_setprio(1); _Pragma("unroll") for (int m = 0; m < 4; ++m) _Pragma("unroll") for (int n = 0; n < 2; ++n) _Pragma("unroll") for (int k = 0; k < 2; ++k) \
;     acc[ai][bj][m][n] = __builtin_amdgcn_mfma_f32_16x16x32_bf16(Bt[n][k], At[m][k], acc[ai][bj][m][n], 0, 0, 0); __builtin_amdgcn_s_setprio(0); } while (0)
; #define PG8_WAIT_V(n) asm volatile("s_waitcnt vmcnt(" #n ")" ::: "memory")
; #define PG8_WAIT_L(n) asm volatile("s_waitcnt lgkmcnt(" #n ")" ::: "memory")
; #define PG8_BAR __builtin_amdgcn_s_barrier()
; #define PG8_SCHED __builtin_amdgcn_sched_barrier(0)
; template <class Epi, class Sched = StaticOrder>
; DI void gemm_phase(LAS unsigned char* lds, const Gemm g, const Sched& S, const Epi& E) {
;     ...
;     for (int t = 0; t < nt; t += 2) {
;       const bool last = (t == nt - 2);
;       const char* a1 = cA + (size_t)(t + 1) * kstep;
;       const char* a2 = last ? nA : cA + (size_t)(t + 2) * kstep; const char* b2 = last ? nB : cB + (size_t)(t + 2) * kstep;
;       const char* a3 = a2 + kstep; const char* b3 = b2 + kstep;
;       PG8_LDB(B0, 0, 0); PG8_SCHED; PG8_LDA(At, 0, 0); PG8_STAGE(PG8_SA(1, 1), a1 + hstep, voffA);
;       PG8_WAIT_L(8); PG8_BAR; PG8_WAIT_L(0); PG8_MMA(0, 0, At, B0); PG8_BAR; PG8_SCHED;
;       PG8_LDB(B1, 0, 1); PG8_STAGE(PG8_SB(0, 0), b2, voffB);
;       PG8_BAR; PG8_WAIT_L(0); PG8_MMA(0, 1, At, B1); PG8_BAR;
;       PG8_LDA(At, 0, 1); PG8_STAGE(PG8_SA(0, 0), a2, voffA);
;       PG8_BAR; PG8_WAIT_L(0); PG8_MMA(1, 0, At, B0); PG8_BAR; PG8_SCHED;
;       PG8_STAGE(PG8_SB(0, 1), b2 + hstep, voffB);
;       PG8_WAIT_V(6); PG8_BAR; PG8_MMA(1, 1, At, B1); PG8_BAR;
.LBB0_346:
	ds_read_b128 v[128:131], v173
	ds_read_b128 v[132:135], v173 offset:1024
	ds_read_b128 v[154:157], v173 offset:2048
	ds_read_b128 v[158:161], v173 offset:3072
	s_add_u32 s8, s6, 0xfff80080
	s_addc_u32 s9, s7, -1
	s_cmp_eq_u32 s52, 28
	s_cselect_b32 s11, s31, s9
	s_cselect_b32 s10, s42, s8
	s_cselect_b32 s9, s29, s45
	s_cselect_b32 s8, s43, s44
	s_add_i32 m0, s48, 0xc000
	ds_read_b128 v[162:165], v174
	ds_read_b128 v[166:169], v174 offset:1024
	ds_read_b128 v[178:181], v174 offset:2048
	ds_read_b128 v[182:185], v174 offset:3072
	ds_read_b128 v[186:189], v174 offset:4096
	ds_read_b128 v[190:193], v174 offset:5120
	ds_read_b128 v[194:197], v174 offset:6144
	ds_read_b128 v[198:201], v174 offset:7168
	global_load_lds_dwordx4 v146, s[6:7]
	s_add_i32 m0, s48, 0xe000
	s_nop 0
	global_load_lds_dwordx4 v148, s[6:7]
	s_waitcnt lgkmcnt(0)
	s_setprio 1
	s_barrier
	v_mfma_f32_16x16x32_bf16 v[124:127], v[128:131], v[162:165], v[124:127]
	v_mfma_f32_16x16x32_bf16 v[120:123], v[154:157], v[162:165], v[120:123]
	v_mfma_f32_16x16x32_bf16 v[108:111], v[128:131], v[178:181], v[108:111]
	v_mfma_f32_16x16x32_bf16 v[104:107], v[154:157], v[178:181], v[104:107]
	v_mfma_f32_16x16x32_bf16 v[100:103], v[128:131], v[186:189], v[100:103]
	v_mfma_f32_16x16x32_bf16 v[92:95], v[154:157], v[186:189], v[92:95]
	v_mfma_f32_16x16x32_bf16 v[84:87], v[128:131], v[194:197], v[84:87]
	v_mfma_f32_16x16x32_bf16 v[76:79], v[154:157], v[194:197], v[76:79]
	v_mfma_f32_16x16x32_bf16 v[124:127], v[132:135], v[166:169], v[124:127]
	v_mfma_f32_16x16x32_bf16 v[120:123], v[158:161], v[166:169], v[120:123]
	v_mfma_f32_16x16x32_bf16 v[108:111], v[132:135], v[182:185], v[108:111]
	v_mfma_f32_16x16x32_bf16 v[104:107], v[158:161], v[182:185], v[104:107]
	v_mfma_f32_16x16x32_bf16 v[100:103], v[132:135], v[190:193], v[100:103]
	v_mfma_f32_16x16x32_bf16 v[92:95], v[158:161], v[190:193], v[92:95]
	v_mfma_f32_16x16x32_bf16 v[84:87], v[132:135], v[198:201], v[84:87]
	v_mfma_f32_16x16x32_bf16 v[76:79], v[158:161], v[198:201], v[76:79]
	s_barrier
	s_setprio 0
	s_add_i32 s53, s65, s41
	s_add_u32 s98, s8, 0x80
	s_addc_u32 s99, s9, 0
	s_add_u32 s100, s10, 0x80
	s_addc_u32 s101, s11, 0
	s_mov_b32 m0, s53
	ds_read_b128 v[202:205], v175
	ds_read_b128 v[206:209], v175 offset:1024
	ds_read_b128 v[212:215], v175 offset:2048
	ds_read_b128 v[216:219], v175 offset:3072
	global_load_lds_dwordx4 v140, s[8:9]
	s_add_i32 m0, s53, 0x2000
	s_nop 0
	global_load_lds_dwordx4 v136, s[8:9]
	s_waitcnt lgkmcnt(0)
	s_setprio 1
	s_barrier
	v_mfma_f32_16x16x32_bf16 v[116:119], v[202:205], v[162:165], v[116:119]
	v_mfma_f32_16x16x32_bf16 v[112:115], v[212:215], v[162:165], v[112:115]
	v_mfma_f32_16x16x32_bf16 v[96:99], v[202:205], v[178:181], v[96:99]
	v_mfma_f32_16x16x32_bf16 v[88:91], v[212:215], v[178:181], v[88:91]
	v_mfma_f32_16x16x32_bf16 v[80:83], v[202:205], v[186:189], v[80:83]
	v_mfma_f32_16x16x32_bf16 v[72:75], v[212:215], v[186:189], v[72:75]
	v_mfma_f32_16x16x32_bf16 v[68:71], v[202:205], v[194:197], v[68:71]
	v_mfma_f32_16x16x32_bf16 v[64:67], v[212:215], v[194:197], v[64:67]
	v_mfma_f32_16x16x32_bf16 v[116:119], v[206:209], v[166:169], v[116:119]
	v_mfma_f32_16x16x32_bf16 v[112:115], v[216:219], v[166:169], v[112:115]
	v_mfma_f32_16x16x32_bf16 v[96:99], v[206:209], v[182:185], v[96:99]
	v_mfma_f32_16x16x32_bf16 v[88:91], v[216:219], v[182:185], v[88:91]
	v_mfma_f32_16x16x32_bf16 v[80:83], v[206:209], v[190:193], v[80:83]
	v_mfma_f32_16x16x32_bf16 v[72:75], v[216:219], v[190:193], v[72:75]
	v_mfma_f32_16x16x32_bf16 v[68:71], v[206:209], v[198:201], v[68:71]
	v_mfma_f32_16x16x32_bf16 v[64:67], v[216:219], v[198:201], v[64:67]
	s_barrier
	s_setprio 0
	s_mov_b32 m0, s48
	ds_read_b128 v[162:165], v174 offset:16384
	ds_read_b128 v[166:169], v174 offset:17408
	ds_read_b128 v[178:181], v174 offset:18432
	ds_read_b128 v[182:185], v174 offset:19456
	ds_read_b128 v[186:189], v174 offset:20480
	ds_read_b128 v[190:193], v174 offset:21504
	ds_read_b128 v[194:197], v174 offset:22528
	ds_read_b128 v[198:201], v174 offset:23552
	global_load_lds_dwordx4 v142, s[10:11]
	s_mov_b32 m0, s49
	s_nop 0
	global_load_lds_dwordx4 v138, s[10:11]
	s_waitcnt lgkmcnt(0)
	s_setprio 1
	s_barrier
	v_mfma_f32_16x16x32_bf16 v[60:63], v[128:131], v[162:165], v[60:63]
	v_mfma_f32_16x16x32_bf16 v[56:59], v[154:157], v[162:165], v[56:59]
	v_mfma_f32_16x16x32_bf16 v[52:55], v[128:131], v[178:181], v[52:55]
	v_mfma_f32_16x16x32_bf16 v[44:47], v[154:157], v[178:181], v[44:47]
	v_mfma_f32_16x16x32_bf16 v[36:39], v[128:131], v[186:189], v[36:39]
	v_mfma_f32_16x16x32_bf16 v[28:31], v[154:157], v[186:189], v[28:31]
	v_mfma_f32_16x16x32_bf16 v[20:23], v[128:131], v[194:197], v[20:23]
	v_mfma_f32_16x16x32_bf16 v[12:15], v[154:157], v[194:197], v[12:15]
	v_mfma_f32_16x16x32_bf16 v[60:63], v[132:135], v[166:169], v[60:63]
	v_mfma_f32_16x16x32_bf16 v[56:59], v[158:161], v[166:169], v[56:59]
	v_mfma_f32_16x16x32_bf16 v[52:55], v[132:135], v[182:185], v[52:55]
	v_mfma_f32_16x16x32_bf16 v[44:47], v[158:161], v[182:185], v[44:47]
	v_mfma_f32_16x16x32_bf16 v[36:39], v[132:135], v[190:193], v[36:39]
	v_mfma_f32_16x16x32_bf16 v[28:31], v[158:161], v[190:193], v[28:31]
	v_mfma_f32_16x16x32_bf16 v[20:23], v[132:135], v[198:201], v[20:23]
	v_mfma_f32_16x16x32_bf16 v[12:15], v[158:161], v[198:201], v[12:15]
	s_barrier
	s_setprio 0
	s_add_u32 s54, s8, 0x80000
	s_addc_u32 s55, s9, 0
	s_add_i32 s53, s72, s41
	s_mov_b32 m0, s53
	s_nop 0
	global_load_lds_dwordx4 v140, s[54:55]
	s_add_i32 m0, s53, 0x2000
	s_nop 0
	global_load_lds_dwordx4 v136, s[54:55]
	s_waitcnt vmcnt(6)
	s_setprio 1
	s_barrier
; #define PG8_STAGE(bufoff, gbase, voff) do { _Pragma("unroll") for (int _i = 0; _i < 2; ++_i) \
;     __builtin_amdgcn_global_load_lds((const unsigned*)((const char*)(gbase) + (voff)[_i]), (LAS unsigned*)(lds + (bufoff) + ldsw + _i * 8192), 16, 0, 0); } while (0)
; #define PG8_LDA(dst, b, h) do { _Pragma("unroll") for (int m = 0; m < 4; ++m) _Pragma("unroll") for (int k = 0; k < 2; ++k) dst[m][k] = *(const LAS bf16x8*)(lds + PG8_SA(b, h) + aoff + m * 2048 + k * 1024); } while (0)
; #define PG8_LDB(dst, b, h) do { _Pragma("unroll") for (int n = 0; n < 2; ++n) _Pragma("unroll") for (int k = 0; k < 2; ++k) dst[n][k] = *(const LAS bf16x8*)(lds + PG8_SB(b, h) + boff + n * 2048 + k * 1024); } while (0)
; #define PG8_MMA(ai, bj, At, Bt) do { __builtin_amdgcn_s_setprio(1); _Pragma("unroll") for (int m = 0; m < 4; ++m) _Pragma("unroll") for (int n = 0; n < 2; ++n) _Pragma("unroll") for (int k = 0; k < 2; ++k) \
;     acc[ai][bj][m][n] = __builtin_amdgcn_mfma_f32_16x16x32_bf16(Bt[n][k], At[m][k], acc[ai][bj][m][n], 0, 0, 0); __builtin_amdgcn_s_setprio(0); } while (0)
; #define PG8_WAIT_V(n) asm volatile("s_waitcnt vmcnt(" #n ")" ::: "memory")
; #define PG8_WAIT_L(n) asm volatile("s_waitcnt lgkmcnt(" #n ")" ::: "memory")
; #define PG8_BAR __builtin_amdgcn_s_barrier()
; #define PG8_SCHED __builtin_amdgcn_sched_barrier(0)
; template <class Epi, class Sched = StaticOrder>
; DI void gemm_phase(LAS unsigned char* lds, const Gemm g, const Sched& S, const Epi& E) {
;     ...
;       PG8_WAIT_V(6); PG8_BAR; PG8_MMA(1, 1, At, B1); PG8_BAR;
;       PG8_LDB(B0, 1, 0); PG8_SCHED; PG8_LDA(At, 1, 0); PG8_STAGE(PG8_SA(0, 1), a2 + hstep, voffA);
;       PG8_WAIT_L(8); PG8_BAR; PG8_WAIT_L(0); PG8_MMA(0, 0, At, B0); PG8_BAR; PG8_SCHED;
;       PG8_LDB(B1, 1, 1); PG8_STAGE(PG8_SB(1, 0), b3, voffB);
;       PG8_BAR; PG8_WAIT_L(0); PG8_MMA(0, 1, At, B1); PG8_BAR;
;       PG8_LDA(At, 1, 1); PG8_STAGE(PG8_SA(1, 0), a3, voffA);
;       PG8_BAR; PG8_WAIT_L(0); PG8_MMA(1, 0, At, B0); PG8_BAR; PG8_SCHED;
	v_mfma_f32_16x16x32_bf16 v[48:51], v[202:205], v[162:165], v[48:51]
	v_mfma_f32_16x16x32_bf16 v[40:43], v[212:215], v[162:165], v[40:43]
	v_mfma_f32_16x16x32_bf16 v[32:35], v[202:205], v[178:181], v[32:35]
	v_mfma_f32_16x16x32_bf16 v[24:27], v[212:215], v[178:181], v[24:27]
	v_mfma_f32_16x16x32_bf16 v[16:19], v[202:205], v[186:189], v[16:19]
	v_mfma_f32_16x16x32_bf16 v[8:11], v[212:215], v[186:189], v[8:11]
	v_mfma_f32_16x16x32_bf16 v[4:7], v[202:205], v[194:197], v[4:7]
	v_mfma_f32_16x16x32_bf16 v[0:3], v[212:215], v[194:197], v[0:3]
	v_mfma_f32_16x16x32_bf16 v[48:51], v[206:209], v[166:169], v[48:51]
	v_mfma_f32_16x16x32_bf16 v[40:43], v[216:219], v[166:169], v[40:43]
	v_mfma_f32_16x16x32_bf16 v[32:35], v[206:209], v[182:185], v[32:35]
	v_mfma_f32_16x16x32_bf16 v[24:27], v[216:219], v[182:185], v[24:27]
	v_mfma_f32_16x16x32_bf16 v[16:19], v[206:209], v[190:193], v[16:19]
	v_mfma_f32_16x16x32_bf16 v[8:11], v[216:219], v[190:193], v[8:11]
	v_mfma_f32_16x16x32_bf16 v[4:7], v[206:209], v[198:201], v[4:7]
	v_mfma_f32_16x16x32_bf16 v[0:3], v[216:219], v[198:201], v[0:3]
	s_barrier
	s_setprio 0
	s_add_i32 s53, 0, 0x18000
	v_add_u32_e32 v158, s53, v171
	ds_read_b128 v[128:131], v158
	ds_read_b128 v[132:135], v158 offset:1024
	ds_read_b128 v[154:157], v158 offset:2048
	ds_read_b128 v[158:161], v158 offset:3072
	s_add_u32 s10, s10, 0x80000
	s_addc_u32 s11, s11, 0
	s_mov_b32 m0, s50
	ds_read_b128 v[162:165], v174 offset:32768
	ds_read_b128 v[166:169], v174 offset:33792
	ds_read_b128 v[178:181], v174 offset:34816
	ds_read_b128 v[182:185], v174 offset:35840
	ds_read_b128 v[186:189], v174 offset:36864
	ds_read_b128 v[190:193], v174 offset:37888
	ds_read_b128 v[194:197], v174 offset:38912
	ds_read_b128 v[198:201], v174 offset:39936
	global_load_lds_dwordx4 v142, s[10:11]
	s_mov_b32 m0, s51
	s_nop 0
	global_load_lds_dwordx4 v138, s[10:11]
	s_waitcnt lgkmcnt(0)
	s_setprio 1
	s_barrier
	v_mfma_f32_16x16x32_bf16 v[124:127], v[128:131], v[162:165], v[124:127]
	v_mfma_f32_16x16x32_bf16 v[120:123], v[154:157], v[162:165], v[120:123]
	v_mfma_f32_16x16x32_bf16 v[108:111], v[128:131], v[178:181], v[108:111]
	v_mfma_f32_16x16x32_bf16 v[104:107], v[154:157], v[178:181], v[104:107]
	v_mfma_f32_16x16x32_bf16 v[100:103], v[128:131], v[186:189], v[100:103]
	v_mfma_f32_16x16x32_bf16 v[92:95], v[154:157], v[186:189], v[92:95]
	v_mfma_f32_16x16x32_bf16 v[84:87], v[128:131], v[194:197], v[84:87]
	v_mfma_f32_16x16x32_bf16 v[76:79], v[154:157], v[194:197], v[76:79]
	v_mfma_f32_16x16x32_bf16 v[124:127], v[132:135], v[166:169], v[124:127]
	v_mfma_f32_16x16x32_bf16 v[120:123], v[158:161], v[166:169], v[120:123]
	v_mfma_f32_16x16x32_bf16 v[108:111], v[132:135], v[182:185], v[108:111]
	v_mfma_f32_16x16x32_bf16 v[104:107], v[158:161], v[182:185], v[104:107]
	v_mfma_f32_16x16x32_bf16 v[100:103], v[132:135], v[190:193], v[100:103]
	v_mfma_f32_16x16x32_bf16 v[92:95], v[158:161], v[190:193], v[92:95]
	v_mfma_f32_16x16x32_bf16 v[84:87], v[132:135], v[198:201], v[84:87]
	v_mfma_f32_16x16x32_bf16 v[76:79], v[158:161], v[198:201], v[76:79]
	s_barrier
	s_setprio 0
	s_add_i32 s10, 0, 0x1c000
	s_add_i32 s11, s53, s41
	v_add_u32_e32 v177, s10, v171
	s_mov_b32 m0, s11
	ds_read_b128 v[202:205], v177
	ds_read_b128 v[206:209], v177 offset:1024
	ds_read_b128 v[212:215], v177 offset:2048
	ds_read_b128 v[216:219], v177 offset:3072
	global_load_lds_dwordx4 v140, s[98:99]
	s_add_i32 m0, s11, 0x2000
	s_nop 0
	global_load_lds_dwordx4 v136, s[98:99]
	s_waitcnt lgkmcnt(0)
	s_setprio 1
	s_barrier
	v_mfma_f32_16x16x32_bf16 v[116:119], v[202:205], v[162:165], v[116:119]
	v_mfma_f32_16x16x32_bf16 v[112:115], v[212:215], v[162:165], v[112:115]
	v_mfma_f32_16x16x32_bf16 v[96:99], v[202:205], v[178:181], v[96:99]
	v_mfma_f32_16x16x32_bf16 v[88:91], v[212:215], v[178:181], v[88:91]
	v_mfma_f32_16x16x32_bf16 v[80:83], v[202:205], v[186:189], v[80:83]
	v_mfma_f32_16x16x32_bf16 v[72:75], v[212:215], v[186:189], v[72:75]
	v_mfma_f32_16x16x32_bf16 v[68:71], v[202:205], v[194:197], v[68:71]
	v_mfma_f32_16x16x32_bf16 v[64:67], v[212:215], v[194:197], v[64:67]
	v_mfma_f32_16x16x32_bf16 v[116:119], v[206:209], v[166:169], v[116:119]
	v_mfma_f32_16x16x32_bf16 v[112:115], v[216:219], v[166:169], v[112:115]
	v_mfma_f32_16x16x32_bf16 v[96:99], v[206:209], v[182:185], v[96:99]
	v_mfma_f32_16x16x32_bf16 v[88:91], v[216:219], v[182:185], v[88:91]
	v_mfma_f32_16x16x32_bf16 v[80:83], v[206:209], v[190:193], v[80:83]
	v_mfma_f32_16x16x32_bf16 v[72:75], v[216:219], v[190:193], v[72:75]
	v_mfma_f32_16x16x32_bf16 v[68:71], v[206:209], v[198:201], v[68:71]
	v_mfma_f32_16x16x32_bf16 v[64:67], v[216:219], v[198:201], v[64:67]
	s_barrier
	s_setprio 0
	s_mov_b32 m0, s56
	ds_read_b128 v[162:165], v174 offset:49152
	ds_read_b128 v[166:169], v174 offset:50176
	ds_read_b128 v[178:181], v174 offset:51200
	ds_read_b128 v[182:185], v174 offset:52224
	ds_read_b128 v[186:189], v174 offset:53248
	ds_read_b128 v[190:193], v174 offset:54272
	ds_read_b128 v[194:197], v174 offset:55296
	ds_read_b128 v[198:201], v174 offset:56320
	global_load_lds_dwordx4 v142, s[100:101]
	s_mov_b32 m0, s57
	s_nop 0
	global_load_lds_dwordx4 v138, s[100:101]
	s_waitcnt lgkmcnt(0)
	s_setprio 1
	s_barrier
; #define PG8_STAGE(bufoff, gbase, voff) do { _Pragma("unroll") for (int _i = 0; _i < 2; ++_i) \
;     __builtin_amdgcn_global_load_lds((const unsigned*)((const char*)(gbase) + (voff)[_i]), (LAS unsigned*)(lds + (bufoff) + ldsw + _i * 8192), 16, 0, 0); } while (0)
; #define PG8_MMA(ai, bj, At, Bt) do { __builtin_amdgcn_s_setprio(1); _Pragma("unroll") for (int m = 0; m < 4; ++m) _Pragma("unroll") for (int n = 0; n < 2; ++n) _Pragma("unroll") for (int k = 0; k < 2; ++k) \
;     acc[ai][bj][m][n] = __builtin_amdgcn_mfma_f32_16x16x32_bf16(Bt[n][k], At[m][k], acc[ai][bj][m][n], 0, 0, 0); __builtin_amdgcn_s_setprio(0); } while (0)
; #define PG8_WAIT_V(n) asm volatile("s_waitcnt vmcnt(" #n ")" ::: "memory")
; #define PG8_WAIT_L(n) asm volatile("s_waitcnt lgkmcnt(" #n ")" ::: "memory")
; #define PG8_BAR __builtin_amdgcn_s_barrier()
; #define PG8_SCHED __builtin_amdgcn_sched_barrier(0)
; DI float row_rstd(const float* ssq, int row, int fq) {
;   const f32x4 a = *(const f32x4*)(ssq + (size_t)row * 32 + fq * 8), b = *(const f32x4*)(ssq + (size_t)row * 32 + fq * 8 + 4);
;   float sm = ((a[0] + a[1]) + (a[2] + a[3])) + ((b[0] + b[1]) + (b[2] + b[3]));
;   sm += __shfl_xor(sm, 16); sm += __shfl_xor(sm, 32);
;   return rsqrtf(sm * (1.0f / 2048.f) + 1e-6f);
; template <class Epi, class Sched = StaticOrder>
; DI void gemm_phase(LAS unsigned char* lds, const Gemm g, const Sched& S, const Epi& E) {
;     ...
;       PG8_BAR; PG8_WAIT_L(0); PG8_MMA(1, 0, At, B0); PG8_BAR; PG8_SCHED;
;       PG8_STAGE(PG8_SB(1, 1), b3 + hstep, voffB);
;       PG8_WAIT_V(6); PG8_BAR; PG8_MMA(1, 1, At, B1); PG8_BAR;
;     }
;     E(acc, cur, wr, wc, fr, fq);
	v_mfma_f32_16x16x32_bf16 v[60:63], v[128:131], v[162:165], v[60:63]
	v_mfma_f32_16x16x32_bf16 v[56:59], v[154:157], v[162:165], v[56:59]
	v_mfma_f32_16x16x32_bf16 v[52:55], v[128:131], v[178:181], v[52:55]
	v_mfma_f32_16x16x32_bf16 v[44:47], v[154:157], v[178:181], v[44:47]
	v_mfma_f32_16x16x32_bf16 v[36:39], v[128:131], v[186:189], v[36:39]
	v_mfma_f32_16x16x32_bf16 v[28:31], v[154:157], v[186:189], v[28:31]
	v_mfma_f32_16x16x32_bf16 v[20:23], v[128:131], v[194:197], v[20:23]
	v_mfma_f32_16x16x32_bf16 v[12:15], v[154:157], v[194:197], v[12:15]
	v_mfma_f32_16x16x32_bf16 v[60:63], v[132:135], v[166:169], v[60:63]
	v_mfma_f32_16x16x32_bf16 v[56:59], v[158:161], v[166:169], v[56:59]
	v_mfma_f32_16x16x32_bf16 v[52:55], v[132:135], v[182:185], v[52:55]
	v_mfma_f32_16x16x32_bf16 v[44:47], v[158:161], v[182:185], v[44:47]
	v_mfma_f32_16x16x32_bf16 v[36:39], v[132:135], v[190:193], v[36:39]
	v_mfma_f32_16x16x32_bf16 v[28:31], v[158:161], v[190:193], v[28:31]
	v_mfma_f32_16x16x32_bf16 v[20:23], v[132:135], v[198:201], v[20:23]
	v_mfma_f32_16x16x32_bf16 v[12:15], v[158:161], v[198:201], v[12:15]
	s_barrier
	s_setprio 0
	s_add_u32 s8, s8, 0x80080
	s_addc_u32 s9, s9, 0
	s_add_i32 s10, s10, s41
	s_mov_b32 m0, s10
	s_nop 0
	global_load_lds_dwordx4 v140, s[8:9]
	s_add_i32 m0, s10, 0x2000
	s_nop 0
	global_load_lds_dwordx4 v136, s[8:9]
	s_waitcnt vmcnt(6)
	s_add_i32 s52, s52, 2
	s_add_u32 s6, s6, 0x100
	s_addc_u32 s7, s7, 0
	s_add_u32 s44, s44, 0x100
	s_addc_u32 s45, s45, 0
	s_cmp_gt_u32 s52, 29
	s_setprio 1
	s_barrier
	v_mfma_f32_16x16x32_bf16 v[48:51], v[202:205], v[162:165], v[48:51]
	v_mfma_f32_16x16x32_bf16 v[40:43], v[212:215], v[162:165], v[40:43]
	v_mfma_f32_16x16x32_bf16 v[32:35], v[202:205], v[178:181], v[32:35]
	v_mfma_f32_16x16x32_bf16 v[24:27], v[212:215], v[178:181], v[24:27]
	v_mfma_f32_16x16x32_bf16 v[16:19], v[202:205], v[186:189], v[16:19]
	v_mfma_f32_16x16x32_bf16 v[8:11], v[212:215], v[186:189], v[8:11]
	v_mfma_f32_16x16x32_bf16 v[4:7], v[202:205], v[194:197], v[4:7]
	v_mfma_f32_16x16x32_bf16 v[0:3], v[212:215], v[194:197], v[0:3]
	v_mfma_f32_16x16x32_bf16 v[48:51], v[206:209], v[166:169], v[48:51]
	v_mfma_f32_16x16x32_bf16 v[40:43], v[216:219], v[166:169], v[40:43]
	v_mfma_f32_16x16x32_bf16 v[32:35], v[206:209], v[182:185], v[32:35]
	v_mfma_f32_16x16x32_bf16 v[24:27], v[216:219], v[182:185], v[24:27]
	v_mfma_f32_16x16x32_bf16 v[16:19], v[206:209], v[190:193], v[16:19]
	v_mfma_f32_16x16x32_bf16 v[8:11], v[216:219], v[190:193], v[8:11]
	v_mfma_f32_16x16x32_bf16 v[4:7], v[206:209], v[198:201], v[4:7]
	v_mfma_f32_16x16x32_bf16 v[0:3], v[216:219], v[198:201], v[0:3]
	s_barrier
	s_setprio 0
	s_cbranch_scc0 .LBB0_346
	v_lshl_add_u32 v168, s4, 8, v170
	v_ashrrev_i32_e32 v169, 31, v168
	v_or_b32_e32 v154, 16, v168
	v_lshlrev_b64 v[128:129], 7, v[168:169]
	v_ashrrev_i32_e32 v155, 31, v154
	v_lshl_add_u64 v[128:129], v[144:145], 0, v[128:129]
	v_lshlrev_b64 v[156:157], 7, v[154:155]
	global_load_dwordx4 v[132:135], v[128:129], off
	s_nop 0
	global_load_dwordx4 v[128:131], v[128:129], off offset:16
	v_lshl_add_u64 v[156:157], v[144:145], 0, v[156:157]
	global_load_dwordx4 v[178:181], v[156:157], off
	global_load_dwordx4 v[182:185], v[156:157], off offset:16
	v_or_b32_e32 v160, 32, v168
	v_ashrrev_i32_e32 v161, 31, v160
	v_lshlrev_b64 v[156:157], 7, v[160:161]
	v_lshl_add_u64 v[156:157], v[144:145], 0, v[156:157]
	global_load_dwordx4 v[186:189], v[156:157], off
	global_load_dwordx4 v[190:193], v[156:157], off offset:16
	v_or_b32_e32 v156, 48, v168
	v_ashrrev_i32_e32 v157, 31, v156
	v_lshlrev_b64 v[158:159], 7, v[156:157]
	v_lshl_add_u64 v[158:159], v[144:145], 0, v[158:159]
	global_load_dwordx4 v[194:197], v[158:159], off
	global_load_dwordx4 v[198:201], v[158:159], off offset:16
	v_add_u32_e32 v164, 0x80, v168
	v_ashrrev_i32_e32 v165, 31, v164
	v_lshlrev_b64 v[158:159], 7, v[164:165]
	v_lshl_add_u64 v[158:159], v[144:145], 0, v[158:159]
	global_load_dwordx4 v[202:205], v[158:159], off
	global_load_dwordx4 v[206:209], v[158:159], off offset:16
	v_add_u32_e32 v158, 0x90, v168
	v_ashrrev_i32_e32 v159, 31, v158
	v_lshlrev_b64 v[162:163], 7, v[158:159]
	v_lshl_add_u64 v[162:163], v[144:145], 0, v[162:163]
	global_load_dwordx4 v[212:215], v[162:163], off
	global_load_dwordx4 v[216:219], v[162:163], off offset:16
	v_add_u32_e32 v166, 0xa0, v168
	v_ashrrev_i32_e32 v167, 31, v166
	v_lshlrev_b64 v[162:163], 7, v[166:167]
	v_lshl_add_u64 v[162:163], v[144:145], 0, v[162:163]
	global_load_dwordx4 v[220:223], v[162:163], off
	global_load_dwordx4 v[224:227], v[162:163], off offset:16
	v_add_u32_e32 v162, 0xb0, v168
	v_ashrrev_i32_e32 v163, 31, v162
	v_lshlrev_b64 v[228:229], 7, v[162:163]
	v_lshl_add_u64 v[232:233], v[144:145], 0, v[228:229]
	global_load_dwordx4 v[228:231], v[232:233], off
	s_nop 0
	global_load_dwordx4 v[232:235], v[232:233], off offset:16
	s_waitcnt vmcnt(0)
	v_mov_b32_e32 v236, v132
	v_mov_b32_e32 v237, v128
	v_mov_b32_e32 v128, v133
	v_mov_b32_e32 v132, v134
	v_mov_b32_e32 v133, v130
	v_mov_b32_e32 v130, v135
	v_pk_add_f32 v[130:131], v[132:133], v[130:131]
	v_mov_b32_e32 v132, v178
	v_mov_b32_e32 v133, v182
	v_mov_b32_e32 v182, v179
	v_mov_b32_e32 v134, v180
	v_mov_b32_e32 v135, v184
	v_mov_b32_e32 v184, v181
	v_pk_add_f32 v[128:129], v[236:237], v[128:129]
	v_pk_add_f32 v[132:133], v[132:133], v[182:183]
	v_pk_add_f32 v[134:135], v[134:135], v[184:185]
	v_pk_add_f32 v[128:129], v[128:129], v[130:131]
	v_pk_add_f32 v[130:131], v[132:133], v[134:135]
	v_mov_b32_e32 v133, v128
	v_mov_b32_e32 v132, v130
	v_and_b32_e32 v130, 64, v176
	v_add_u32_e32 v155, 64, v130
	v_xor_b32_e32 v130, 16, v176
	v_cmp_lt_i32_e32 vcc, v130, v155
	v_mov_b32_e32 v128, v131
	v_pk_add_f32 v[128:129], v[132:133], v[128:129]
	v_cndmask_b32_e32 v130, v176, v130, vcc
	v_lshlrev_b32_e32 v157, 2, v130
	ds_bpermute_b32 v131, v157, v129
	ds_bpermute_b32 v130, v157, v128
	v_mov_b32_e32 v178, v186
	v_mov_b32_e32 v179, v190
	v_mov_b32_e32 v190, v187
	v_mov_b32_e32 v186, v194
	s_waitcnt lgkmcnt(0)
; DI unsigned pack2(float lo, float hi) { f32x2 v = {lo, hi}; bf16v2 r = __builtin_convertvector(v, bf16v2); return __builtin_bit_cast(unsigned, r); }
; DI float row_rstd(const float* ssq, int row, int fq) {
;   const f32x4 a = *(const f32x4*)(ssq + (size_t)row * 32 + fq * 8), b = *(const f32x4*)(ssq + (size_t)row * 32 + fq * 8 + 4);
;   float sm = ((a[0] + a[1]) + (a[2] + a[3])) + ((b[0] + b[1]) + (b[2] + b[3]));
;   sm += __shfl_xor(sm, 16); sm += __shfl_xor(sm, 32);
;   return rsqrtf(sm * (1.0f / 2048.f) + 1e-6f);
;   DI void operator()(const f32x4 (&acc)[2][2][4][2], const Unit& u, int wr, int wc, int fr, int fq) const {
;     const int row0 = u.pm * BM + wr * 64 + fr, col0 = u.pn * BM + wc * 32 + 8 * fq;
;     float rsv[2][4];
; #pragma unroll
;     for (int ai = 0; ai < 2; ++ai)
; #pragma unroll
;       for (int m = 0; m < 4; ++m) rsv[ai][m] = row_rstd(ssq, row0 + ai * HALF + m * 16, fq);
; #pragma unroll
;     for (int ai = 0; ai < 2; ++ai)
; #pragma unroll
;       for (int m = 0; m < 4; ++m) {
;         const int row = row0 + ai * HALF + m * 16;
;         const float rs = rsv[ai][m];
;         bf16_t* rowp = O + (size_t)row * ldc + col0;
; #pragma unroll
;         for (int bj = 0; bj < 2; ++bj) {
;           const f32x4 v0 = acc[ai][bj][m][0] * rs, v1 = acc[ai][bj][m][1] * rs;
;           u32x4 w; w.x = pack2(v0[0], v0[1]); w.y = pack2(v0[2], v0[3]); w.z = pack2(v1[0], v1[1]); w.w = pack2(v1[2], v1[3]);
;           *(u32x4*)(rowp + bj * HALF) = w;
	v_pk_add_f32 v[128:129], v[128:129], v[130:131]
	v_xor_b32_e32 v130, 32, v176
	v_cmp_lt_i32_e32 vcc, v130, v155
	v_mov_b32_e32 v187, v198
	v_mov_b32_e32 v198, v195
	v_cndmask_b32_e32 v130, v176, v130, vcc
	v_lshlrev_b32_e32 v155, 2, v130
	ds_bpermute_b32 v131, v155, v129
	ds_bpermute_b32 v130, v155, v128
	v_pk_add_f32 v[182:183], v[186:187], v[198:199]
	v_mov_b32_e32 v180, v188
	v_mov_b32_e32 v181, v192
	v_mov_b32_e32 v192, v189
	s_waitcnt lgkmcnt(0)
	v_pk_add_f32 v[128:129], v[128:129], v[130:131]
	v_mov_b64_e32 v[130:131], s[26:27]
	v_pk_fma_f32 v[128:129], v[128:129], s[24:25], v[130:131] op_sel_hi:[1,0,0]
	v_mov_b32_e32 v188, v196
	v_mul_f32_e32 v159, 0x4b800000, v129
	v_cmp_gt_f32_e32 vcc, s73, v129
	v_mov_b32_e32 v189, v200
	v_mov_b32_e32 v200, v197
	v_cndmask_b32_e32 v129, v129, v159, vcc
	v_rsq_f32_e32 v129, v129
	v_pk_add_f32 v[178:179], v[178:179], v[190:191]
	v_pk_add_f32 v[180:181], v[180:181], v[192:193]
	v_pk_add_f32 v[184:185], v[188:189], v[200:201]
	v_mul_f32_e32 v159, 0x45800000, v129
	v_cndmask_b32_e32 v198, v129, v159, vcc
	v_pk_mul_f32 v[126:127], v[126:127], v[198:199] op_sel_hi:[1,0]
	v_pk_mul_f32 v[124:125], v[124:125], v[198:199] op_sel_hi:[1,0]
	v_pk_mul_f32 v[122:123], v[122:123], v[198:199] op_sel_hi:[1,0]
	v_pk_mul_f32 v[120:121], v[120:121], v[198:199] op_sel_hi:[1,0]
	v_cvt_pk_bf16_f32 v124, v124, v125
	v_cvt_pk_bf16_f32 v125, v126, v127
	v_cvt_pk_bf16_f32 v127, v122, v123
	v_lshl_or_b32 v122, s5, 8, v172
	v_cvt_pk_bf16_f32 v126, v120, v121
	v_ashrrev_i32_e32 v123, 31, v122
	v_mov_b64_e32 v[120:121], s[2:3]
	v_mad_i64_i32 v[168:169], s[4:5], v168, s76, v[120:121]
	v_lshlrev_b64 v[122:123], 1, v[122:123]
	v_lshl_add_u64 v[168:169], v[168:169], 0, v[122:123]
	global_store_dwordx4 v[168:169], v[124:127], off
	v_mov_b32_e32 v194, v202
	v_mov_b32_e32 v195, v206
	v_pk_add_f32 v[124:125], v[178:179], v[180:181]
	v_pk_add_f32 v[126:127], v[182:183], v[184:185]
	v_mov_b32_e32 v179, v124
	v_mov_b32_e32 v178, v126
	v_mov_b32_e32 v124, v127
	v_pk_add_f32 v[124:125], v[178:179], v[124:125]
	ds_bpermute_b32 v127, v157, v125
	ds_bpermute_b32 v126, v157, v124
	v_mov_b32_e32 v206, v203
	v_mov_b32_e32 v196, v204
	v_mov_b32_e32 v197, v208
	v_mov_b32_e32 v208, v205
	v_mov_b32_e32 v202, v212
	v_mov_b32_e32 v203, v216
	v_mov_b32_e32 v216, v213
	v_mov_b32_e32 v204, v214
	v_mov_b32_e32 v205, v218
	v_mov_b32_e32 v218, v215
	v_pk_add_f32 v[186:187], v[194:195], v[206:207]
	v_pk_add_f32 v[188:189], v[196:197], v[208:209]
	v_pk_add_f32 v[190:191], v[202:203], v[216:217]
	v_pk_add_f32 v[192:193], v[204:205], v[218:219]
	v_pk_mul_f32 v[178:179], v[114:115], v[198:199] op_sel_hi:[1,0]
	s_waitcnt lgkmcnt(0)
	v_pk_add_f32 v[114:115], v[124:125], v[126:127]
	v_pk_add_f32 v[126:127], v[186:187], v[188:189]
	v_pk_add_f32 v[180:181], v[190:191], v[192:193]
	v_mov_b32_e32 v183, v126
	v_mov_b32_e32 v182, v180
	v_mov_b32_e32 v126, v181
	v_pk_add_f32 v[126:127], v[182:183], v[126:127]
	ds_bpermute_b32 v125, v155, v115
	ds_bpermute_b32 v124, v155, v114
	ds_bpermute_b32 v181, v157, v127
	ds_bpermute_b32 v180, v157, v126
	v_mul_f32_e32 v129, 0x4b800000, v128
	v_cmp_gt_f32_e32 vcc, s73, v128
	s_waitcnt lgkmcnt(2)
	v_pk_add_f32 v[114:115], v[114:115], v[124:125]
	v_mov_b32_e32 v194, v220
	s_waitcnt lgkmcnt(0)
	v_pk_add_f32 v[124:125], v[126:127], v[180:181]
	ds_bpermute_b32 v127, v155, v125
	ds_bpermute_b32 v126, v155, v124
	v_pk_fma_f32 v[114:115], v[114:115], s[24:25], v[130:131] op_sel_hi:[1,0,0]
	v_cndmask_b32_e32 v159, v128, v129, vcc
	v_mul_f32_e32 v128, 0x4b800000, v115
	v_cmp_gt_f32_e64 s[4:5], s73, v115
	v_cmp_gt_f32_e64 s[6:7], s73, v114
	v_mov_b32_e32 v195, v224
	v_cndmask_b32_e64 v161, v115, v128, s[4:5]
	v_mul_f32_e32 v115, 0x4b800000, v114
	v_mov_b32_e32 v224, v221
	v_mov_b32_e32 v196, v222
	v_mov_b32_e32 v197, v226
	v_mov_b32_e32 v226, v223
	v_cndmask_b32_e64 v163, v114, v115, s[6:7]
	s_waitcnt lgkmcnt(0)
	v_pk_add_f32 v[114:115], v[124:125], v[126:127]
	v_pk_add_f32 v[132:133], v[194:195], v[224:225]
	v_pk_add_f32 v[134:135], v[196:197], v[226:227]
	v_mov_b32_e32 v194, v228
	v_mov_b32_e32 v195, v232
	v_mov_b32_e32 v232, v229
	v_mov_b32_e32 v196, v230
	v_mov_b32_e32 v197, v234
	v_mov_b32_e32 v234, v231
	v_pk_fma_f32 v[114:115], v[114:115], s[24:25], v[130:131] op_sel_hi:[1,0,0]
	v_pk_add_f32 v[194:195], v[194:195], v[232:233]
	v_pk_add_f32 v[196:197], v[196:197], v[234:235]
	v_mul_f32_e32 v124, 0x4b800000, v115
	v_cmp_gt_f32_e64 s[8:9], s73, v115
	v_pk_add_f32 v[126:127], v[194:195], v[196:197]
	v_cmp_gt_f32_e64 s[10:11], s73, v114
	v_cndmask_b32_e64 v165, v115, v124, s[8:9]
	v_pk_add_f32 v[124:125], v[132:133], v[134:135]
	v_mov_b32_e32 v128, v126
	v_mov_b32_e32 v129, v124
	v_mov_b32_e32 v124, v127
	v_pk_add_f32 v[124:125], v[128:129], v[124:125]
	ds_bpermute_b32 v127, v157, v125
	ds_bpermute_b32 v126, v157, v124
	v_rsq_f32_e32 v128, v159
	v_mul_f32_e32 v115, 0x4b800000, v114
	v_cndmask_b32_e64 v129, v114, v115, s[10:11]
	v_pk_mul_f32 v[116:117], v[116:117], v[198:199] op_sel_hi:[1,0]
	s_waitcnt lgkmcnt(0)
	v_pk_add_f32 v[114:115], v[124:125], v[126:127]
	ds_bpermute_b32 v125, v155, v115
	ds_bpermute_b32 v124, v155, v114
	v_mul_f32_e32 v126, 0x45800000, v128
	v_rsq_f32_e32 v127, v161
	v_cndmask_b32_e32 v126, v128, v126, vcc
	v_rsq_f32_e32 v128, v163
	s_waitcnt lgkmcnt(0)
; DI unsigned pack2(float lo, float hi) { f32x2 v = {lo, hi}; bf16v2 r = __builtin_convertvector(v, bf16v2); return __builtin_bit_cast(unsigned, r); }
;   DI void operator()(const f32x4 (&acc)[2][2][4][2], const Unit& u, int wr, int wc, int fr, int fq) const {
;     ...
;     for (int ai = 0; ai < 2; ++ai)
; #pragma unroll
;       for (int m = 0; m < 4; ++m) {
;         const int row = row0 + ai * HALF + m * 16;
;         const float rs = rsv[ai][m];
;         bf16_t* rowp = O + (size_t)row * ldc + col0;
; #pragma unroll
;         for (int bj = 0; bj < 2; ++bj) {
;           const f32x4 v0 = acc[ai][bj][m][0] * rs, v1 = acc[ai][bj][m][1] * rs;
;           u32x4 w; w.x = pack2(v0[0], v0[1]); w.y = pack2(v0[2], v0[3]); w.z = pack2(v1[0], v1[1]); w.w = pack2(v1[2], v1[3]);
;           *(u32x4*)(rowp + bj * HALF) = w;
;         }
	v_pk_add_f32 v[114:115], v[114:115], v[124:125]
	v_mul_f32_e32 v124, 0x45800000, v127
	v_cndmask_b32_e64 v124, v127, v124, s[4:5]
	v_mul_f32_e32 v127, 0x45800000, v128
	v_pk_fma_f32 v[114:115], v[114:115], s[24:25], v[130:131] op_sel_hi:[1,0,0]
	v_rsq_f32_e32 v125, v165
	v_cndmask_b32_e64 v128, v128, v127, s[6:7]
	v_rsq_f32_e32 v127, v129
	v_mul_f32_e32 v129, 0x4b800000, v115
	v_cmp_gt_f32_e32 vcc, s73, v115
	v_cmp_gt_f32_e64 s[4:5], s73, v114
	v_pk_mul_f32 v[118:119], v[118:119], v[198:199] op_sel_hi:[1,0]
	v_cndmask_b32_e32 v129, v115, v129, vcc
	v_mul_f32_e32 v115, 0x4b800000, v114
	v_cndmask_b32_e64 v131, v114, v115, s[4:5]
	v_cvt_pk_bf16_f32 v114, v116, v117
	v_rsq_f32_e32 v117, v129
	v_cvt_pk_bf16_f32 v115, v118, v119
	v_rsq_f32_e32 v119, v131
	v_mul_f32_e32 v116, 0x45800000, v125
	v_pk_mul_f32 v[112:113], v[112:113], v[198:199] op_sel_hi:[1,0]
	v_cndmask_b32_e64 v118, v125, v116, s[8:9]
	v_mul_f32_e32 v116, 0x45800000, v127
	v_cndmask_b32_e64 v130, v127, v116, s[10:11]
	v_cvt_pk_bf16_f32 v116, v112, v113
	v_mul_f32_e32 v112, 0x45800000, v117
	v_cndmask_b32_e32 v132, v117, v112, vcc
	v_mul_f32_e32 v112, 0x45800000, v119
	v_cvt_pk_bf16_f32 v117, v178, v179
	v_cndmask_b32_e64 v112, v119, v112, s[4:5]
	global_store_dwordx4 v[168:169], v[114:117], off offset:256
	v_pk_mul_f32 v[110:111], v[110:111], v[126:127] op_sel_hi:[1,0]
	v_pk_mul_f32 v[108:109], v[108:109], v[126:127] op_sel_hi:[1,0]
	v_mad_i64_i32 v[114:115], s[4:5], v154, s76, v[120:121]
	v_pk_mul_f32 v[116:117], v[106:107], v[126:127] op_sel_hi:[1,0]
	v_pk_mul_f32 v[106:107], v[104:105], v[126:127] op_sel_hi:[1,0]
	v_lshl_add_u64 v[114:115], v[114:115], 0, v[122:123]
	v_cvt_pk_bf16_f32 v104, v108, v109
	v_cvt_pk_bf16_f32 v105, v110, v111
	v_cvt_pk_bf16_f32 v106, v106, v107
	v_cvt_pk_bf16_f32 v107, v116, v117
	global_store_dwordx4 v[114:115], v[104:107], off
	v_pk_mul_f32 v[98:99], v[98:99], v[126:127] op_sel_hi:[1,0]
	v_pk_mul_f32 v[96:97], v[96:97], v[126:127] op_sel_hi:[1,0]
	v_pk_mul_f32 v[104:105], v[90:91], v[126:127] op_sel_hi:[1,0]
	v_pk_mul_f32 v[90:91], v[88:89], v[126:127] op_sel_hi:[1,0]
	v_cvt_pk_bf16_f32 v88, v96, v97
	v_cvt_pk_bf16_f32 v89, v98, v99
	v_cvt_pk_bf16_f32 v90, v90, v91
	v_cvt_pk_bf16_f32 v91, v104, v105
	global_store_dwordx4 v[114:115], v[88:91], off offset:256
	v_pk_mul_f32 v[94:95], v[94:95], v[124:125] op_sel_hi:[1,0]
	v_pk_mul_f32 v[92:93], v[92:93], v[124:125] op_sel_hi:[1,0]
	v_mad_i64_i32 v[88:89], s[4:5], v160, s76, v[120:121]
	v_lshl_add_u64 v[96:97], v[88:89], 0, v[122:123]
	v_pk_mul_f32 v[90:91], v[102:103], v[124:125] op_sel_hi:[1,0]
	v_pk_mul_f32 v[88:89], v[100:101], v[124:125] op_sel_hi:[1,0]
	v_pk_mul_f32 v[82:83], v[82:83], v[124:125] op_sel_hi:[1,0]
	v_cvt_pk_bf16_f32 v88, v88, v89
	v_cvt_pk_bf16_f32 v89, v90, v91
	v_cvt_pk_bf16_f32 v90, v92, v93
	v_cvt_pk_bf16_f32 v91, v94, v95
	global_store_dwordx4 v[96:97], v[88:91], off
	v_pk_mul_f32 v[80:81], v[80:81], v[124:125] op_sel_hi:[1,0]
	v_pk_mul_f32 v[78:79], v[78:79], v[128:129] op_sel_hi:[1,0]
	v_pk_mul_f32 v[88:89], v[74:75], v[124:125] op_sel_hi:[1,0]
	v_pk_mul_f32 v[74:75], v[72:73], v[124:125] op_sel_hi:[1,0]
	v_cvt_pk_bf16_f32 v72, v80, v81
	v_cvt_pk_bf16_f32 v73, v82, v83
	v_cvt_pk_bf16_f32 v74, v74, v75
	v_cvt_pk_bf16_f32 v75, v88, v89
	global_store_dwordx4 v[96:97], v[72:75], off offset:256
	v_pk_mul_f32 v[76:77], v[76:77], v[128:129] op_sel_hi:[1,0]
	v_pk_mul_f32 v[70:71], v[70:71], v[128:129] op_sel_hi:[1,0]
	v_mad_i64_i32 v[72:73], s[4:5], v156, s76, v[120:121]
	v_lshl_add_u64 v[80:81], v[72:73], 0, v[122:123]
	v_pk_mul_f32 v[74:75], v[86:87], v[128:129] op_sel_hi:[1,0]
	v_pk_mul_f32 v[72:73], v[84:85], v[128:129] op_sel_hi:[1,0]
	v_pk_mul_f32 v[68:69], v[68:69], v[128:129] op_sel_hi:[1,0]
	v_cvt_pk_bf16_f32 v72, v72, v73
	v_cvt_pk_bf16_f32 v73, v74, v75
	v_cvt_pk_bf16_f32 v74, v76, v77
	v_cvt_pk_bf16_f32 v75, v78, v79
	global_store_dwordx4 v[80:81], v[72:75], off
	v_pk_mul_f32 v[62:63], v[62:63], v[118:119] op_sel_hi:[1,0]
	v_pk_mul_f32 v[60:61], v[60:61], v[118:119] op_sel_hi:[1,0]
	v_pk_mul_f32 v[72:73], v[66:67], v[128:129] op_sel_hi:[1,0]
	v_pk_mul_f32 v[66:67], v[64:65], v[128:129] op_sel_hi:[1,0]
; DI unsigned pack2(float lo, float hi) { f32x2 v = {lo, hi}; bf16v2 r = __builtin_convertvector(v, bf16v2); return __builtin_bit_cast(unsigned, r); }
; #define PG8_WAIT_V(n) asm volatile("s_waitcnt vmcnt(" #n ")" ::: "memory")
; #define PG8_BAR __builtin_amdgcn_s_barrier()
;   DI void operator()(const f32x4 (&acc)[2][2][4][2], const Unit& u, int wr, int wc, int fr, int fq) const {
;     ...
;     for (int ai = 0; ai < 2; ++ai)
; #pragma unroll
;       for (int m = 0; m < 4; ++m) {
;         const int row = row0 + ai * HALF + m * 16;
;         const float rs = rsv[ai][m];
;         bf16_t* rowp = O + (size_t)row * ldc + col0;
; #pragma unroll
;         for (int bj = 0; bj < 2; ++bj) {
;           const f32x4 v0 = acc[ai][bj][m][0] * rs, v1 = acc[ai][bj][m][1] * rs;
;           u32x4 w; w.x = pack2(v0[0], v0[1]); w.y = pack2(v0[2], v0[3]); w.z = pack2(v1[0], v1[1]); w.w = pack2(v1[2], v1[3]);
;           *(u32x4*)(rowp + bj * HALF) = w;
;         }
; template <class Epi, class Sched = StaticOrder>
; DI void gemm_phase(LAS unsigned char* lds, const Gemm g, const Sched& S, const Epi& E) {
;     ...
;   PG8_WAIT_V(0);
;   if (wr == 0) PG8_BAR;
;   PG8_BAR;
	v_cvt_pk_bf16_f32 v64, v68, v69
	v_cvt_pk_bf16_f32 v65, v70, v71
	v_cvt_pk_bf16_f32 v66, v66, v67
	v_cvt_pk_bf16_f32 v67, v72, v73
	global_store_dwordx4 v[80:81], v[64:67], off offset:256
	v_pk_mul_f32 v[50:51], v[50:51], v[118:119] op_sel_hi:[1,0]
	v_pk_mul_f32 v[48:49], v[48:49], v[118:119] op_sel_hi:[1,0]
	v_mad_i64_i32 v[64:65], s[4:5], v164, s76, v[120:121]
	v_pk_mul_f32 v[66:67], v[58:59], v[118:119] op_sel_hi:[1,0]
	v_pk_mul_f32 v[58:59], v[56:57], v[118:119] op_sel_hi:[1,0]
	v_lshl_add_u64 v[64:65], v[64:65], 0, v[122:123]
	v_cvt_pk_bf16_f32 v56, v60, v61
	v_cvt_pk_bf16_f32 v57, v62, v63
	v_cvt_pk_bf16_f32 v58, v58, v59
	v_cvt_pk_bf16_f32 v59, v66, v67
	global_store_dwordx4 v[64:65], v[56:59], off
	v_pk_mul_f32 v[46:47], v[46:47], v[130:131] op_sel_hi:[1,0]
	v_pk_mul_f32 v[44:45], v[44:45], v[130:131] op_sel_hi:[1,0]
	v_pk_mul_f32 v[56:57], v[42:43], v[118:119] op_sel_hi:[1,0]
	v_pk_mul_f32 v[42:43], v[40:41], v[118:119] op_sel_hi:[1,0]
	v_cvt_pk_bf16_f32 v40, v48, v49
	v_cvt_pk_bf16_f32 v41, v50, v51
	v_cvt_pk_bf16_f32 v42, v42, v43
	v_cvt_pk_bf16_f32 v43, v56, v57
	global_store_dwordx4 v[64:65], v[40:43], off offset:256
	v_pk_mul_f32 v[34:35], v[34:35], v[130:131] op_sel_hi:[1,0]
	v_pk_mul_f32 v[32:33], v[32:33], v[130:131] op_sel_hi:[1,0]
	v_mad_i64_i32 v[40:41], s[4:5], v158, s76, v[120:121]
	v_lshl_add_u64 v[48:49], v[40:41], 0, v[122:123]
	v_pk_mul_f32 v[42:43], v[54:55], v[130:131] op_sel_hi:[1,0]
	v_pk_mul_f32 v[40:41], v[52:53], v[130:131] op_sel_hi:[1,0]
	v_pk_mul_f32 v[30:31], v[30:31], v[132:133] op_sel_hi:[1,0]
	v_cvt_pk_bf16_f32 v40, v40, v41
	v_cvt_pk_bf16_f32 v41, v42, v43
	v_cvt_pk_bf16_f32 v42, v44, v45
	v_cvt_pk_bf16_f32 v43, v46, v47
	global_store_dwordx4 v[48:49], v[40:43], off
	v_pk_mul_f32 v[28:29], v[28:29], v[132:133] op_sel_hi:[1,0]
	v_pk_mul_f32 v[18:19], v[18:19], v[132:133] op_sel_hi:[1,0]
	v_pk_mul_f32 v[40:41], v[26:27], v[130:131] op_sel_hi:[1,0]
	v_pk_mul_f32 v[26:27], v[24:25], v[130:131] op_sel_hi:[1,0]
	v_cvt_pk_bf16_f32 v24, v32, v33
	v_cvt_pk_bf16_f32 v25, v34, v35
	v_cvt_pk_bf16_f32 v26, v26, v27
	v_cvt_pk_bf16_f32 v27, v40, v41
	global_store_dwordx4 v[48:49], v[24:27], off offset:256
	v_pk_mul_f32 v[16:17], v[16:17], v[132:133] op_sel_hi:[1,0]
	v_pk_mul_f32 v[14:15], v[14:15], v[112:113] op_sel_hi:[1,0]
	v_mad_i64_i32 v[24:25], s[4:5], v166, s76, v[120:121]
	v_lshl_add_u64 v[32:33], v[24:25], 0, v[122:123]
	v_pk_mul_f32 v[26:27], v[38:39], v[132:133] op_sel_hi:[1,0]
	v_pk_mul_f32 v[24:25], v[36:37], v[132:133] op_sel_hi:[1,0]
	v_pk_mul_f32 v[12:13], v[12:13], v[112:113] op_sel_hi:[1,0]
	v_cvt_pk_bf16_f32 v24, v24, v25
	v_cvt_pk_bf16_f32 v25, v26, v27
	v_cvt_pk_bf16_f32 v26, v28, v29
	v_cvt_pk_bf16_f32 v27, v30, v31
	global_store_dwordx4 v[32:33], v[24:27], off
	v_pk_mul_f32 v[6:7], v[6:7], v[112:113] op_sel_hi:[1,0]
	v_pk_mul_f32 v[4:5], v[4:5], v[112:113] op_sel_hi:[1,0]
	v_pk_mul_f32 v[24:25], v[10:11], v[132:133] op_sel_hi:[1,0]
	v_pk_mul_f32 v[10:11], v[8:9], v[132:133] op_sel_hi:[1,0]
	v_cvt_pk_bf16_f32 v8, v16, v17
	v_cvt_pk_bf16_f32 v9, v18, v19
	v_cvt_pk_bf16_f32 v10, v10, v11
	v_cvt_pk_bf16_f32 v11, v24, v25
	global_store_dwordx4 v[32:33], v[8:11], off offset:256
	s_and_b64 vcc, exec, s[0:1]
	s_mov_b64 s[8:9], s[36:37]
	v_mad_i64_i32 v[8:9], s[4:5], v162, s76, v[120:121]
	v_lshl_add_u64 v[16:17], v[8:9], 0, v[122:123]
	v_pk_mul_f32 v[10:11], v[22:23], v[112:113] op_sel_hi:[1,0]
	v_pk_mul_f32 v[8:9], v[20:21], v[112:113] op_sel_hi:[1,0]
	s_mov_b32 s5, s28
	v_cvt_pk_bf16_f32 v8, v8, v9
	v_cvt_pk_bf16_f32 v9, v10, v11
	v_cvt_pk_bf16_f32 v10, v12, v13
	v_cvt_pk_bf16_f32 v11, v14, v15
	global_store_dwordx4 v[16:17], v[8:11], off
	s_mov_b32 s4, s30
	s_mov_b64 s[6:7], s[34:35]
	v_pk_mul_f32 v[8:9], v[2:3], v[112:113] op_sel_hi:[1,0]
	v_pk_mul_f32 v[2:3], v[0:1], v[112:113] op_sel_hi:[1,0]
	v_cvt_pk_bf16_f32 v0, v4, v5
	v_cvt_pk_bf16_f32 v1, v6, v7
	v_cvt_pk_bf16_f32 v2, v2, v3
	v_cvt_pk_bf16_f32 v3, v8, v9
	global_store_dwordx4 v[16:17], v[0:3], off offset:256
	s_cbranch_vccz .LBB0_343
	s_waitcnt vmcnt(0)
	s_cmpk_gt_u32 s27, 0xff
	s_cbranch_scc1 .LBB0_350
	s_barrier

; #define PG8_STAGE(bufoff, gbase, voff) do { _Pragma("unroll") for (int _i = 0; _i < 2; ++_i) \
;     __builtin_amdgcn_global_load_lds((const unsigned*)((const char*)(gbase) + (voff)[_i]), (LAS unsigned*)(lds + (bufoff) + ldsw + _i * 8192), 16, 0, 0); } while (0)
; #define PG8_LDA(dst, b, h) do { _Pragma("unroll") for (int m = 0; m < 4; ++m) _Pragma("unroll") for (int k = 0; k < 2; ++k) dst[m][k] = *(const LAS bf16x8*)(lds + PG8_SA(b, h) + aoff + m * 2048 + k * 1024); } while (0)
; #define PG8_LDB(dst, b, h) do { _Pragma("unroll") for (int n = 0; n < 2; ++n) _Pragma("unroll") for (int k = 0; k < 2; ++k) dst[n][k] = *(const LAS bf16x8*)(lds + PG8_SB(b, h) + boff + n * 2048 + k * 1024); } while (0)
; #define PG8_MMA(ai, bj, At, Bt) do { __builtin_amdgcn_s_setprio(1); _Pragma("unroll") for (int m = 0; m < 4; ++m) _Pragma("unroll") for (int n = 0; n < 2; ++n) _Pragma("unroll") for (int k = 0; k < 2; ++k) \
;     acc[ai][bj][m][n] = __builtin_amdgcn_mfma_f32_16x16x32_bf16(Bt[n][k], At[m][k], acc[ai][bj][m][n], 0, 0, 0); __builtin_amdgcn_s_setprio(0); } while (0)
; #define PG8_WAIT_V(n) asm volatile("s_waitcnt vmcnt(" #n ")" ::: "memory")
; #define PG8_WAIT_L(n) asm volatile("s_waitcnt lgkmcnt(" #n ")" ::: "memory")
; #define PG8_BAR __builtin_amdgcn_s_barrier()
; #define PG8_SCHED __builtin_amdgcn_sched_barrier(0)
; template <class Epi, class Sched = StaticOrder>
; DI void gemm_phase(LAS unsigned char* lds, const Gemm g, const Sched& S, const Epi& E) {
;     ...
;     for (int t = 0; t < nt; t += 2) {
;       const bool last = (t == nt - 2);
;       const char* a1 = cA + (size_t)(t + 1) * kstep;
;       const char* a2 = last ? nA : cA + (size_t)(t + 2) * kstep; const char* b2 = last ? nB : cB + (size_t)(t + 2) * kstep;
;       const char* a3 = a2 + kstep; const char* b3 = b2 + kstep;
;       PG8_LDB(B0, 0, 0); PG8_SCHED; PG8_LDA(At, 0, 0); PG8_STAGE(PG8_SA(1, 1), a1 + hstep, voffA);
;       PG8_WAIT_L(8); PG8_BAR; PG8_WAIT_L(0); PG8_MMA(0, 0, At, B0); PG8_BAR; PG8_SCHED;
;       PG8_LDB(B1, 0, 1); PG8_STAGE(PG8_SB(0, 0), b2, voffB);
;       PG8_BAR; PG8_WAIT_L(0); PG8_MMA(0, 1, At, B1); PG8_BAR;
;       PG8_LDA(At, 0, 1); PG8_STAGE(PG8_SA(0, 0), a2, voffA);
;       PG8_BAR; PG8_WAIT_L(0); PG8_MMA(1, 0, At, B0); PG8_BAR; PG8_SCHED;
;       PG8_STAGE(PG8_SB(0, 1), b2 + hstep, voffB);
;       PG8_WAIT_V(6); PG8_BAR; PG8_MMA(1, 1, At, B1); PG8_BAR;
.LBB0_728:
	ds_read_b128 v[128:131], v207
	ds_read_b128 v[132:135], v207 offset:1024
	ds_read_b128 v[136:139], v207 offset:2048
	ds_read_b128 v[140:143], v207 offset:3072
	s_add_u32 s24, s22, 0xfff80080
	s_addc_u32 s25, s23, -1
	s_cmp_eq_u32 s53, 28
	s_cselect_b32 s27, s17, s25
	s_cselect_b32 s26, s43, s24
	s_cselect_b32 s25, s15, s52
	s_cselect_b32 s24, s44, s45
	s_add_i32 m0, s37, 0xc000
	ds_read_b128 v[144:147], v208
	ds_read_b128 v[148:151], v208 offset:1024
	ds_read_b128 v[152:155], v208 offset:2048
	ds_read_b128 v[156:159], v208 offset:3072
	ds_read_b128 v[160:163], v208 offset:4096
	ds_read_b128 v[164:167], v208 offset:5120
	ds_read_b128 v[168:171], v208 offset:6144
	ds_read_b128 v[172:175], v208 offset:7168
	global_load_lds_dwordx4 v184, s[22:23]
	s_add_i32 m0, s37, 0xe000
	s_nop 0
	global_load_lds_dwordx4 v186, s[22:23]
	s_waitcnt lgkmcnt(0)
	s_setprio 1
	s_barrier
	v_mfma_f32_16x16x32_bf16 v[124:127], v[128:131], v[144:147], v[124:127]
	v_mfma_f32_16x16x32_bf16 v[120:123], v[136:139], v[144:147], v[120:123]
	v_mfma_f32_16x16x32_bf16 v[108:111], v[128:131], v[152:155], v[108:111]
	v_mfma_f32_16x16x32_bf16 v[104:107], v[136:139], v[152:155], v[104:107]
	v_mfma_f32_16x16x32_bf16 v[92:95], v[128:131], v[160:163], v[92:95]
	v_mfma_f32_16x16x32_bf16 v[88:91], v[136:139], v[160:163], v[88:91]
	v_mfma_f32_16x16x32_bf16 v[76:79], v[128:131], v[168:171], v[76:79]
	v_mfma_f32_16x16x32_bf16 v[72:75], v[136:139], v[168:171], v[72:75]
	v_mfma_f32_16x16x32_bf16 v[124:127], v[132:135], v[148:151], v[124:127]
	v_mfma_f32_16x16x32_bf16 v[120:123], v[140:143], v[148:151], v[120:123]
	v_mfma_f32_16x16x32_bf16 v[108:111], v[132:135], v[156:159], v[108:111]
	v_mfma_f32_16x16x32_bf16 v[104:107], v[140:143], v[156:159], v[104:107]
	v_mfma_f32_16x16x32_bf16 v[92:95], v[132:135], v[164:167], v[92:95]
	v_mfma_f32_16x16x32_bf16 v[88:91], v[140:143], v[164:167], v[88:91]
	v_mfma_f32_16x16x32_bf16 v[76:79], v[132:135], v[172:175], v[76:79]
	v_mfma_f32_16x16x32_bf16 v[72:75], v[140:143], v[172:175], v[72:75]
	s_barrier
	s_setprio 0
	s_add_i32 s54, s50, s35
	s_add_u32 s98, s24, 0x80
	s_addc_u32 s99, s25, 0
	s_add_u32 s100, s26, 0x80
	s_addc_u32 s101, s27, 0
	s_mov_b32 m0, s54
	ds_read_b128 v[192:195], v209
	ds_read_b128 v[196:199], v209 offset:1024
	ds_read_b128 v[200:203], v209 offset:2048
	ds_read_b128 v[212:215], v209 offset:3072
	global_load_lds_dwordx4 v180, s[24:25]
	s_add_i32 m0, s54, 0x2000
	s_nop 0
	global_load_lds_dwordx4 v176, s[24:25]
	s_waitcnt lgkmcnt(0)
	s_setprio 1
	s_barrier
	v_mfma_f32_16x16x32_bf16 v[116:119], v[192:195], v[144:147], v[116:119]
	v_mfma_f32_16x16x32_bf16 v[112:115], v[200:203], v[144:147], v[112:115]
	v_mfma_f32_16x16x32_bf16 v[100:103], v[192:195], v[152:155], v[100:103]
	v_mfma_f32_16x16x32_bf16 v[96:99], v[200:203], v[152:155], v[96:99]
	v_mfma_f32_16x16x32_bf16 v[84:87], v[192:195], v[160:163], v[84:87]
	v_mfma_f32_16x16x32_bf16 v[80:83], v[200:203], v[160:163], v[80:83]
	v_mfma_f32_16x16x32_bf16 v[68:71], v[192:195], v[168:171], v[68:71]
	v_mfma_f32_16x16x32_bf16 v[64:67], v[200:203], v[168:171], v[64:67]
	v_mfma_f32_16x16x32_bf16 v[116:119], v[196:199], v[148:151], v[116:119]
	v_mfma_f32_16x16x32_bf16 v[112:115], v[212:215], v[148:151], v[112:115]
	v_mfma_f32_16x16x32_bf16 v[100:103], v[196:199], v[156:159], v[100:103]
	v_mfma_f32_16x16x32_bf16 v[96:99], v[212:215], v[156:159], v[96:99]
	v_mfma_f32_16x16x32_bf16 v[84:87], v[196:199], v[164:167], v[84:87]
	v_mfma_f32_16x16x32_bf16 v[80:83], v[212:215], v[164:167], v[80:83]
	v_mfma_f32_16x16x32_bf16 v[68:71], v[196:199], v[172:175], v[68:71]
	v_mfma_f32_16x16x32_bf16 v[64:67], v[212:215], v[172:175], v[64:67]
	s_barrier
	s_setprio 0
	s_mov_b32 m0, s37
	ds_read_b128 v[144:147], v208 offset:16384
	ds_read_b128 v[148:151], v208 offset:17408
	ds_read_b128 v[152:155], v208 offset:18432
	ds_read_b128 v[156:159], v208 offset:19456
	ds_read_b128 v[160:163], v208 offset:20480
	ds_read_b128 v[164:167], v208 offset:21504
	ds_read_b128 v[168:171], v208 offset:22528
	ds_read_b128 v[172:175], v208 offset:23552
	global_load_lds_dwordx4 v182, s[26:27]
	s_mov_b32 m0, s38
	s_nop 0
	global_load_lds_dwordx4 v178, s[26:27]
	s_waitcnt lgkmcnt(0)
	s_setprio 1
	s_barrier
	v_mfma_f32_16x16x32_bf16 v[60:63], v[128:131], v[144:147], v[60:63]
	v_mfma_f32_16x16x32_bf16 v[56:59], v[136:139], v[144:147], v[56:59]
	v_mfma_f32_16x16x32_bf16 v[44:47], v[128:131], v[152:155], v[44:47]
	v_mfma_f32_16x16x32_bf16 v[40:43], v[136:139], v[152:155], v[40:43]
	v_mfma_f32_16x16x32_bf16 v[28:31], v[128:131], v[160:163], v[28:31]
	v_mfma_f32_16x16x32_bf16 v[24:27], v[136:139], v[160:163], v[24:27]
	v_mfma_f32_16x16x32_bf16 v[12:15], v[128:131], v[168:171], v[12:15]
	v_mfma_f32_16x16x32_bf16 v[8:11], v[136:139], v[168:171], v[8:11]
	v_mfma_f32_16x16x32_bf16 v[60:63], v[132:135], v[148:151], v[60:63]
	v_mfma_f32_16x16x32_bf16 v[56:59], v[140:143], v[148:151], v[56:59]
	v_mfma_f32_16x16x32_bf16 v[44:47], v[132:135], v[156:159], v[44:47]
	v_mfma_f32_16x16x32_bf16 v[40:43], v[140:143], v[156:159], v[40:43]
	v_mfma_f32_16x16x32_bf16 v[28:31], v[132:135], v[164:167], v[28:31]
	v_mfma_f32_16x16x32_bf16 v[24:27], v[140:143], v[164:167], v[24:27]
	v_mfma_f32_16x16x32_bf16 v[12:15], v[132:135], v[172:175], v[12:15]
	v_mfma_f32_16x16x32_bf16 v[8:11], v[140:143], v[172:175], v[8:11]
	s_barrier
	s_setprio 0
	s_add_u32 s54, s24, 0x80000
	s_addc_u32 s55, s25, 0
	s_add_i32 s57, s51, s35
	s_mov_b32 m0, s57
	s_nop 0
	global_load_lds_dwordx4 v180, s[54:55]
	s_add_i32 m0, s57, 0x2000
	s_nop 0
	global_load_lds_dwordx4 v176, s[54:55]
	s_waitcnt vmcnt(6)
	s_setprio 1
	s_barrier
; #define PG8_STAGE(bufoff, gbase, voff) do { _Pragma("unroll") for (int _i = 0; _i < 2; ++_i) \
;     __builtin_amdgcn_global_load_lds((const unsigned*)((const char*)(gbase) + (voff)[_i]), (LAS unsigned*)(lds + (bufoff) + ldsw + _i * 8192), 16, 0, 0); } while (0)
; #define PG8_LDA(dst, b, h) do { _Pragma("unroll") for (int m = 0; m < 4; ++m) _Pragma("unroll") for (int k = 0; k < 2; ++k) dst[m][k] = *(const LAS bf16x8*)(lds + PG8_SA(b, h) + aoff + m * 2048 + k * 1024); } while (0)
; #define PG8_LDB(dst, b, h) do { _Pragma("unroll") for (int n = 0; n < 2; ++n) _Pragma("unroll") for (int k = 0; k < 2; ++k) dst[n][k] = *(const LAS bf16x8*)(lds + PG8_SB(b, h) + boff + n * 2048 + k * 1024); } while (0)
; #define PG8_MMA(ai, bj, At, Bt) do { __builtin_amdgcn_s_setprio(1); _Pragma("unroll") for (int m = 0; m < 4; ++m) _Pragma("unroll") for (int n = 0; n < 2; ++n) _Pragma("unroll") for (int k = 0; k < 2; ++k) \
;     acc[ai][bj][m][n] = __builtin_amdgcn_mfma_f32_16x16x32_bf16(Bt[n][k], At[m][k], acc[ai][bj][m][n], 0, 0, 0); __builtin_amdgcn_s_setprio(0); } while (0)
; #define PG8_WAIT_V(n) asm volatile("s_waitcnt vmcnt(" #n ")" ::: "memory")
; #define PG8_WAIT_L(n) asm volatile("s_waitcnt lgkmcnt(" #n ")" ::: "memory")
; #define PG8_BAR __builtin_amdgcn_s_barrier()
; #define PG8_SCHED __builtin_amdgcn_sched_barrier(0)
; template <class Epi, class Sched = StaticOrder>
; DI void gemm_phase(LAS unsigned char* lds, const Gemm g, const Sched& S, const Epi& E) {
;     ...
;       PG8_WAIT_V(6); PG8_BAR; PG8_MMA(1, 1, At, B1); PG8_BAR;
;       PG8_LDB(B0, 1, 0); PG8_SCHED; PG8_LDA(At, 1, 0); PG8_STAGE(PG8_SA(0, 1), a2 + hstep, voffA);
;       PG8_WAIT_L(8); PG8_BAR; PG8_WAIT_L(0); PG8_MMA(0, 0, At, B0); PG8_BAR; PG8_SCHED;
;       PG8_LDB(B1, 1, 1); PG8_STAGE(PG8_SB(1, 0), b3, voffB);
;       PG8_BAR; PG8_WAIT_L(0); PG8_MMA(0, 1, At, B1); PG8_BAR;
;       PG8_LDA(At, 1, 1); PG8_STAGE(PG8_SA(1, 0), a3, voffA);
;       PG8_BAR; PG8_WAIT_L(0); PG8_MMA(1, 0, At, B0); PG8_BAR; PG8_SCHED;
	v_mfma_f32_16x16x32_bf16 v[52:55], v[192:195], v[144:147], v[52:55]
	v_mfma_f32_16x16x32_bf16 v[48:51], v[200:203], v[144:147], v[48:51]
	v_mfma_f32_16x16x32_bf16 v[36:39], v[192:195], v[152:155], v[36:39]
	v_mfma_f32_16x16x32_bf16 v[32:35], v[200:203], v[152:155], v[32:35]
	v_mfma_f32_16x16x32_bf16 v[20:23], v[192:195], v[160:163], v[20:23]
	v_mfma_f32_16x16x32_bf16 v[16:19], v[200:203], v[160:163], v[16:19]
	v_mfma_f32_16x16x32_bf16 v[4:7], v[192:195], v[168:171], v[4:7]
	v_mfma_f32_16x16x32_bf16 v[0:3], v[200:203], v[168:171], v[0:3]
	v_mfma_f32_16x16x32_bf16 v[52:55], v[196:199], v[148:151], v[52:55]
	v_mfma_f32_16x16x32_bf16 v[48:51], v[212:215], v[148:151], v[48:51]
	v_mfma_f32_16x16x32_bf16 v[36:39], v[196:199], v[156:159], v[36:39]
	v_mfma_f32_16x16x32_bf16 v[32:35], v[212:215], v[156:159], v[32:35]
	v_mfma_f32_16x16x32_bf16 v[20:23], v[196:199], v[164:167], v[20:23]
	v_mfma_f32_16x16x32_bf16 v[16:19], v[212:215], v[164:167], v[16:19]
	v_mfma_f32_16x16x32_bf16 v[4:7], v[196:199], v[172:175], v[4:7]
	v_mfma_f32_16x16x32_bf16 v[0:3], v[212:215], v[172:175], v[0:3]
	s_barrier
	s_setprio 0
	s_add_i32 s54, 0, 0x18000
	v_add_u32_e32 v140, s54, v205
	ds_read_b128 v[128:131], v140
	ds_read_b128 v[132:135], v140 offset:1024
	ds_read_b128 v[136:139], v140 offset:2048
	ds_read_b128 v[140:143], v140 offset:3072
	s_add_u32 s26, s26, 0x80000
	s_addc_u32 s27, s27, 0
	s_mov_b32 m0, s39
	ds_read_b128 v[144:147], v208 offset:32768
	ds_read_b128 v[148:151], v208 offset:33792
	ds_read_b128 v[152:155], v208 offset:34816
	ds_read_b128 v[156:159], v208 offset:35840
	ds_read_b128 v[160:163], v208 offset:36864
	ds_read_b128 v[164:167], v208 offset:37888
	ds_read_b128 v[168:171], v208 offset:38912
	ds_read_b128 v[172:175], v208 offset:39936
	global_load_lds_dwordx4 v182, s[26:27]
	s_mov_b32 m0, s40
	s_nop 0
	global_load_lds_dwordx4 v178, s[26:27]
	s_waitcnt lgkmcnt(0)
	s_setprio 1
	s_barrier
	v_mfma_f32_16x16x32_bf16 v[124:127], v[128:131], v[144:147], v[124:127]
	v_mfma_f32_16x16x32_bf16 v[120:123], v[136:139], v[144:147], v[120:123]
	v_mfma_f32_16x16x32_bf16 v[108:111], v[128:131], v[152:155], v[108:111]
	v_mfma_f32_16x16x32_bf16 v[104:107], v[136:139], v[152:155], v[104:107]
	v_mfma_f32_16x16x32_bf16 v[92:95], v[128:131], v[160:163], v[92:95]
	v_mfma_f32_16x16x32_bf16 v[88:91], v[136:139], v[160:163], v[88:91]
	v_mfma_f32_16x16x32_bf16 v[76:79], v[128:131], v[168:171], v[76:79]
	v_mfma_f32_16x16x32_bf16 v[72:75], v[136:139], v[168:171], v[72:75]
	v_mfma_f32_16x16x32_bf16 v[124:127], v[132:135], v[148:151], v[124:127]
	v_mfma_f32_16x16x32_bf16 v[120:123], v[140:143], v[148:151], v[120:123]
	v_mfma_f32_16x16x32_bf16 v[108:111], v[132:135], v[156:159], v[108:111]
	v_mfma_f32_16x16x32_bf16 v[104:107], v[140:143], v[156:159], v[104:107]
	v_mfma_f32_16x16x32_bf16 v[92:95], v[132:135], v[164:167], v[92:95]
	v_mfma_f32_16x16x32_bf16 v[88:91], v[140:143], v[164:167], v[88:91]
	v_mfma_f32_16x16x32_bf16 v[76:79], v[132:135], v[172:175], v[76:79]
	v_mfma_f32_16x16x32_bf16 v[72:75], v[140:143], v[172:175], v[72:75]
	s_barrier
	s_setprio 0
	s_add_i32 s26, 0, 0x1c000
	s_add_i32 s27, s54, s35
	v_add_u32_e32 v212, s26, v205
	s_mov_b32 m0, s27
	ds_read_b128 v[192:195], v212
	ds_read_b128 v[196:199], v212 offset:1024
	ds_read_b128 v[200:203], v212 offset:2048
	ds_read_b128 v[212:215], v212 offset:3072
	global_load_lds_dwordx4 v180, s[98:99]
	s_add_i32 m0, s27, 0x2000
	s_nop 0
	global_load_lds_dwordx4 v176, s[98:99]
	s_waitcnt lgkmcnt(0)
	s_setprio 1
	s_barrier
	v_mfma_f32_16x16x32_bf16 v[116:119], v[192:195], v[144:147], v[116:119]
	v_mfma_f32_16x16x32_bf16 v[112:115], v[200:203], v[144:147], v[112:115]
	v_mfma_f32_16x16x32_bf16 v[100:103], v[192:195], v[152:155], v[100:103]
	v_mfma_f32_16x16x32_bf16 v[96:99], v[200:203], v[152:155], v[96:99]
	v_mfma_f32_16x16x32_bf16 v[84:87], v[192:195], v[160:163], v[84:87]
	v_mfma_f32_16x16x32_bf16 v[80:83], v[200:203], v[160:163], v[80:83]
	v_mfma_f32_16x16x32_bf16 v[68:71], v[192:195], v[168:171], v[68:71]
	v_mfma_f32_16x16x32_bf16 v[64:67], v[200:203], v[168:171], v[64:67]
	v_mfma_f32_16x16x32_bf16 v[116:119], v[196:199], v[148:151], v[116:119]
	v_mfma_f32_16x16x32_bf16 v[112:115], v[212:215], v[148:151], v[112:115]
	v_mfma_f32_16x16x32_bf16 v[100:103], v[196:199], v[156:159], v[100:103]
	v_mfma_f32_16x16x32_bf16 v[96:99], v[212:215], v[156:159], v[96:99]
	v_mfma_f32_16x16x32_bf16 v[84:87], v[196:199], v[164:167], v[84:87]
	v_mfma_f32_16x16x32_bf16 v[80:83], v[212:215], v[164:167], v[80:83]
	v_mfma_f32_16x16x32_bf16 v[68:71], v[196:199], v[172:175], v[68:71]
	v_mfma_f32_16x16x32_bf16 v[64:67], v[212:215], v[172:175], v[64:67]
	s_barrier
	s_setprio 0
	s_mov_b32 m0, s46
	ds_read_b128 v[144:147], v208 offset:49152
	ds_read_b128 v[148:151], v208 offset:50176
	ds_read_b128 v[152:155], v208 offset:51200
	ds_read_b128 v[156:159], v208 offset:52224
	ds_read_b128 v[160:163], v208 offset:53248
	ds_read_b128 v[164:167], v208 offset:54272
	ds_read_b128 v[168:171], v208 offset:55296
	ds_read_b128 v[172:175], v208 offset:56320
	global_load_lds_dwordx4 v182, s[100:101]
	s_mov_b32 m0, s47
	s_nop 0
	global_load_lds_dwordx4 v178, s[100:101]
	s_waitcnt lgkmcnt(0)
	s_setprio 1
	s_barrier
; #define PG8_STAGE(bufoff, gbase, voff) do { _Pragma("unroll") for (int _i = 0; _i < 2; ++_i) \
;     __builtin_amdgcn_global_load_lds((const unsigned*)((const char*)(gbase) + (voff)[_i]), (LAS unsigned*)(lds + (bufoff) + ldsw + _i * 8192), 16, 0, 0); } while (0)
; #define PG8_MMA(ai, bj, At, Bt) do { __builtin_amdgcn_s_setprio(1); _Pragma("unroll") for (int m = 0; m < 4; ++m) _Pragma("unroll") for (int n = 0; n < 2; ++n) _Pragma("unroll") for (int k = 0; k < 2; ++k) \
;     acc[ai][bj][m][n] = __builtin_amdgcn_mfma_f32_16x16x32_bf16(Bt[n][k], At[m][k], acc[ai][bj][m][n], 0, 0, 0); __builtin_amdgcn_s_setprio(0); } while (0)
; #define PG8_WAIT_V(n) asm volatile("s_waitcnt vmcnt(" #n ")" ::: "memory")
; #define PG8_WAIT_L(n) asm volatile("s_waitcnt lgkmcnt(" #n ")" ::: "memory")
; #define PG8_BAR __builtin_amdgcn_s_barrier()
; #define PG8_SCHED __builtin_amdgcn_sched_barrier(0)
; template <class Epi, class Sched = StaticOrder>
; DI void gemm_phase(LAS unsigned char* lds, const Gemm g, const Sched& S, const Epi& E) {
;     ...
;       PG8_BAR; PG8_WAIT_L(0); PG8_MMA(1, 0, At, B0); PG8_BAR; PG8_SCHED;
;       PG8_STAGE(PG8_SB(1, 1), b3 + hstep, voffB);
;       PG8_WAIT_V(6); PG8_BAR; PG8_MMA(1, 1, At, B1); PG8_BAR;
;     }
	v_mfma_f32_16x16x32_bf16 v[60:63], v[128:131], v[144:147], v[60:63]
	v_mfma_f32_16x16x32_bf16 v[56:59], v[136:139], v[144:147], v[56:59]
	v_mfma_f32_16x16x32_bf16 v[44:47], v[128:131], v[152:155], v[44:47]
	v_mfma_f32_16x16x32_bf16 v[40:43], v[136:139], v[152:155], v[40:43]
	v_mfma_f32_16x16x32_bf16 v[28:31], v[128:131], v[160:163], v[28:31]
	v_mfma_f32_16x16x32_bf16 v[24:27], v[136:139], v[160:163], v[24:27]
	v_mfma_f32_16x16x32_bf16 v[12:15], v[128:131], v[168:171], v[12:15]
	v_mfma_f32_16x16x32_bf16 v[8:11], v[136:139], v[168:171], v[8:11]
	v_mfma_f32_16x16x32_bf16 v[60:63], v[132:135], v[148:151], v[60:63]
	v_mfma_f32_16x16x32_bf16 v[56:59], v[140:143], v[148:151], v[56:59]
	v_mfma_f32_16x16x32_bf16 v[44:47], v[132:135], v[156:159], v[44:47]
	v_mfma_f32_16x16x32_bf16 v[40:43], v[140:143], v[156:159], v[40:43]
	v_mfma_f32_16x16x32_bf16 v[28:31], v[132:135], v[164:167], v[28:31]
	v_mfma_f32_16x16x32_bf16 v[24:27], v[140:143], v[164:167], v[24:27]
	v_mfma_f32_16x16x32_bf16 v[12:15], v[132:135], v[172:175], v[12:15]
	v_mfma_f32_16x16x32_bf16 v[8:11], v[140:143], v[172:175], v[8:11]
	s_barrier
	s_setprio 0
	s_add_u32 s24, s24, 0x80080
	s_addc_u32 s25, s25, 0
	s_add_i32 s26, s26, s35
	s_mov_b32 m0, s26
	s_nop 0
	global_load_lds_dwordx4 v180, s[24:25]
	s_add_i32 m0, s26, 0x2000
	s_nop 0
	global_load_lds_dwordx4 v176, s[24:25]
	s_waitcnt vmcnt(6)
	s_add_i32 s53, s53, 2
	s_add_u32 s22, s22, 0x100
	s_addc_u32 s23, s23, 0
	s_add_u32 s45, s45, 0x100
	s_addc_u32 s52, s52, 0
	s_cmp_gt_u32 s53, 29
	s_setprio 1
	s_barrier
	v_mfma_f32_16x16x32_bf16 v[52:55], v[192:195], v[144:147], v[52:55]
	v_mfma_f32_16x16x32_bf16 v[48:51], v[200:203], v[144:147], v[48:51]
	v_mfma_f32_16x16x32_bf16 v[36:39], v[192:195], v[152:155], v[36:39]
	v_mfma_f32_16x16x32_bf16 v[32:35], v[200:203], v[152:155], v[32:35]
	v_mfma_f32_16x16x32_bf16 v[20:23], v[192:195], v[160:163], v[20:23]
	v_mfma_f32_16x16x32_bf16 v[16:19], v[200:203], v[160:163], v[16:19]
	v_mfma_f32_16x16x32_bf16 v[4:7], v[192:195], v[168:171], v[4:7]
	v_mfma_f32_16x16x32_bf16 v[0:3], v[200:203], v[168:171], v[0:3]
	v_mfma_f32_16x16x32_bf16 v[52:55], v[196:199], v[148:151], v[52:55]
	v_mfma_f32_16x16x32_bf16 v[48:51], v[212:215], v[148:151], v[48:51]
	v_mfma_f32_16x16x32_bf16 v[36:39], v[196:199], v[156:159], v[36:39]
	v_mfma_f32_16x16x32_bf16 v[32:35], v[212:215], v[156:159], v[32:35]
	v_mfma_f32_16x16x32_bf16 v[20:23], v[196:199], v[164:167], v[20:23]
	v_mfma_f32_16x16x32_bf16 v[16:19], v[212:215], v[164:167], v[16:19]
	v_mfma_f32_16x16x32_bf16 v[4:7], v[196:199], v[172:175], v[4:7]
	v_mfma_f32_16x16x32_bf16 v[0:3], v[212:215], v[172:175], v[0:3]
	s_barrier
	s_setprio 0
	s_cbranch_scc0 .LBB0_728
; DI unsigned pack2(float lo, float hi) { f32x2 v = {lo, hi}; bf16v2 r = __builtin_convertvector(v, bf16v2); return __builtin_bit_cast(unsigned, r); }
;   DI void operator()(const f32x4 (&acc)[2][2][4][2], const Unit& u, int wr, int wc, int fr, int fq) const {
;     const int row0 = u.pm * BM + wr * 64 + fr, col0 = u.pn * BM + wc * 32 + 8 * fq;
; #pragma unroll
;     for (int ai = 0; ai < 2; ++ai) {
;       f32x4 bv[4][2][2];
; #pragma unroll
;       for (int m = 0; m < 4; ++m)
; #pragma unroll
;         for (int bj = 0; bj < 2; ++bj) {
;           const float* bp = base + (size_t)(row0 + ai * HALF + m * 16) * 2048 + col0 + bj * HALF;
;           bv[m][bj][0] = *(const f32x4*)bp; bv[m][bj][1] = *(const f32x4*)(bp + 4);
;         }
; #pragma unroll
;       for (int m = 0; m < 4; ++m) {
;         const int row = row0 + ai * HALF + m * 16;
;         const size_t off = (size_t)row * 2048 + col0;
;         float ss = 0.f;
; #pragma unroll
;         for (int bj = 0; bj < 2; ++bj) {
;           const f32x4 v0 = acc[ai][bj][m][0] + bv[m][bj][0], v1 = acc[ai][bj][m][1] + bv[m][bj][1];
;           *(f32x4*)(C + off + bj * HALF) = v0; *(f32x4*)(C + off + bj * HALF + 4) = v1;
;           if (xb) {
;             u32x4 w; w.x = pack2(v0[0], v0[1]); w.y = pack2(v0[2], v0[3]); w.z = pack2(v1[0], v1[1]); w.w = pack2(v1[2], v1[3]);
;             *(u32x4*)(xb + off + bj * HALF) = w;
;             ss += v0[0] * v0[0] + v0[1] * v0[1] + v0[2] * v0[2] + v0[3] * v0[3] + v1[0] * v1[0] + v1[1] * v1[1] + v1[2] * v1[2] + v1[3] * v1[3];
;           }
;         }
;         if (xb) {
;           ss += __shfl_xor(ss, 16); ss += __shfl_xor(ss, 32);
;           if (fq == 0) ssq[(size_t)row * 32 + u.pn * 4 + wc] = ss;
;         }
	v_lshl_add_u32 v196, s12, 8, v204
	v_lshl_or_b32 v192, s42, 8, v206
	v_ashrrev_i32_e32 v193, 31, v192
	v_ashrrev_i32_e32 v197, 31, v196
	v_lshl_add_u64 v[194:195], v[192:193], 2, s[60:61]
	v_lshlrev_b64 v[128:129], 13, v[196:197]
	v_lshl_add_u64 v[128:129], v[194:195], 0, v[128:129]
	global_load_dwordx4 v[214:217], v[128:129], off
	global_load_dwordx4 v[218:221], v[128:129], off offset:16
	global_load_dwordx4 v[222:225], v[128:129], off offset:512
	global_load_dwordx4 v[226:229], v[128:129], off offset:528
	v_or_b32_e32 v202, 16, v196
	v_or_b32_e32 v200, 32, v196
	v_or_b32_e32 v198, 48, v196
	v_ashrrev_i32_e32 v203, 31, v202
	v_ashrrev_i32_e32 v201, 31, v200
	v_ashrrev_i32_e32 v199, 31, v198
	v_lshlrev_b64 v[128:129], 13, v[202:203]
	v_lshlrev_b64 v[130:131], 13, v[200:201]
	v_lshlrev_b64 v[132:133], 13, v[198:199]
	v_lshl_add_u64 v[128:129], v[194:195], 0, v[128:129]
	v_lshl_add_u64 v[130:131], v[194:195], 0, v[130:131]
	v_lshl_add_u64 v[132:133], v[194:195], 0, v[132:133]
	global_load_dwordx4 v[168:171], v[128:129], off offset:16
	global_load_dwordx4 v[172:175], v[128:129], off
	global_load_dwordx4 v[160:163], v[128:129], off offset:528
	global_load_dwordx4 v[164:167], v[128:129], off offset:512
	global_load_dwordx4 v[152:155], v[130:131], off offset:16
	global_load_dwordx4 v[156:159], v[130:131], off
	global_load_dwordx4 v[144:147], v[130:131], off offset:528
	global_load_dwordx4 v[148:151], v[130:131], off offset:512
	global_load_dwordx4 v[136:139], v[132:133], off offset:16
	global_load_dwordx4 v[140:143], v[132:133], off
	s_nop 0
	global_load_dwordx4 v[128:131], v[132:133], off offset:528
	s_nop 0
	global_load_dwordx4 v[132:135], v[132:133], off offset:512
	v_and_b32_e32 v212, 64, v211
	v_xor_b32_e32 v230, 16, v211
	v_add_u32_e32 v232, 64, v212
	v_xor_b32_e32 v231, 32, v211
	v_cmp_lt_i32_e32 vcc, v230, v232
	v_lshlrev_b64 v[212:213], 11, v[196:197]
	v_readlane_b32 s64, v243, 3
	v_cndmask_b32_e32 v233, v211, v230, vcc
	v_cmp_lt_i32_e32 vcc, v231, v232
	v_readlane_b32 s78, v243, 17
	v_readlane_b32 s79, v243, 18
	v_cndmask_b32_e32 v234, v211, v231, vcc
	v_lshl_add_u64 v[230:231], v[212:213], 0, v[192:193]
	v_lshlrev_b32_e32 v212, 2, v233
	v_lshl_add_u64 v[232:233], v[230:231], 2, s[78:79]
	v_lshl_add_u64 v[230:231], v[230:231], 1, s[2:3]
	s_lshl_b32 s22, s42, 2
	s_ashr_i32 s23, s22, 31
	v_readlane_b32 s65, v243, 4
	v_readlane_b32 s66, v243, 5
	v_readlane_b32 s67, v243, 6
	v_readlane_b32 s68, v243, 7
	v_readlane_b32 s69, v243, 8
	v_readlane_b32 s70, v243, 9
	v_readlane_b32 s71, v243, 10
	v_readlane_b32 s72, v243, 11
	v_readlane_b32 s73, v243, 12
	v_readlane_b32 s74, v243, 13
	v_readlane_b32 s75, v243, 14
	v_readlane_b32 s76, v243, 15
	v_readlane_b32 s77, v243, 16
	s_waitcnt vmcnt(0)
	v_pk_add_f32 v[126:127], v[126:127], v[216:217]
	v_pk_add_f32 v[124:125], v[124:125], v[214:215]
	v_pk_add_f32 v[116:117], v[116:117], v[222:223]
	v_pk_add_f32 v[122:123], v[122:123], v[220:221]
	v_pk_add_f32 v[120:121], v[120:121], v[218:219]
	v_pk_add_f32 v[214:215], v[112:113], v[226:227]
	global_store_dwordx4 v[232:233], v[124:127], off
	global_store_dwordx4 v[232:233], v[120:123], off offset:16
	v_cvt_pk_bf16_f32 v112, v124, v125
	v_mul_f32_e32 v125, v125, v125
	v_mul_f32_e32 v213, v117, v117
	v_pk_add_f32 v[118:119], v[118:119], v[224:225]
	v_fmac_f32_e32 v125, v124, v124
	v_fmac_f32_e32 v213, v116, v116
	v_fmac_f32_e32 v125, v126, v126
	v_fmac_f32_e32 v213, v118, v118
	v_fmac_f32_e32 v125, v127, v127
	v_fmac_f32_e32 v213, v119, v119
	v_fmac_f32_e32 v125, v120, v120
	v_fmac_f32_e32 v213, v214, v214
	v_pk_add_f32 v[216:217], v[114:115], v[228:229]
	v_fmac_f32_e32 v125, v121, v121
	v_fmac_f32_e32 v213, v215, v215
	v_fmac_f32_e32 v125, v122, v122
	v_fmac_f32_e32 v213, v216, v216
	v_fmac_f32_e32 v125, v123, v123
	v_fmac_f32_e32 v213, v217, v217
	v_cvt_pk_bf16_f32 v114, v120, v121
	v_add_f32_e32 v120, v125, v213
	ds_bpermute_b32 v121, v212, v120
	v_cvt_pk_bf16_f32 v113, v126, v127
	v_cvt_pk_bf16_f32 v115, v122, v123
	global_store_dwordx4 v[230:231], v[112:115], off
	global_store_dwordx4 v[232:233], v[116:119], off offset:512
	global_store_dwordx4 v[232:233], v[214:217], off offset:528
	v_cvt_pk_bf16_f32 v122, v116, v117
	s_waitcnt lgkmcnt(0)
	v_add_f32_e32 v112, v120, v121
	v_lshlrev_b32_e32 v120, 2, v234
	ds_bpermute_b32 v113, v120, v112
	v_cvt_pk_bf16_f32 v123, v118, v119
	v_cvt_pk_bf16_f32 v124, v214, v215
	v_cvt_pk_bf16_f32 v125, v216, v217
	global_store_dwordx4 v[230:231], v[122:125], off offset:256
	s_and_saveexec_b64 s[24:25], s[0:1]
	s_cbranch_execz .LBB0_731
	s_waitcnt lgkmcnt(0)
	v_add_f32_e32 v114, v112, v113
	v_lshlrev_b64 v[112:113], 7, v[196:197]
	v_lshl_add_u64 v[112:113], s[8:9], 0, v[112:113]
	v_lshl_add_u64 v[112:113], s[22:23], 2, v[112:113]
	s_lshl_b32 s12, s41, 2
	v_lshl_add_u64 v[112:113], v[112:113], 0, s[12:13]
	global_store_dword v[112:113], v114, off

; #define PG8_STAGE(bufoff, gbase, voff) do { _Pragma("unroll") for (int _i = 0; _i < 2; ++_i) \
;     __builtin_amdgcn_global_load_lds((const unsigned*)((const char*)(gbase) + (voff)[_i]), (LAS unsigned*)(lds + (bufoff) + ldsw + _i * 8192), 16, 0, 0); } while (0)
; #define PG8_LDA(dst, b, h) do { _Pragma("unroll") for (int m = 0; m < 4; ++m) _Pragma("unroll") for (int k = 0; k < 2; ++k) dst[m][k] = *(const LAS bf16x8*)(lds + PG8_SA(b, h) + aoff + m * 2048 + k * 1024); } while (0)
; #define PG8_LDB(dst, b, h) do { _Pragma("unroll") for (int n = 0; n < 2; ++n) _Pragma("unroll") for (int k = 0; k < 2; ++k) dst[n][k] = *(const LAS bf16x8*)(lds + PG8_SB(b, h) + boff + n * 2048 + k * 1024); } while (0)
; #define PG8_MMA(ai, bj, At, Bt) do { __builtin_amdgcn_s_setprio(1); _Pragma("unroll") for (int m = 0; m < 4; ++m) _Pragma("unroll") for (int n = 0; n < 2; ++n) _Pragma("unroll") for (int k = 0; k < 2; ++k) \
;     acc[ai][bj][m][n] = __builtin_amdgcn_mfma_f32_16x16x32_bf16(Bt[n][k], At[m][k], acc[ai][bj][m][n], 0, 0, 0); __builtin_amdgcn_s_setprio(0); } while (0)
; #define PG8_WAIT_V(n) asm volatile("s_waitcnt vmcnt(" #n ")" ::: "memory")
; #define PG8_WAIT_L(n) asm volatile("s_waitcnt lgkmcnt(" #n ")" ::: "memory")
; #define PG8_BAR __builtin_amdgcn_s_barrier()
; #define PG8_SCHED __builtin_amdgcn_sched_barrier(0)
; template <class Epi, class Sched = StaticOrder>
; DI void gemm_phase(LAS unsigned char* lds, const Gemm g, const Sched& S, const Epi& E) {
;     ...
;     for (int t = 0; t < nt; t += 2) {
;       const bool last = (t == nt - 2);
;       const char* a1 = cA + (size_t)(t + 1) * kstep;
;       const char* a2 = last ? nA : cA + (size_t)(t + 2) * kstep; const char* b2 = last ? nB : cB + (size_t)(t + 2) * kstep;
;       const char* a3 = a2 + kstep; const char* b3 = b2 + kstep;
;       PG8_LDB(B0, 0, 0); PG8_SCHED; PG8_LDA(At, 0, 0); PG8_STAGE(PG8_SA(1, 1), a1 + hstep, voffA);
;       PG8_WAIT_L(8); PG8_BAR; PG8_WAIT_L(0); PG8_MMA(0, 0, At, B0); PG8_BAR; PG8_SCHED;
;       PG8_LDB(B1, 0, 1); PG8_STAGE(PG8_SB(0, 0), b2, voffB);
;       PG8_BAR; PG8_WAIT_L(0); PG8_MMA(0, 1, At, B1); PG8_BAR;
;       PG8_LDA(At, 0, 1); PG8_STAGE(PG8_SA(0, 0), a2, voffA);
;       PG8_BAR; PG8_WAIT_L(0); PG8_MMA(1, 0, At, B0); PG8_BAR; PG8_SCHED;
;       PG8_STAGE(PG8_SB(0, 1), b2 + hstep, voffB);
;       PG8_WAIT_V(6); PG8_BAR; PG8_MMA(1, 1, At, B1); PG8_BAR;
.LBB0_811:
	ds_read_b128 v[64:67], v201
	ds_read_b128 v[68:71], v201 offset:1024
	ds_read_b128 v[72:75], v201 offset:2048
	ds_read_b128 v[76:79], v201 offset:3072
	s_add_u32 s46, s14, 0xfff80080
	s_addc_u32 s47, s15, -1
	s_cmp_eq_u32 s52, 28
	s_cselect_b32 s49, s37, s47
	s_cselect_b32 s48, s42, s46
	s_cselect_b32 s47, s35, s45
	s_cselect_b32 s46, s43, s44
	s_add_i32 m0, s62, 0xc000
	ds_read_b128 v[80:83], v202
	ds_read_b128 v[84:87], v202 offset:1024
	ds_read_b128 v[92:95], v202 offset:2048
	ds_read_b128 v[96:99], v202 offset:3072
	ds_read_b128 v[180:183], v202 offset:4096
	ds_read_b128 v[184:187], v202 offset:5120
	ds_read_b128 v[188:191], v202 offset:6144
	ds_read_b128 v[192:195], v202 offset:7168
	global_load_lds_dwordx4 v170, s[14:15]
	s_add_i32 m0, s62, 0xe000
	s_nop 0
	global_load_lds_dwordx4 v172, s[14:15]
	s_waitcnt lgkmcnt(0)
	s_setprio 1
	s_barrier
	v_mfma_f32_16x16x32_bf16 v[156:159], v[64:67], v[80:83], v[156:159]
	v_mfma_f32_16x16x32_bf16 v[144:147], v[72:75], v[80:83], v[144:147]
	v_mfma_f32_16x16x32_bf16 v[140:143], v[64:67], v[92:95], v[140:143]
	v_mfma_f32_16x16x32_bf16 v[132:135], v[72:75], v[92:95], v[132:135]
	v_mfma_f32_16x16x32_bf16 v[124:127], v[64:67], v[180:183], v[124:127]
	v_mfma_f32_16x16x32_bf16 v[116:119], v[72:75], v[180:183], v[116:119]
	v_mfma_f32_16x16x32_bf16 v[112:115], v[64:67], v[188:191], v[112:115]
	v_mfma_f32_16x16x32_bf16 v[108:111], v[72:75], v[188:191], v[108:111]
	v_mfma_f32_16x16x32_bf16 v[156:159], v[68:71], v[84:87], v[156:159]
	v_mfma_f32_16x16x32_bf16 v[144:147], v[76:79], v[84:87], v[144:147]
	v_mfma_f32_16x16x32_bf16 v[140:143], v[68:71], v[96:99], v[140:143]
	v_mfma_f32_16x16x32_bf16 v[132:135], v[76:79], v[96:99], v[132:135]
	v_mfma_f32_16x16x32_bf16 v[124:127], v[68:71], v[184:187], v[124:127]
	v_mfma_f32_16x16x32_bf16 v[116:119], v[76:79], v[184:187], v[116:119]
	v_mfma_f32_16x16x32_bf16 v[112:115], v[68:71], v[192:195], v[112:115]
	v_mfma_f32_16x16x32_bf16 v[108:111], v[76:79], v[192:195], v[108:111]
	s_barrier
	s_setprio 0
	s_add_i32 s53, s72, s60
	s_add_u32 s98, s46, 0x80
	s_addc_u32 s99, s47, 0
	s_add_u32 s100, s48, 0x80
	s_addc_u32 s101, s49, 0
	s_mov_b32 m0, s53
	ds_read_b128 v[206:209], v203
	ds_read_b128 v[212:215], v203 offset:1024
	ds_read_b128 v[216:219], v203 offset:2048
	ds_read_b128 v[220:223], v203 offset:3072
	global_load_lds_dwordx4 v164, s[46:47]
	s_add_i32 m0, s53, 0x2000
	s_nop 0
	global_load_lds_dwordx4 v160, s[46:47]
	s_waitcnt lgkmcnt(0)
	s_setprio 1
	s_barrier
	v_mfma_f32_16x16x32_bf16 v[152:155], v[206:209], v[80:83], v[152:155]
	v_mfma_f32_16x16x32_bf16 v[80:83], v[216:219], v[80:83], v[148:151]
	v_mfma_f32_16x16x32_bf16 v[152:155], v[212:215], v[84:87], v[152:155]
	v_mfma_f32_16x16x32_bf16 v[80:83], v[220:223], v[84:87], v[80:83]
	v_mfma_f32_16x16x32_bf16 v[84:87], v[206:209], v[92:95], v[136:139]
	v_mfma_f32_16x16x32_bf16 v[92:95], v[216:219], v[92:95], v[128:131]
	v_mfma_f32_16x16x32_bf16 v[104:107], v[216:219], v[180:183], v[104:107]
	v_mfma_f32_16x16x32_bf16 v[100:103], v[206:209], v[188:191], v[100:103]
	v_mfma_f32_16x16x32_bf16 v[88:91], v[216:219], v[188:191], v[88:91]
	v_mfma_f32_16x16x32_bf16 v[84:87], v[212:215], v[96:99], v[84:87]
	v_mfma_f32_16x16x32_bf16 v[92:95], v[220:223], v[96:99], v[92:95]
	v_mfma_f32_16x16x32_bf16 v[96:99], v[206:209], v[180:183], v[120:123]
	v_mfma_f32_16x16x32_bf16 v[104:107], v[220:223], v[184:187], v[104:107]
	v_mfma_f32_16x16x32_bf16 v[100:103], v[212:215], v[192:195], v[100:103]
	v_mfma_f32_16x16x32_bf16 v[88:91], v[220:223], v[192:195], v[88:91]
	v_mfma_f32_16x16x32_bf16 v[96:99], v[212:215], v[184:187], v[96:99]
	s_barrier
	s_setprio 0
	s_mov_b32 m0, s62
	ds_read_b128 v[120:123], v202 offset:16384
	ds_read_b128 v[128:131], v202 offset:17408
	ds_read_b128 v[136:139], v202 offset:18432
	ds_read_b128 v[148:151], v202 offset:19456
	ds_read_b128 v[180:183], v202 offset:20480
	ds_read_b128 v[184:187], v202 offset:21504
	ds_read_b128 v[188:191], v202 offset:22528
	ds_read_b128 v[192:195], v202 offset:23552
	global_load_lds_dwordx4 v166, s[48:49]
	s_mov_b32 m0, s63
	s_nop 0
	global_load_lds_dwordx4 v162, s[48:49]
	s_waitcnt lgkmcnt(0)
	s_setprio 1
	s_barrier
	v_mfma_f32_16x16x32_bf16 v[60:63], v[64:67], v[120:123], v[60:63]
	v_mfma_f32_16x16x32_bf16 v[48:51], v[72:75], v[120:123], v[48:51]
	v_mfma_f32_16x16x32_bf16 v[44:47], v[64:67], v[136:139], v[44:47]
	v_mfma_f32_16x16x32_bf16 v[36:39], v[72:75], v[136:139], v[36:39]
	v_mfma_f32_16x16x32_bf16 v[28:31], v[64:67], v[180:183], v[28:31]
	v_mfma_f32_16x16x32_bf16 v[20:23], v[72:75], v[180:183], v[20:23]
	v_mfma_f32_16x16x32_bf16 v[16:19], v[64:67], v[188:191], v[16:19]
	v_mfma_f32_16x16x32_bf16 v[12:15], v[72:75], v[188:191], v[12:15]
	v_mfma_f32_16x16x32_bf16 v[60:63], v[68:71], v[128:131], v[60:63]
	v_mfma_f32_16x16x32_bf16 v[48:51], v[76:79], v[128:131], v[48:51]
	v_mfma_f32_16x16x32_bf16 v[44:47], v[68:71], v[148:151], v[44:47]
	v_mfma_f32_16x16x32_bf16 v[36:39], v[76:79], v[148:151], v[36:39]
	v_mfma_f32_16x16x32_bf16 v[28:31], v[68:71], v[184:187], v[28:31]
	v_mfma_f32_16x16x32_bf16 v[20:23], v[76:79], v[184:187], v[20:23]
	v_mfma_f32_16x16x32_bf16 v[16:19], v[68:71], v[192:195], v[16:19]
	v_mfma_f32_16x16x32_bf16 v[12:15], v[76:79], v[192:195], v[12:15]
	s_barrier
	s_setprio 0
	s_add_u32 s54, s46, 0x80000
	s_addc_u32 s55, s47, 0
	s_add_i32 s53, s73, s60
	s_mov_b32 m0, s53
	s_nop 0
	global_load_lds_dwordx4 v164, s[54:55]
	s_add_i32 m0, s53, 0x2000
	s_nop 0
	global_load_lds_dwordx4 v160, s[54:55]
	s_waitcnt vmcnt(6)
	s_setprio 1
	s_barrier
; #define PG8_STAGE(bufoff, gbase, voff) do { _Pragma("unroll") for (int _i = 0; _i < 2; ++_i) \
;     __builtin_amdgcn_global_load_lds((const unsigned*)((const char*)(gbase) + (voff)[_i]), (LAS unsigned*)(lds + (bufoff) + ldsw + _i * 8192), 16, 0, 0); } while (0)
; #define PG8_LDA(dst, b, h) do { _Pragma("unroll") for (int m = 0; m < 4; ++m) _Pragma("unroll") for (int k = 0; k < 2; ++k) dst[m][k] = *(const LAS bf16x8*)(lds + PG8_SA(b, h) + aoff + m * 2048 + k * 1024); } while (0)
; #define PG8_LDB(dst, b, h) do { _Pragma("unroll") for (int n = 0; n < 2; ++n) _Pragma("unroll") for (int k = 0; k < 2; ++k) dst[n][k] = *(const LAS bf16x8*)(lds + PG8_SB(b, h) + boff + n * 2048 + k * 1024); } while (0)
; #define PG8_MMA(ai, bj, At, Bt) do { __builtin_amdgcn_s_setprio(1); _Pragma("unroll") for (int m = 0; m < 4; ++m) _Pragma("unroll") for (int n = 0; n < 2; ++n) _Pragma("unroll") for (int k = 0; k < 2; ++k) \
;     acc[ai][bj][m][n] = __builtin_amdgcn_mfma_f32_16x16x32_bf16(Bt[n][k], At[m][k], acc[ai][bj][m][n], 0, 0, 0); __builtin_amdgcn_s_setprio(0); } while (0)
; #define PG8_WAIT_V(n) asm volatile("s_waitcnt vmcnt(" #n ")" ::: "memory")
; #define PG8_WAIT_L(n) asm volatile("s_waitcnt lgkmcnt(" #n ")" ::: "memory")
; #define PG8_BAR __builtin_amdgcn_s_barrier()
; #define PG8_SCHED __builtin_amdgcn_sched_barrier(0)
; template <class Epi, class Sched = StaticOrder>
; DI void gemm_phase(LAS unsigned char* lds, const Gemm g, const Sched& S, const Epi& E) {
;     ...
;       PG8_WAIT_V(6); PG8_BAR; PG8_MMA(1, 1, At, B1); PG8_BAR;
;       PG8_LDB(B0, 1, 0); PG8_SCHED; PG8_LDA(At, 1, 0); PG8_STAGE(PG8_SA(0, 1), a2 + hstep, voffA);
;       PG8_WAIT_L(8); PG8_BAR; PG8_WAIT_L(0); PG8_MMA(0, 0, At, B0); PG8_BAR; PG8_SCHED;
;       PG8_LDB(B1, 1, 1); PG8_STAGE(PG8_SB(1, 0), b3, voffB);
;       PG8_BAR; PG8_WAIT_L(0); PG8_MMA(0, 1, At, B1); PG8_BAR;
;       PG8_LDA(At, 1, 1); PG8_STAGE(PG8_SA(1, 0), a3, voffA);
;       PG8_BAR; PG8_WAIT_L(0); PG8_MMA(1, 0, At, B0); PG8_BAR; PG8_SCHED;
	v_mfma_f32_16x16x32_bf16 v[56:59], v[206:209], v[120:123], v[56:59]
	v_mfma_f32_16x16x32_bf16 v[52:55], v[216:219], v[120:123], v[52:55]
	v_mfma_f32_16x16x32_bf16 v[40:43], v[206:209], v[136:139], v[40:43]
	v_mfma_f32_16x16x32_bf16 v[32:35], v[216:219], v[136:139], v[32:35]
	v_mfma_f32_16x16x32_bf16 v[24:27], v[206:209], v[180:183], v[24:27]
	v_mfma_f32_16x16x32_bf16 v[8:11], v[216:219], v[180:183], v[8:11]
	v_mfma_f32_16x16x32_bf16 v[4:7], v[206:209], v[188:191], v[4:7]
	v_mfma_f32_16x16x32_bf16 v[0:3], v[216:219], v[188:191], v[0:3]
	v_mfma_f32_16x16x32_bf16 v[56:59], v[212:215], v[128:131], v[56:59]
	v_mfma_f32_16x16x32_bf16 v[52:55], v[220:223], v[128:131], v[52:55]
	v_mfma_f32_16x16x32_bf16 v[40:43], v[212:215], v[148:151], v[40:43]
	v_mfma_f32_16x16x32_bf16 v[32:35], v[220:223], v[148:151], v[32:35]
	v_mfma_f32_16x16x32_bf16 v[24:27], v[212:215], v[184:187], v[24:27]
	v_mfma_f32_16x16x32_bf16 v[8:11], v[220:223], v[184:187], v[8:11]
	v_mfma_f32_16x16x32_bf16 v[4:7], v[212:215], v[192:195], v[4:7]
	v_mfma_f32_16x16x32_bf16 v[0:3], v[220:223], v[192:195], v[0:3]
	s_barrier
	s_setprio 0
	s_add_i32 s53, 0, 0x18000
	v_add_u32_e32 v76, s53, v198
	ds_read_b128 v[64:67], v76
	ds_read_b128 v[68:71], v76 offset:1024
	ds_read_b128 v[72:75], v76 offset:2048
	ds_read_b128 v[76:79], v76 offset:3072
	s_add_u32 s48, s48, 0x80000
	s_addc_u32 s49, s49, 0
	s_mov_b32 m0, s64
	ds_read_b128 v[120:123], v202 offset:32768
	ds_read_b128 v[128:131], v202 offset:33792
	ds_read_b128 v[180:183], v202 offset:34816
	ds_read_b128 v[184:187], v202 offset:35840
	ds_read_b128 v[188:191], v202 offset:36864
	ds_read_b128 v[192:195], v202 offset:37888
	ds_read_b128 v[206:209], v202 offset:38912
	ds_read_b128 v[212:215], v202 offset:39936
	global_load_lds_dwordx4 v166, s[48:49]
	s_mov_b32 m0, s65
	s_nop 0
	global_load_lds_dwordx4 v162, s[48:49]
	s_waitcnt lgkmcnt(0)
	s_setprio 1
	s_barrier
	v_mfma_f32_16x16x32_bf16 v[136:139], v[64:67], v[120:123], v[156:159]
	v_mfma_f32_16x16x32_bf16 v[156:159], v[68:71], v[128:131], v[136:139]
	v_mfma_f32_16x16x32_bf16 v[136:139], v[72:75], v[120:123], v[144:147]
	v_mfma_f32_16x16x32_bf16 v[144:147], v[76:79], v[128:131], v[136:139]
	v_mfma_f32_16x16x32_bf16 v[136:139], v[64:67], v[180:183], v[140:143]
	v_mfma_f32_16x16x32_bf16 v[132:135], v[72:75], v[180:183], v[132:135]
	v_mfma_f32_16x16x32_bf16 v[124:127], v[64:67], v[188:191], v[124:127]
	v_mfma_f32_16x16x32_bf16 v[116:119], v[72:75], v[188:191], v[116:119]
	v_mfma_f32_16x16x32_bf16 v[112:115], v[64:67], v[206:209], v[112:115]
	v_mfma_f32_16x16x32_bf16 v[108:111], v[72:75], v[206:209], v[108:111]
	v_mfma_f32_16x16x32_bf16 v[140:143], v[68:71], v[184:187], v[136:139]
	v_mfma_f32_16x16x32_bf16 v[132:135], v[76:79], v[184:187], v[132:135]
	v_mfma_f32_16x16x32_bf16 v[124:127], v[68:71], v[192:195], v[124:127]
	v_mfma_f32_16x16x32_bf16 v[116:119], v[76:79], v[192:195], v[116:119]
	v_mfma_f32_16x16x32_bf16 v[112:115], v[68:71], v[212:215], v[112:115]
	v_mfma_f32_16x16x32_bf16 v[108:111], v[76:79], v[212:215], v[108:111]
	s_barrier
	s_setprio 0
	s_add_i32 s48, 0, 0x1c000
	v_add_u32_e32 v136, s48, v198
	s_add_i32 s49, s53, s60
	ds_read_b128 v[216:219], v136
	ds_read_b128 v[220:223], v136 offset:1024
	ds_read_b128 v[224:227], v136 offset:2048
	ds_read_b128 v[228:231], v136 offset:3072
	s_mov_b32 m0, s49
	s_nop 0
	global_load_lds_dwordx4 v164, s[98:99]
	s_add_i32 m0, s49, 0x2000
	s_nop 0
	global_load_lds_dwordx4 v160, s[98:99]
	s_waitcnt lgkmcnt(0)
	s_setprio 1
	s_barrier
	v_mfma_f32_16x16x32_bf16 v[80:83], v[224:227], v[120:123], v[80:83]
	v_mfma_f32_16x16x32_bf16 v[136:139], v[216:219], v[120:123], v[152:155]
	v_mfma_f32_16x16x32_bf16 v[148:151], v[228:231], v[128:131], v[80:83]
	v_mfma_f32_16x16x32_bf16 v[80:83], v[216:219], v[180:183], v[84:87]
	v_mfma_f32_16x16x32_bf16 v[152:155], v[220:223], v[128:131], v[136:139]
	v_mfma_f32_16x16x32_bf16 v[136:139], v[220:223], v[184:187], v[80:83]
	v_mfma_f32_16x16x32_bf16 v[80:83], v[224:227], v[180:183], v[92:95]
	v_mfma_f32_16x16x32_bf16 v[128:131], v[228:231], v[184:187], v[80:83]
	v_mfma_f32_16x16x32_bf16 v[80:83], v[216:219], v[188:191], v[96:99]
	v_mfma_f32_16x16x32_bf16 v[120:123], v[220:223], v[192:195], v[80:83]
	v_mfma_f32_16x16x32_bf16 v[80:83], v[224:227], v[188:191], v[104:107]
	v_mfma_f32_16x16x32_bf16 v[104:107], v[228:231], v[192:195], v[80:83]
	v_mfma_f32_16x16x32_bf16 v[80:83], v[216:219], v[206:209], v[100:103]
	v_mfma_f32_16x16x32_bf16 v[100:103], v[220:223], v[212:215], v[80:83]
	v_mfma_f32_16x16x32_bf16 v[80:83], v[224:227], v[206:209], v[88:91]
	v_mfma_f32_16x16x32_bf16 v[88:91], v[228:231], v[212:215], v[80:83]
	s_barrier
	s_setprio 0
	s_mov_b32 m0, s67
	s_nop 2
	ds_read_b128 v[80:83], v202 offset:49152
	ds_read_b128 v[84:87], v202 offset:50176
	ds_read_b128 v[92:95], v202 offset:51200
	ds_read_b128 v[96:99], v202 offset:52224
	ds_read_b128 v[180:183], v202 offset:53248
	ds_read_b128 v[184:187], v202 offset:54272
	ds_read_b128 v[188:191], v202 offset:55296
	ds_read_b128 v[192:195], v202 offset:56320
	global_load_lds_dwordx4 v166, s[100:101]
	s_mov_b32 m0, s68
	s_nop 0
	global_load_lds_dwordx4 v162, s[100:101]
	s_waitcnt lgkmcnt(0)
	s_setprio 1
	s_barrier
; #define PG8_STAGE(bufoff, gbase, voff) do { _Pragma("unroll") for (int _i = 0; _i < 2; ++_i) \
;     __builtin_amdgcn_global_load_lds((const unsigned*)((const char*)(gbase) + (voff)[_i]), (LAS unsigned*)(lds + (bufoff) + ldsw + _i * 8192), 16, 0, 0); } while (0)
; #define PG8_MMA(ai, bj, At, Bt) do { __builtin_amdgcn_s_setprio(1); _Pragma("unroll") for (int m = 0; m < 4; ++m) _Pragma("unroll") for (int n = 0; n < 2; ++n) _Pragma("unroll") for (int k = 0; k < 2; ++k) \
;     acc[ai][bj][m][n] = __builtin_amdgcn_mfma_f32_16x16x32_bf16(Bt[n][k], At[m][k], acc[ai][bj][m][n], 0, 0, 0); __builtin_amdgcn_s_setprio(0); } while (0)
; #define PG8_WAIT_V(n) asm volatile("s_waitcnt vmcnt(" #n ")" ::: "memory")
; #define PG8_WAIT_L(n) asm volatile("s_waitcnt lgkmcnt(" #n ")" ::: "memory")
; #define PG8_BAR __builtin_amdgcn_s_barrier()
; #define PG8_SCHED __builtin_amdgcn_sched_barrier(0)
;   DI void operator()(const f32x4 (&acc)[2][2][4][2], const Unit& u, int wr, int wc, int fr, int fq) const {
;     const int col = u.pn * 128 + wc * 32 + 8 * fq;
;     float w0[8], w1[8], w2[8], bb[8];
; #pragma unroll
;     for (int e = 0; e < 8; ++e) { w0[e] = cw[col + e]; w1[e] = cw[5632 + col + e]; w2[e] = cw[2 * 5632 + col + e]; bb[e] = cb[col + e]; }
; #pragma unroll
;     for (int ai = 0; ai < 2; ++ai) {
;       const int row0 = u.pm * BM + ai * HALF + wr * 64, span = row0 >> 6;
;       float rsv[4];
; #pragma unroll
;       for (int m = 0; m < 4; ++m) rsv[m] = row_rstd(ssq, row0 + 16 * m + fr, fq);
; template <class Epi, class Sched = StaticOrder>
; DI void gemm_phase(LAS unsigned char* lds, const Gemm g, const Sched& S, const Epi& E) {
;     ...
;       PG8_BAR; PG8_WAIT_L(0); PG8_MMA(1, 0, At, B0); PG8_BAR; PG8_SCHED;
;       PG8_STAGE(PG8_SB(1, 1), b3 + hstep, voffB);
;       PG8_WAIT_V(6); PG8_BAR; PG8_MMA(1, 1, At, B1); PG8_BAR;
	v_mfma_f32_16x16x32_bf16 v[60:63], v[64:67], v[80:83], v[60:63]
	v_mfma_f32_16x16x32_bf16 v[48:51], v[72:75], v[80:83], v[48:51]
	v_mfma_f32_16x16x32_bf16 v[44:47], v[64:67], v[92:95], v[44:47]
	v_mfma_f32_16x16x32_bf16 v[36:39], v[72:75], v[92:95], v[36:39]
	v_mfma_f32_16x16x32_bf16 v[28:31], v[64:67], v[180:183], v[28:31]
	v_mfma_f32_16x16x32_bf16 v[20:23], v[72:75], v[180:183], v[20:23]
	v_mfma_f32_16x16x32_bf16 v[16:19], v[64:67], v[188:191], v[16:19]
	v_mfma_f32_16x16x32_bf16 v[12:15], v[72:75], v[188:191], v[12:15]
	v_mfma_f32_16x16x32_bf16 v[60:63], v[68:71], v[84:87], v[60:63]
	v_mfma_f32_16x16x32_bf16 v[48:51], v[76:79], v[84:87], v[48:51]
	v_mfma_f32_16x16x32_bf16 v[44:47], v[68:71], v[96:99], v[44:47]
	v_mfma_f32_16x16x32_bf16 v[36:39], v[76:79], v[96:99], v[36:39]
	v_mfma_f32_16x16x32_bf16 v[28:31], v[68:71], v[184:187], v[28:31]
	v_mfma_f32_16x16x32_bf16 v[20:23], v[76:79], v[184:187], v[20:23]
	v_mfma_f32_16x16x32_bf16 v[16:19], v[68:71], v[192:195], v[16:19]
	v_mfma_f32_16x16x32_bf16 v[12:15], v[76:79], v[192:195], v[12:15]
	s_barrier
	s_setprio 0
	s_add_u32 s46, s46, 0x80080
	s_addc_u32 s47, s47, 0
	s_add_i32 s48, s48, s60
	s_mov_b32 m0, s48
	s_nop 0
	global_load_lds_dwordx4 v164, s[46:47]
	s_add_i32 m0, s48, 0x2000
	s_nop 0
	global_load_lds_dwordx4 v160, s[46:47]
	s_waitcnt vmcnt(6)
	s_add_i32 s52, s52, 2
	s_add_u32 s14, s14, 0x100
	s_addc_u32 s15, s15, 0
	s_add_u32 s44, s44, 0x100
	s_addc_u32 s45, s45, 0
	s_cmp_gt_u32 s52, 29
	s_setprio 1
	s_barrier
	v_mfma_f32_16x16x32_bf16 v[56:59], v[216:219], v[80:83], v[56:59]
	v_mfma_f32_16x16x32_bf16 v[52:55], v[224:227], v[80:83], v[52:55]
	v_mfma_f32_16x16x32_bf16 v[40:43], v[216:219], v[92:95], v[40:43]
	v_mfma_f32_16x16x32_bf16 v[32:35], v[224:227], v[92:95], v[32:35]
	v_mfma_f32_16x16x32_bf16 v[24:27], v[216:219], v[180:183], v[24:27]
	v_mfma_f32_16x16x32_bf16 v[8:11], v[224:227], v[180:183], v[8:11]
	v_mfma_f32_16x16x32_bf16 v[4:7], v[216:219], v[188:191], v[4:7]
	v_mfma_f32_16x16x32_bf16 v[0:3], v[224:227], v[188:191], v[0:3]
	v_mfma_f32_16x16x32_bf16 v[56:59], v[220:223], v[84:87], v[56:59]
	v_mfma_f32_16x16x32_bf16 v[52:55], v[228:231], v[84:87], v[52:55]
	v_mfma_f32_16x16x32_bf16 v[40:43], v[220:223], v[96:99], v[40:43]
	v_mfma_f32_16x16x32_bf16 v[32:35], v[228:231], v[96:99], v[32:35]
	v_mfma_f32_16x16x32_bf16 v[24:27], v[220:223], v[184:187], v[24:27]
	v_mfma_f32_16x16x32_bf16 v[8:11], v[228:231], v[184:187], v[8:11]
	v_mfma_f32_16x16x32_bf16 v[4:7], v[220:223], v[192:195], v[4:7]
	v_mfma_f32_16x16x32_bf16 v[0:3], v[228:231], v[192:195], v[0:3]
	s_barrier
	s_setprio 0
	s_cbranch_scc0 .LBB0_811
	s_lshl_b32 s35, s12, 8
	s_add_i32 s35, s35, s66
	v_or_b32_e32 v190, s35, v179
	v_ashrrev_i32_e32 v191, 31, v190
	v_lshlrev_b64 v[64:65], 7, v[190:191]
	v_or_b32_e32 v188, 16, v190
	v_lshl_add_u64 v[64:65], v[168:169], 0, v[64:65]
	v_ashrrev_i32_e32 v189, 31, v188
	global_load_dwordx4 v[192:195], v[64:65], off
	global_load_dwordx4 v[206:209], v[64:65], off offset:16
	v_lshlrev_b64 v[64:65], 7, v[188:189]
	v_lshl_add_u64 v[64:65], v[168:169], 0, v[64:65]
	global_load_dwordx4 v[212:215], v[64:65], off
	global_load_dwordx4 v[216:219], v[64:65], off offset:16
	v_or_b32_e32 v186, 32, v190
	v_ashrrev_i32_e32 v187, 31, v186
	v_lshlrev_b64 v[64:65], 7, v[186:187]
	v_or_b32_e32 v184, 48, v190
	v_lshl_add_u64 v[64:65], v[168:169], 0, v[64:65]
	v_ashrrev_i32_e32 v185, 31, v184
	global_load_dwordx4 v[220:223], v[64:65], off
	global_load_dwordx4 v[224:227], v[64:65], off offset:16
	v_lshlrev_b64 v[64:65], 7, v[184:185]
	v_lshl_add_u64 v[64:65], v[168:169], 0, v[64:65]
	global_load_dwordx4 v[228:231], v[64:65], off
	global_load_dwordx4 v[232:235], v[64:65], off offset:16
	v_lshl_or_b32 v180, s13, 7, v200
	v_and_b32_e32 v65, 64, v204
	v_xor_b32_e32 v64, 16, v204
	v_ashrrev_i32_e32 v181, 31, v180
	v_add_u32_e32 v65, 64, v65
	v_readlane_b32 s44, v243, 3
	v_xor_b32_e32 v66, 32, v204
	v_lshlrev_b64 v[182:183], 2, v[180:181]
	v_cmp_lt_i32_e32 vcc, v64, v65
	v_readlane_b32 s52, v243, 11
	v_readlane_b32 s53, v243, 12
	v_cndmask_b32_e32 v64, v204, v64, vcc
	v_cmp_lt_i32_e32 vcc, v66, v65
	v_lshl_add_u64 v[92:93], s[52:53], 0, v[182:183]
	v_readlane_b32 s54, v243, 13
	v_cndmask_b32_e32 v65, v204, v66, vcc
	v_add_co_u32_e32 v94, vcc, 0x5000, v92
	v_readlane_b32 s55, v243, 14
	s_nop 0
	v_addc_co_u32_e32 v95, vcc, 0, v93, vcc
	v_add_co_u32_e32 v96, vcc, 0xb000, v92
	v_lshl_add_u64 v[72:73], s[54:55], 0, v[182:183]
	v_lshl_add_u64 v[74:75], v[92:93], 0, s[26:27]
	v_lshl_add_u64 v[76:77], v[92:93], 0, s[28:29]
	v_addc_co_u32_e32 v97, vcc, 0, v93, vcc
	v_lshlrev_b32_e32 v187, 2, v64
	v_lshlrev_b32_e32 v185, 2, v65
	global_load_dwordx4 v[64:67], v[92:93], off offset:16
	global_load_dwordx4 v[80:83], v[92:93], off
	global_load_dwordx4 v[68:71], v[72:73], off offset:16
	global_load_dwordx4 v[84:87], v[72:73], off
	s_nop 0
	global_load_dwordx4 v[72:75], v[74:75], off offset:16
	s_nop 0
	global_load_dwordx4 v[76:79], v[76:77], off offset:16
	s_nop 0
	global_load_dwordx4 v[92:95], v[94:95], off offset:2048
	s_nop 0
	global_load_dwordx4 v[96:99], v[96:97], off
	v_mov_b32_e32 v211, 0
	v_mov_b32_e32 v205, 0
	v_readlane_b32 s45, v243, 4
	v_readlane_b32 s46, v243, 5
	v_readlane_b32 s47, v243, 6
	v_readlane_b32 s48, v243, 7
	v_readlane_b32 s49, v243, 8
	v_readlane_b32 s50, v243, 9
	v_readlane_b32 s51, v243, 10
	v_readlane_b32 s56, v243, 15
	v_readlane_b32 s57, v243, 16
	v_readlane_b32 s58, v243, 17
	v_readlane_b32 s59, v243, 18
	s_waitcnt vmcnt(0)
; DI float dpp_ror1(float v) { return __int_as_float(__builtin_amdgcn_update_dpp(0, __float_as_int(v), 0x121, 0xf, 0xf, false)); }
; DI float dpp_ror2(float v) { return __int_as_float(__builtin_amdgcn_update_dpp(0, __float_as_int(v), 0x122, 0xf, 0xf, false)); }
;   DI void operator()(const f32x4 (&acc)[2][2][4][2], const Unit& u, int wr, int wc, int fr, int fq) const {
;     ...
;       for (int m = 0; m < 4; ++m) rsv[m] = row_rstd(ssq, row0 + 16 * m + fr, fq);
;       float p1[8], p2[8];
; #pragma unroll
;       for (int e = 0; e < 8; ++e) { p1[e] = 0.f; p2[e] = 0.f; }
; #pragma unroll
;       for (int m = 0; m < 4; ++m) {
;         float g[8], uu[8], a[8];
;         const float rs = rsv[m];
; #pragma unroll
;         for (int e = 0; e < 4; ++e) { g[e] = acc[ai][0][m][0][e] * rs; g[4 + e] = acc[ai][0][m][1][e] * rs; uu[e] = acc[ai][1][m][0][e] * rs; uu[4 + e] = acc[ai][1][m][1][e] * rs; }
; #pragma unroll
;         for (int e = 0; e < 8; ++e) {
;           const float x1 = dpp_ror1(g[e]), x2 = dpp_ror2(g[e]);
;           const float pr1 = (fr == 0) ? p1[e] : x1, pr2 = (fr < 2) ? p2[e] : x2;
;           a[e] = w2[e] * g[e] + w1[e] * pr1 + w0[e] * pr2 + bb[e];
;           p1[e] = x1; p2[e] = x2;
;         }
;         if (m == 0 && fr < 2) {
;           float* ha = headA + (size_t)(span * 2 + fr) * 5632 + col; float* hu = headU + (size_t)(span * 2 + fr) * 5632 + col;
;           *(f32x4*)ha = (f32x4){a[0], a[1], a[2], a[3]}; *(f32x4*)(ha + 4) = (f32x4){a[4], a[5], a[6], a[7]};
;           *(f32x4*)hu = (f32x4){uu[0], uu[1], uu[2], uu[3]}; *(f32x4*)(hu + 4) = (f32x4){uu[4], uu[5], uu[6], uu[7]};
;         } else {
	v_mov_b32_e32 v196, v192
	v_mov_b32_e32 v197, v206
	v_mov_b32_e32 v206, v193
	v_mov_b32_e32 v192, v194
	v_mov_b32_e32 v193, v208
	v_mov_b32_e32 v208, v195
	v_pk_add_f32 v[194:195], v[196:197], v[206:207]
	v_pk_add_f32 v[192:193], v[192:193], v[208:209]
	v_mov_b32_e32 v196, v212
	v_mov_b32_e32 v197, v216
	v_mov_b32_e32 v216, v213
	v_mov_b32_e32 v206, v214
	v_mov_b32_e32 v207, v218
	v_mov_b32_e32 v218, v215
	v_pk_add_f32 v[192:193], v[194:195], v[192:193]
	v_pk_add_f32 v[194:195], v[196:197], v[216:217]
	v_pk_add_f32 v[196:197], v[206:207], v[218:219]
	v_mov_b32_e32 v208, v220
	v_pk_add_f32 v[194:195], v[194:195], v[196:197]
	v_mov_b32_e32 v197, v192
	v_mov_b32_e32 v196, v194
	v_mov_b32_e32 v192, v195
	v_pk_add_f32 v[192:193], v[196:197], v[192:193]
	ds_bpermute_b32 v195, v187, v193
	ds_bpermute_b32 v194, v187, v192
	v_mov_b32_e32 v209, v224
	v_mov_b32_e32 v224, v221
	v_mov_b32_e32 v212, v222
	v_mov_b32_e32 v213, v226
	s_waitcnt lgkmcnt(0)
	v_pk_add_f32 v[192:193], v[192:193], v[194:195]
	ds_bpermute_b32 v195, v185, v193
	ds_bpermute_b32 v194, v185, v192
	v_mov_b32_e32 v226, v223
	v_mov_b32_e32 v196, v228
	v_mov_b32_e32 v197, v232
	v_mov_b32_e32 v232, v229
	s_waitcnt lgkmcnt(0)
	v_pk_add_f32 v[192:193], v[192:193], v[194:195]
	v_mov_b32_e32 v206, v230
	v_pk_fma_f32 v[192:193], v[192:193], s[30:31], v[178:179] op_sel_hi:[1,0,0]
	v_mov_b32_e32 v207, v234
	v_mul_f32_e32 v189, 0x4b800000, v193
	v_cmp_gt_f32_e64 s[12:13], s74, v193
	v_mov_b32_e32 v234, v231
	v_pk_add_f32 v[208:209], v[208:209], v[224:225]
	v_cndmask_b32_e64 v189, v193, v189, s[12:13]
	v_rsq_f32_e32 v189, v189
	v_pk_add_f32 v[212:213], v[212:213], v[226:227]
	v_pk_add_f32 v[196:197], v[196:197], v[232:233]
	v_pk_add_f32 v[194:195], v[206:207], v[234:235]
	v_mul_f32_e32 v191, 0x45800000, v189
	v_cndmask_b32_e64 v220, v189, v191, s[12:13]
	v_pk_add_f32 v[208:209], v[208:209], v[212:213]
	v_pk_add_f32 v[194:195], v[196:197], v[194:195]
	v_pk_mul_f32 v[156:157], v[156:157], v[220:221] op_sel_hi:[1,0]
	v_mov_b32_e32 v216, 0
	v_mov_b32_e32 v218, 0
	v_mov_b32_e32 v196, v194
	v_mov_b32_e32 v197, v208
	v_mov_b32_e32 v208, v195
	v_mov_b32_dpp v216, v156 row_ror:1 row_mask:0xf bank_mask:0xf
	v_mov_b32_dpp v218, v157 row_ror:1 row_mask:0xf bank_mask:0xf
	v_pk_add_f32 v[194:195], v[196:197], v[208:209]
	v_cndmask_b32_e64 v207, v218, 0, s[0:1]
	v_cndmask_b32_e64 v206, v216, 0, s[0:1]
	v_pk_mul_f32 v[158:159], v[158:159], v[220:221] op_sel_hi:[1,0]
	v_mov_b32_e32 v212, 0
	v_mov_b32_e32 v214, 0
	ds_bpermute_b32 v197, v187, v195
	ds_bpermute_b32 v196, v187, v194
	v_mov_b32_e32 v215, 0
	v_mov_b32_e32 v217, 0
	v_pk_mul_f32 v[206:207], v[92:93], v[206:207]
	v_mov_b32_dpp v212, v158 row_ror:1 row_mask:0xf bank_mask:0xf
	v_mov_b32_dpp v214, v159 row_ror:1 row_mask:0xf bank_mask:0xf
	v_mov_b32_dpp v215, v156 row_ror:2 row_mask:0xf bank_mask:0xf
	v_mov_b32_dpp v217, v157 row_ror:2 row_mask:0xf bank_mask:0xf
	v_pk_fma_f32 v[156:157], v[96:97], v[156:157], v[206:207]
	v_mov_b32_e32 v213, 0
	v_cndmask_b32_e64 v207, v214, 0, s[0:1]
	v_cndmask_b32_e64 v206, v212, 0, s[0:1]
	v_cndmask_b32_e64 v209, v217, 0, s[4:5]
	v_cndmask_b32_e64 v208, v215, 0, s[4:5]
	v_mov_b32_dpp v211, v158 row_ror:2 row_mask:0xf bank_mask:0xf
	v_mov_b32_dpp v213, v159 row_ror:2 row_mask:0xf bank_mask:0xf
	v_pk_mul_f32 v[206:207], v[94:95], v[206:207]
	v_pk_fma_f32 v[156:157], v[80:81], v[208:209], v[156:157]
	v_cndmask_b32_e64 v209, v213, 0, s[4:5]
	v_cndmask_b32_e64 v208, v211, 0, s[4:5]
	v_pk_fma_f32 v[158:159], v[98:99], v[158:159], v[206:207]
	v_pk_mul_f32 v[144:145], v[144:145], v[220:221] op_sel_hi:[1,0]
	v_pk_fma_f32 v[158:159], v[82:83], v[208:209], v[158:159]
	v_mov_b32_e32 v207, 0
	v_mov_b32_e32 v209, 0
	v_pk_mul_f32 v[146:147], v[146:147], v[220:221] op_sel_hi:[1,0]
	v_mov_b32_e32 v191, 0
	s_waitcnt lgkmcnt(0)
	v_pk_add_f32 v[194:195], v[194:195], v[196:197]
	v_mov_b32_dpp v207, v144 row_ror:1 row_mask:0xf bank_mask:0xf
	v_mov_b32_dpp v209, v145 row_ror:1 row_mask:0xf bank_mask:0xf
	v_mov_b32_dpp v191, v146 row_ror:1 row_mask:0xf bank_mask:0xf
	v_mov_b32_dpp v205, v147 row_ror:1 row_mask:0xf bank_mask:0xf
	ds_bpermute_b32 v197, v185, v195
	ds_bpermute_b32 v196, v185, v194
	v_pk_mul_f32 v[152:153], v[152:153], v[220:221] op_sel_hi:[1,0]
	v_pk_mul_f32 v[148:149], v[148:149], v[220:221] op_sel_hi:[1,0]
	v_pk_mul_f32 v[154:155], v[154:155], v[220:221] op_sel_hi:[1,0]
	v_pk_mul_f32 v[150:151], v[150:151], v[220:221] op_sel_hi:[1,0]
	v_mov_b32_e32 v206, 0
	v_mov_b32_e32 v208, 0
	v_cndmask_b32_e64 v223, v209, 0, s[0:1]
	v_cndmask_b32_e64 v222, v207, 0, s[0:1]
	v_mov_b32_e32 v189, 0
	v_mov_b32_e32 v193, 0
	v_cndmask_b32_e64 v221, v205, 0, s[0:1]
	v_cndmask_b32_e64 v220, v191, 0, s[0:1]
	v_mov_b32_dpp v206, v144 row_ror:2 row_mask:0xf bank_mask:0xf
	v_mov_b32_dpp v208, v145 row_ror:2 row_mask:0xf bank_mask:0xf
	v_pk_mul_f32 v[222:223], v[72:73], v[222:223]
	v_mov_b32_dpp v189, v146 row_ror:2 row_mask:0xf bank_mask:0xf
	v_mov_b32_dpp v193, v147 row_ror:2 row_mask:0xf bank_mask:0xf
	v_pk_mul_f32 v[220:221], v[74:75], v[220:221]
	v_cndmask_b32_e64 v225, v208, 0, s[4:5]
	v_cndmask_b32_e64 v224, v206, 0, s[4:5]
	v_pk_fma_f32 v[144:145], v[76:77], v[144:145], v[222:223]
	v_cndmask_b32_e64 v223, v193, 0, s[4:5]
	v_cndmask_b32_e64 v222, v189, 0, s[4:5]
	v_pk_fma_f32 v[146:147], v[78:79], v[146:147], v[220:221]
	v_pk_fma_f32 v[144:145], v[64:65], v[224:225], v[144:145]
	v_pk_fma_f32 v[146:147], v[66:67], v[222:223], v[146:147]
	v_cmp_gt_f32_e32 vcc, s74, v192
	v_pk_add_f32 v[156:157], v[84:85], v[156:157]
	v_pk_add_f32 v[158:159], v[86:87], v[158:159]
	v_pk_add_f32 v[144:145], v[68:69], v[144:145]
	v_pk_add_f32 v[146:147], v[70:71], v[146:147]
	s_and_saveexec_b64 s[12:13], s[10:11]
	s_xor_b64 s[12:13], exec, s[12:13]
	s_cbranch_execz .LBB0_814
; DI unsigned pack2(float lo, float hi) { f32x2 v = {lo, hi}; bf16v2 r = __builtin_convertvector(v, bf16v2); return __builtin_bit_cast(unsigned, r); }
; DI float silu_f(float x) { return x * sigmoid_f(x); }
;   DI void operator()(const f32x4 (&acc)[2][2][4][2], const Unit& u, int wr, int wc, int fr, int fq) const {
;     ...
;           u32x4 w;
;           w.x = pack2(silu_f(a[0]) * uu[0], silu_f(a[1]) * uu[1]);
;           w.y = pack2(silu_f(a[2]) * uu[2], silu_f(a[3]) * uu[3]);
;           w.z = pack2(silu_f(a[4]) * uu[4], silu_f(a[5]) * uu[5]);
;           w.w = pack2(silu_f(a[6]) * uu[6], silu_f(a[7]) * uu[7]);
;           *(u32x4*)(H + (size_t)(row0 + 16 * m + fr) * 5632 + col) = w;
;         }
	v_mul_f32_e32 v219, 0xbfb8aa3b, v156
	v_exp_f32_e32 v219, v219
	v_mul_f32_e32 v220, 0xbfb8aa3b, v157
	v_exp_f32_e32 v220, v220
	v_mul_f32_e32 v222, 0xbfb8aa3b, v159
	v_add_f32_e32 v219, 1.0, v219
	v_exp_f32_e32 v223, v222
	v_add_f32_e32 v221, 1.0, v220
	v_rcp_f32_e32 v220, v219
	v_mul_f32_e32 v219, 0xbfb8aa3b, v158
	v_exp_f32_e32 v219, v219
	v_rcp_f32_e32 v221, v221
	v_add_f32_e32 v219, 1.0, v219
	v_rcp_f32_e32 v222, v219
	v_add_f32_e32 v219, 1.0, v223
	v_rcp_f32_e32 v223, v219
	v_pk_mul_f32 v[156:157], v[156:157], v[220:221]
	s_nop 0
	v_pk_mul_f32 v[152:153], v[152:153], v[156:157]
	v_pk_mul_f32 v[156:157], v[158:159], v[222:223]
	v_cvt_pk_bf16_f32 v152, v152, v153
	v_mul_f32_e32 v153, 0xbfb8aa3b, v144
	v_pk_mul_f32 v[154:155], v[154:155], v[156:157]
	v_exp_f32_e32 v156, v153
	v_mul_f32_e32 v153, 0xbfb8aa3b, v145
	v_exp_f32_e32 v157, v153
	v_cvt_pk_bf16_f32 v153, v154, v155
	v_add_f32_e32 v154, 1.0, v156
	v_mul_f32_e32 v156, 0xbfb8aa3b, v146
	v_add_f32_e32 v155, 1.0, v157
	v_mul_f32_e32 v157, 0xbfb8aa3b, v147
	v_exp_f32_e32 v156, v156
	v_exp_f32_e32 v157, v157
	v_rcp_f32_e32 v154, v154
	v_rcp_f32_e32 v155, v155
	v_add_f32_e32 v156, 1.0, v156
	v_add_f32_e32 v157, 1.0, v157
	v_rcp_f32_e32 v156, v156
	v_rcp_f32_e32 v157, v157
	v_pk_mul_f32 v[144:145], v[144:145], v[154:155]
	s_nop 0
	v_pk_mul_f32 v[144:145], v[148:149], v[144:145]
	s_nop 0
	v_cvt_pk_bf16_f32 v154, v144, v145
	v_pk_mul_f32 v[144:145], v[146:147], v[156:157]
	s_nop 0
	v_pk_mul_f32 v[144:145], v[150:151], v[144:145]
	s_nop 0
	v_cvt_pk_bf16_f32 v155, v144, v145
	v_mov_b64_e32 v[144:145], s[16:17]
	v_mad_i64_i32 v[144:145], s[14:15], v190, s75, v[144:145]
	v_lshl_add_u64 v[144:145], v[180:181], 1, v[144:145]
	global_store_dwordx4 v[144:145], v[152:155], off

; #define PG8_STAGE(bufoff, gbase, voff) do { _Pragma("unroll") for (int _i = 0; _i < 2; ++_i) \
;     __builtin_amdgcn_global_load_lds((const unsigned*)((const char*)(gbase) + (voff)[_i]), (LAS unsigned*)(lds + (bufoff) + ldsw + _i * 8192), 16, 0, 0); } while (0)
; #define PG8_LDA(dst, b, h) do { _Pragma("unroll") for (int m = 0; m < 4; ++m) _Pragma("unroll") for (int k = 0; k < 2; ++k) dst[m][k] = *(const LAS bf16x8*)(lds + PG8_SA(b, h) + aoff + m * 2048 + k * 1024); } while (0)
; #define PG8_LDB(dst, b, h) do { _Pragma("unroll") for (int n = 0; n < 2; ++n) _Pragma("unroll") for (int k = 0; k < 2; ++k) dst[n][k] = *(const LAS bf16x8*)(lds + PG8_SB(b, h) + boff + n * 2048 + k * 1024); } while (0)
; #define PG8_MMA(ai, bj, At, Bt) do { __builtin_amdgcn_s_setprio(1); _Pragma("unroll") for (int m = 0; m < 4; ++m) _Pragma("unroll") for (int n = 0; n < 2; ++n) _Pragma("unroll") for (int k = 0; k < 2; ++k) \
;     acc[ai][bj][m][n] = __builtin_amdgcn_mfma_f32_16x16x32_bf16(Bt[n][k], At[m][k], acc[ai][bj][m][n], 0, 0, 0); __builtin_amdgcn_s_setprio(0); } while (0)
; #define PG8_WAIT_V(n) asm volatile("s_waitcnt vmcnt(" #n ")" ::: "memory")
; #define PG8_WAIT_L(n) asm volatile("s_waitcnt lgkmcnt(" #n ")" ::: "memory")
; #define PG8_BAR __builtin_amdgcn_s_barrier()
; #define PG8_SCHED __builtin_amdgcn_sched_barrier(0)
; template <class Epi, class Sched = StaticOrder>
; DI void gemm_phase(LAS unsigned char* lds, const Gemm g, const Sched& S, const Epi& E) {
;     ...
;       PG8_LDB(B0, 0, 0); PG8_SCHED; PG8_LDA(At, 0, 0); PG8_STAGE(PG8_SA(1, 1), a1 + hstep, voffA);
;       PG8_WAIT_L(8); PG8_BAR; PG8_WAIT_L(0); PG8_MMA(0, 0, At, B0); PG8_BAR; PG8_SCHED;
;       PG8_LDB(B1, 0, 1); PG8_STAGE(PG8_SB(0, 0), b2, voffB);
;       PG8_BAR; PG8_WAIT_L(0); PG8_MMA(0, 1, At, B1); PG8_BAR;
;       PG8_LDA(At, 0, 1); PG8_STAGE(PG8_SA(0, 0), a2, voffA);
;       PG8_BAR; PG8_WAIT_L(0); PG8_MMA(1, 0, At, B0); PG8_BAR; PG8_SCHED;
;       PG8_STAGE(PG8_SB(0, 1), b2 + hstep, voffB);
;       PG8_WAIT_V(6); PG8_BAR; PG8_MMA(1, 1, At, B1); PG8_BAR;
.LBB0_961:
	ds_read_b128 v[128:131], v214
	ds_read_b128 v[132:135], v214 offset:1024
	ds_read_b128 v[136:139], v214 offset:2048
	ds_read_b128 v[140:143], v214 offset:3072
	s_add_u32 s20, s18, 0xffea0080
	s_addc_u32 s21, s19, -1
	s_cmpk_eq_i32 s44, 0x54
	s_cselect_b32 s23, s5, s21
	s_cselect_b32 s22, s4, s20
	s_cselect_b32 s21, s7, s43
	s_cselect_b32 s20, s6, s42
	s_add_i32 m0, s31, 0xc000
	ds_read_b128 v[144:147], v215
	ds_read_b128 v[148:151], v215 offset:1024
	ds_read_b128 v[152:155], v215 offset:2048
	ds_read_b128 v[156:159], v215 offset:3072
	ds_read_b128 v[160:163], v215 offset:4096
	ds_read_b128 v[164:167], v215 offset:5120
	ds_read_b128 v[168:171], v215 offset:6144
	ds_read_b128 v[172:175], v215 offset:7168
	global_load_lds_dwordx4 v184, s[18:19]
	s_add_i32 m0, s31, 0xe000
	s_nop 0
	global_load_lds_dwordx4 v186, s[18:19]
	s_waitcnt lgkmcnt(0)
	s_setprio 1
	s_barrier
	v_mfma_f32_16x16x32_bf16 v[124:127], v[128:131], v[144:147], v[124:127]
	v_mfma_f32_16x16x32_bf16 v[120:123], v[136:139], v[144:147], v[120:123]
	v_mfma_f32_16x16x32_bf16 v[108:111], v[128:131], v[152:155], v[108:111]
	v_mfma_f32_16x16x32_bf16 v[104:107], v[136:139], v[152:155], v[104:107]
	v_mfma_f32_16x16x32_bf16 v[92:95], v[128:131], v[160:163], v[92:95]
	v_mfma_f32_16x16x32_bf16 v[88:91], v[136:139], v[160:163], v[88:91]
	v_mfma_f32_16x16x32_bf16 v[76:79], v[128:131], v[168:171], v[76:79]
	v_mfma_f32_16x16x32_bf16 v[72:75], v[136:139], v[168:171], v[72:75]
	v_mfma_f32_16x16x32_bf16 v[124:127], v[132:135], v[148:151], v[124:127]
	v_mfma_f32_16x16x32_bf16 v[120:123], v[140:143], v[148:151], v[120:123]
	v_mfma_f32_16x16x32_bf16 v[108:111], v[132:135], v[156:159], v[108:111]
	v_mfma_f32_16x16x32_bf16 v[104:107], v[140:143], v[156:159], v[104:107]
	v_mfma_f32_16x16x32_bf16 v[92:95], v[132:135], v[164:167], v[92:95]
	v_mfma_f32_16x16x32_bf16 v[88:91], v[140:143], v[164:167], v[88:91]
	v_mfma_f32_16x16x32_bf16 v[76:79], v[132:135], v[172:175], v[76:79]
	v_mfma_f32_16x16x32_bf16 v[72:75], v[140:143], v[172:175], v[72:75]
	s_barrier
	s_setprio 0
	s_add_i32 s45, s46, s30
	s_add_u32 s98, s20, 0x80
	s_addc_u32 s99, s21, 0
	s_add_u32 s100, s22, 0x80
	s_addc_u32 s101, s23, 0
	s_mov_b32 m0, s45
	ds_read_b128 v[192:195], v216
	ds_read_b128 v[196:199], v216 offset:1024
	ds_read_b128 v[200:203], v216 offset:2048
	ds_read_b128 v[204:207], v216 offset:3072
	global_load_lds_dwordx4 v178, s[20:21]
	s_add_i32 m0, s45, 0x2000
	s_nop 0
	global_load_lds_dwordx4 v182, s[20:21]
	s_waitcnt lgkmcnt(0)
	s_setprio 1
	s_barrier
	v_mfma_f32_16x16x32_bf16 v[116:119], v[192:195], v[144:147], v[116:119]
	v_mfma_f32_16x16x32_bf16 v[112:115], v[200:203], v[144:147], v[112:115]
	v_mfma_f32_16x16x32_bf16 v[100:103], v[192:195], v[152:155], v[100:103]
	v_mfma_f32_16x16x32_bf16 v[96:99], v[200:203], v[152:155], v[96:99]
	v_mfma_f32_16x16x32_bf16 v[84:87], v[192:195], v[160:163], v[84:87]
	v_mfma_f32_16x16x32_bf16 v[80:83], v[200:203], v[160:163], v[80:83]
	v_mfma_f32_16x16x32_bf16 v[68:71], v[192:195], v[168:171], v[68:71]
	v_mfma_f32_16x16x32_bf16 v[64:67], v[200:203], v[168:171], v[64:67]
	v_mfma_f32_16x16x32_bf16 v[116:119], v[196:199], v[148:151], v[116:119]
	v_mfma_f32_16x16x32_bf16 v[112:115], v[204:207], v[148:151], v[112:115]
	v_mfma_f32_16x16x32_bf16 v[100:103], v[196:199], v[156:159], v[100:103]
	v_mfma_f32_16x16x32_bf16 v[96:99], v[204:207], v[156:159], v[96:99]
	v_mfma_f32_16x16x32_bf16 v[84:87], v[196:199], v[164:167], v[84:87]
	v_mfma_f32_16x16x32_bf16 v[80:83], v[204:207], v[164:167], v[80:83]
	v_mfma_f32_16x16x32_bf16 v[68:71], v[196:199], v[172:175], v[68:71]
	v_mfma_f32_16x16x32_bf16 v[64:67], v[204:207], v[172:175], v[64:67]
	s_barrier
	s_setprio 0
	s_mov_b32 m0, s31
	ds_read_b128 v[144:147], v215 offset:16384
	ds_read_b128 v[148:151], v215 offset:17408
	ds_read_b128 v[152:155], v215 offset:18432
	ds_read_b128 v[156:159], v215 offset:19456
	ds_read_b128 v[160:163], v215 offset:20480
	ds_read_b128 v[164:167], v215 offset:21504
	ds_read_b128 v[168:171], v215 offset:22528
	ds_read_b128 v[172:175], v215 offset:23552
	global_load_lds_dwordx4 v176, s[22:23]
	s_mov_b32 m0, s33
	s_nop 0
	global_load_lds_dwordx4 v180, s[22:23]
	s_waitcnt lgkmcnt(0)
	s_setprio 1
	s_barrier
	v_mfma_f32_16x16x32_bf16 v[60:63], v[128:131], v[144:147], v[60:63]
	v_mfma_f32_16x16x32_bf16 v[56:59], v[136:139], v[144:147], v[56:59]
	v_mfma_f32_16x16x32_bf16 v[44:47], v[128:131], v[152:155], v[44:47]
	v_mfma_f32_16x16x32_bf16 v[40:43], v[136:139], v[152:155], v[40:43]
	v_mfma_f32_16x16x32_bf16 v[28:31], v[128:131], v[160:163], v[28:31]
	v_mfma_f32_16x16x32_bf16 v[24:27], v[136:139], v[160:163], v[24:27]
	v_mfma_f32_16x16x32_bf16 v[12:15], v[128:131], v[168:171], v[12:15]
	v_mfma_f32_16x16x32_bf16 v[8:11], v[136:139], v[168:171], v[8:11]
	v_mfma_f32_16x16x32_bf16 v[60:63], v[132:135], v[148:151], v[60:63]
	v_mfma_f32_16x16x32_bf16 v[56:59], v[140:143], v[148:151], v[56:59]
	v_mfma_f32_16x16x32_bf16 v[44:47], v[132:135], v[156:159], v[44:47]
	v_mfma_f32_16x16x32_bf16 v[40:43], v[140:143], v[156:159], v[40:43]
	v_mfma_f32_16x16x32_bf16 v[28:31], v[132:135], v[164:167], v[28:31]
	v_mfma_f32_16x16x32_bf16 v[24:27], v[140:143], v[164:167], v[24:27]
	v_mfma_f32_16x16x32_bf16 v[12:15], v[132:135], v[172:175], v[12:15]
	v_mfma_f32_16x16x32_bf16 v[8:11], v[140:143], v[172:175], v[8:11]
	s_barrier
	s_setprio 0
	s_add_u32 s52, s20, 0x160000
	s_addc_u32 s53, s21, 0
	s_add_i32 s45, s47, s30
	s_mov_b32 m0, s45
	s_nop 0
	global_load_lds_dwordx4 v178, s[52:53]
	s_add_i32 m0, s45, 0x2000
	s_nop 0
	global_load_lds_dwordx4 v182, s[52:53]
	s_waitcnt vmcnt(6)
	s_setprio 1
	s_barrier
; #define PG8_STAGE(bufoff, gbase, voff) do { _Pragma("unroll") for (int _i = 0; _i < 2; ++_i) \
;     __builtin_amdgcn_global_load_lds((const unsigned*)((const char*)(gbase) + (voff)[_i]), (LAS unsigned*)(lds + (bufoff) + ldsw + _i * 8192), 16, 0, 0); } while (0)
; #define PG8_LDA(dst, b, h) do { _Pragma("unroll") for (int m = 0; m < 4; ++m) _Pragma("unroll") for (int k = 0; k < 2; ++k) dst[m][k] = *(const LAS bf16x8*)(lds + PG8_SA(b, h) + aoff + m * 2048 + k * 1024); } while (0)
; #define PG8_LDB(dst, b, h) do { _Pragma("unroll") for (int n = 0; n < 2; ++n) _Pragma("unroll") for (int k = 0; k < 2; ++k) dst[n][k] = *(const LAS bf16x8*)(lds + PG8_SB(b, h) + boff + n * 2048 + k * 1024); } while (0)
; #define PG8_MMA(ai, bj, At, Bt) do { __builtin_amdgcn_s_setprio(1); _Pragma("unroll") for (int m = 0; m < 4; ++m) _Pragma("unroll") for (int n = 0; n < 2; ++n) _Pragma("unroll") for (int k = 0; k < 2; ++k) \
;     acc[ai][bj][m][n] = __builtin_amdgcn_mfma_f32_16x16x32_bf16(Bt[n][k], At[m][k], acc[ai][bj][m][n], 0, 0, 0); __builtin_amdgcn_s_setprio(0); } while (0)
; #define PG8_WAIT_V(n) asm volatile("s_waitcnt vmcnt(" #n ")" ::: "memory")
; #define PG8_WAIT_L(n) asm volatile("s_waitcnt lgkmcnt(" #n ")" ::: "memory")
; #define PG8_BAR __builtin_amdgcn_s_barrier()
; #define PG8_SCHED __builtin_amdgcn_sched_barrier(0)
; template <class Epi, class Sched = StaticOrder>
; DI void gemm_phase(LAS unsigned char* lds, const Gemm g, const Sched& S, const Epi& E) {
;     ...
;       PG8_WAIT_V(6); PG8_BAR; PG8_MMA(1, 1, At, B1); PG8_BAR;
;       PG8_LDB(B0, 1, 0); PG8_SCHED; PG8_LDA(At, 1, 0); PG8_STAGE(PG8_SA(0, 1), a2 + hstep, voffA);
;       PG8_WAIT_L(8); PG8_BAR; PG8_WAIT_L(0); PG8_MMA(0, 0, At, B0); PG8_BAR; PG8_SCHED;
;       PG8_LDB(B1, 1, 1); PG8_STAGE(PG8_SB(1, 0), b3, voffB);
;       PG8_BAR; PG8_WAIT_L(0); PG8_MMA(0, 1, At, B1); PG8_BAR;
;       PG8_LDA(At, 1, 1); PG8_STAGE(PG8_SA(1, 0), a3, voffA);
;       PG8_BAR; PG8_WAIT_L(0); PG8_MMA(1, 0, At, B0); PG8_BAR; PG8_SCHED;
	v_mfma_f32_16x16x32_bf16 v[52:55], v[192:195], v[144:147], v[52:55]
	v_mfma_f32_16x16x32_bf16 v[48:51], v[200:203], v[144:147], v[48:51]
	v_mfma_f32_16x16x32_bf16 v[36:39], v[192:195], v[152:155], v[36:39]
	v_mfma_f32_16x16x32_bf16 v[32:35], v[200:203], v[152:155], v[32:35]
	v_mfma_f32_16x16x32_bf16 v[20:23], v[192:195], v[160:163], v[20:23]
	v_mfma_f32_16x16x32_bf16 v[16:19], v[200:203], v[160:163], v[16:19]
	v_mfma_f32_16x16x32_bf16 v[4:7], v[192:195], v[168:171], v[4:7]
	v_mfma_f32_16x16x32_bf16 v[0:3], v[200:203], v[168:171], v[0:3]
	v_mfma_f32_16x16x32_bf16 v[52:55], v[196:199], v[148:151], v[52:55]
	v_mfma_f32_16x16x32_bf16 v[48:51], v[204:207], v[148:151], v[48:51]
	v_mfma_f32_16x16x32_bf16 v[36:39], v[196:199], v[156:159], v[36:39]
	v_mfma_f32_16x16x32_bf16 v[32:35], v[204:207], v[156:159], v[32:35]
	v_mfma_f32_16x16x32_bf16 v[20:23], v[196:199], v[164:167], v[20:23]
	v_mfma_f32_16x16x32_bf16 v[16:19], v[204:207], v[164:167], v[16:19]
	v_mfma_f32_16x16x32_bf16 v[4:7], v[196:199], v[172:175], v[4:7]
	v_mfma_f32_16x16x32_bf16 v[0:3], v[204:207], v[172:175], v[0:3]
	s_barrier
	s_setprio 0
	s_add_i32 s45, 0, 0x18000
	v_add_u32_e32 v140, s45, v212
	ds_read_b128 v[128:131], v140
	ds_read_b128 v[132:135], v140 offset:1024
	ds_read_b128 v[136:139], v140 offset:2048
	ds_read_b128 v[140:143], v140 offset:3072
	s_add_u32 s22, s22, 0x160000
	s_addc_u32 s23, s23, 0
	s_mov_b32 m0, s34
	ds_read_b128 v[144:147], v215 offset:32768
	ds_read_b128 v[148:151], v215 offset:33792
	ds_read_b128 v[152:155], v215 offset:34816
	ds_read_b128 v[156:159], v215 offset:35840
	ds_read_b128 v[160:163], v215 offset:36864
	ds_read_b128 v[164:167], v215 offset:37888
	ds_read_b128 v[168:171], v215 offset:38912
	ds_read_b128 v[172:175], v215 offset:39936
	global_load_lds_dwordx4 v176, s[22:23]
	s_mov_b32 m0, s35
	s_nop 0
	global_load_lds_dwordx4 v180, s[22:23]
	s_waitcnt lgkmcnt(0)
	s_setprio 1
	s_barrier
	v_mfma_f32_16x16x32_bf16 v[124:127], v[128:131], v[144:147], v[124:127]
	v_mfma_f32_16x16x32_bf16 v[120:123], v[136:139], v[144:147], v[120:123]
	v_mfma_f32_16x16x32_bf16 v[108:111], v[128:131], v[152:155], v[108:111]
	v_mfma_f32_16x16x32_bf16 v[104:107], v[136:139], v[152:155], v[104:107]
	v_mfma_f32_16x16x32_bf16 v[92:95], v[128:131], v[160:163], v[92:95]
	v_mfma_f32_16x16x32_bf16 v[88:91], v[136:139], v[160:163], v[88:91]
	v_mfma_f32_16x16x32_bf16 v[76:79], v[128:131], v[168:171], v[76:79]
	v_mfma_f32_16x16x32_bf16 v[72:75], v[136:139], v[168:171], v[72:75]
	v_mfma_f32_16x16x32_bf16 v[124:127], v[132:135], v[148:151], v[124:127]
	v_mfma_f32_16x16x32_bf16 v[120:123], v[140:143], v[148:151], v[120:123]
	v_mfma_f32_16x16x32_bf16 v[108:111], v[132:135], v[156:159], v[108:111]
	v_mfma_f32_16x16x32_bf16 v[104:107], v[140:143], v[156:159], v[104:107]
	v_mfma_f32_16x16x32_bf16 v[92:95], v[132:135], v[164:167], v[92:95]
	v_mfma_f32_16x16x32_bf16 v[88:91], v[140:143], v[164:167], v[88:91]
	v_mfma_f32_16x16x32_bf16 v[76:79], v[132:135], v[172:175], v[76:79]
	v_mfma_f32_16x16x32_bf16 v[72:75], v[140:143], v[172:175], v[72:75]
	s_barrier
	s_setprio 0
	s_add_i32 s22, 0, 0x1c000
	s_add_i32 s23, s45, s30
	v_add_u32_e32 v204, s22, v212
	s_mov_b32 m0, s23
	ds_read_b128 v[192:195], v204
	ds_read_b128 v[196:199], v204 offset:1024
	ds_read_b128 v[200:203], v204 offset:2048
	ds_read_b128 v[204:207], v204 offset:3072
	global_load_lds_dwordx4 v178, s[98:99]
	s_add_i32 m0, s23, 0x2000
	s_nop 0
	global_load_lds_dwordx4 v182, s[98:99]
	s_waitcnt lgkmcnt(0)
	s_setprio 1
	s_barrier
	v_mfma_f32_16x16x32_bf16 v[116:119], v[192:195], v[144:147], v[116:119]
	v_mfma_f32_16x16x32_bf16 v[112:115], v[200:203], v[144:147], v[112:115]
	v_mfma_f32_16x16x32_bf16 v[100:103], v[192:195], v[152:155], v[100:103]
	v_mfma_f32_16x16x32_bf16 v[96:99], v[200:203], v[152:155], v[96:99]
	v_mfma_f32_16x16x32_bf16 v[84:87], v[192:195], v[160:163], v[84:87]
	v_mfma_f32_16x16x32_bf16 v[80:83], v[200:203], v[160:163], v[80:83]
	v_mfma_f32_16x16x32_bf16 v[68:71], v[192:195], v[168:171], v[68:71]
	v_mfma_f32_16x16x32_bf16 v[64:67], v[200:203], v[168:171], v[64:67]
	v_mfma_f32_16x16x32_bf16 v[116:119], v[196:199], v[148:151], v[116:119]
	v_mfma_f32_16x16x32_bf16 v[112:115], v[204:207], v[148:151], v[112:115]
	v_mfma_f32_16x16x32_bf16 v[100:103], v[196:199], v[156:159], v[100:103]
	v_mfma_f32_16x16x32_bf16 v[96:99], v[204:207], v[156:159], v[96:99]
	v_mfma_f32_16x16x32_bf16 v[84:87], v[196:199], v[164:167], v[84:87]
	v_mfma_f32_16x16x32_bf16 v[80:83], v[204:207], v[164:167], v[80:83]
	v_mfma_f32_16x16x32_bf16 v[68:71], v[196:199], v[172:175], v[68:71]
	v_mfma_f32_16x16x32_bf16 v[64:67], v[204:207], v[172:175], v[64:67]
	s_barrier
	s_setprio 0
	s_mov_b32 m0, s37
	ds_read_b128 v[144:147], v215 offset:49152
	ds_read_b128 v[148:151], v215 offset:50176
	ds_read_b128 v[152:155], v215 offset:51200
	ds_read_b128 v[156:159], v215 offset:52224
	ds_read_b128 v[160:163], v215 offset:53248
	ds_read_b128 v[164:167], v215 offset:54272
	ds_read_b128 v[168:171], v215 offset:55296
	ds_read_b128 v[172:175], v215 offset:56320
	global_load_lds_dwordx4 v176, s[100:101]
	s_mov_b32 m0, s38
	s_nop 0
	global_load_lds_dwordx4 v180, s[100:101]
	s_waitcnt lgkmcnt(0)
	s_setprio 1
	s_barrier
; #define PG8_STAGE(bufoff, gbase, voff) do { _Pragma("unroll") for (int _i = 0; _i < 2; ++_i) \
;     __builtin_amdgcn_global_load_lds((const unsigned*)((const char*)(gbase) + (voff)[_i]), (LAS unsigned*)(lds + (bufoff) + ldsw + _i * 8192), 16, 0, 0); } while (0)
; #define PG8_MMA(ai, bj, At, Bt) do { __builtin_amdgcn_s_setprio(1); _Pragma("unroll") for (int m = 0; m < 4; ++m) _Pragma("unroll") for (int n = 0; n < 2; ++n) _Pragma("unroll") for (int k = 0; k < 2; ++k) \
;     acc[ai][bj][m][n] = __builtin_amdgcn_mfma_f32_16x16x32_bf16(Bt[n][k], At[m][k], acc[ai][bj][m][n], 0, 0, 0); __builtin_amdgcn_s_setprio(0); } while (0)
; #define PG8_WAIT_V(n) asm volatile("s_waitcnt vmcnt(" #n ")" ::: "memory")
; #define PG8_WAIT_L(n) asm volatile("s_waitcnt lgkmcnt(" #n ")" ::: "memory")
; #define PG8_BAR __builtin_amdgcn_s_barrier()
; #define PG8_SCHED __builtin_amdgcn_sched_barrier(0)
; template <class Epi, class Sched = StaticOrder>
; DI void gemm_phase(LAS unsigned char* lds, const Gemm g, const Sched& S, const Epi& E) {
;     ...
;       PG8_BAR; PG8_WAIT_L(0); PG8_MMA(1, 0, At, B0); PG8_BAR; PG8_SCHED;
;       PG8_STAGE(PG8_SB(1, 1), b3 + hstep, voffB);
;       PG8_WAIT_V(6); PG8_BAR; PG8_MMA(1, 1, At, B1); PG8_BAR;
	v_mfma_f32_16x16x32_bf16 v[60:63], v[128:131], v[144:147], v[60:63]
	v_mfma_f32_16x16x32_bf16 v[56:59], v[136:139], v[144:147], v[56:59]
	v_mfma_f32_16x16x32_bf16 v[44:47], v[128:131], v[152:155], v[44:47]
	v_mfma_f32_16x16x32_bf16 v[40:43], v[136:139], v[152:155], v[40:43]
	v_mfma_f32_16x16x32_bf16 v[28:31], v[128:131], v[160:163], v[28:31]
	v_mfma_f32_16x16x32_bf16 v[24:27], v[136:139], v[160:163], v[24:27]
	v_mfma_f32_16x16x32_bf16 v[12:15], v[128:131], v[168:171], v[12:15]
	v_mfma_f32_16x16x32_bf16 v[8:11], v[136:139], v[168:171], v[8:11]
	v_mfma_f32_16x16x32_bf16 v[60:63], v[132:135], v[148:151], v[60:63]
	v_mfma_f32_16x16x32_bf16 v[56:59], v[140:143], v[148:151], v[56:59]
	v_mfma_f32_16x16x32_bf16 v[44:47], v[132:135], v[156:159], v[44:47]
	v_mfma_f32_16x16x32_bf16 v[40:43], v[140:143], v[156:159], v[40:43]
	v_mfma_f32_16x16x32_bf16 v[28:31], v[132:135], v[164:167], v[28:31]
	v_mfma_f32_16x16x32_bf16 v[24:27], v[140:143], v[164:167], v[24:27]
	v_mfma_f32_16x16x32_bf16 v[12:15], v[132:135], v[172:175], v[12:15]
	v_mfma_f32_16x16x32_bf16 v[8:11], v[140:143], v[172:175], v[8:11]
	s_barrier
	s_setprio 0
	s_add_u32 s20, s20, 0x160080
	s_addc_u32 s21, s21, 0
	s_add_i32 s22, s22, s30
	s_mov_b32 m0, s22
	s_nop 0
	global_load_lds_dwordx4 v178, s[20:21]
	s_add_i32 m0, s22, 0x2000
	s_nop 0
	global_load_lds_dwordx4 v182, s[20:21]
	s_waitcnt vmcnt(6)
	s_add_i32 s44, s44, 2
	s_add_u32 s18, s18, 0x100
	s_addc_u32 s19, s19, 0
	s_add_u32 s42, s42, 0x100
	s_addc_u32 s43, s43, 0
	s_cmpk_gt_u32 s44, 0x55
	s_setprio 1
	s_barrier
	v_mfma_f32_16x16x32_bf16 v[52:55], v[192:195], v[144:147], v[52:55]
	v_mfma_f32_16x16x32_bf16 v[48:51], v[200:203], v[144:147], v[48:51]
	v_mfma_f32_16x16x32_bf16 v[36:39], v[192:195], v[152:155], v[36:39]
	v_mfma_f32_16x16x32_bf16 v[32:35], v[200:203], v[152:155], v[32:35]
	v_mfma_f32_16x16x32_bf16 v[20:23], v[192:195], v[160:163], v[20:23]
	v_mfma_f32_16x16x32_bf16 v[16:19], v[200:203], v[160:163], v[16:19]
	v_mfma_f32_16x16x32_bf16 v[4:7], v[192:195], v[168:171], v[4:7]
	v_mfma_f32_16x16x32_bf16 v[0:3], v[200:203], v[168:171], v[0:3]
	v_mfma_f32_16x16x32_bf16 v[52:55], v[196:199], v[148:151], v[52:55]
	v_mfma_f32_16x16x32_bf16 v[48:51], v[204:207], v[148:151], v[48:51]
	v_mfma_f32_16x16x32_bf16 v[36:39], v[196:199], v[156:159], v[36:39]
	v_mfma_f32_16x16x32_bf16 v[32:35], v[204:207], v[156:159], v[32:35]
	v_mfma_f32_16x16x32_bf16 v[20:23], v[196:199], v[164:167], v[20:23]
	v_mfma_f32_16x16x32_bf16 v[16:19], v[204:207], v[164:167], v[16:19]
	v_mfma_f32_16x16x32_bf16 v[4:7], v[196:199], v[172:175], v[4:7]
	v_mfma_f32_16x16x32_bf16 v[0:3], v[204:207], v[172:175], v[0:3]
	s_barrier
	s_setprio 0
	s_cbranch_scc0 .LBB0_961
; DI unsigned pack2(float lo, float hi) { f32x2 v = {lo, hi}; bf16v2 r = __builtin_convertvector(v, bf16v2); return __builtin_bit_cast(unsigned, r); }
;   DI void operator()(const f32x4 (&acc)[2][2][4][2], const Unit& u, int wr, int wc, int fr, int fq) const {
;     const int row0 = u.pm * BM + wr * 64 + fr, col0 = u.pn * BM + wc * 32 + 8 * fq;
; #pragma unroll
;     for (int ai = 0; ai < 2; ++ai) {
;       f32x4 bv[4][2][2];
; #pragma unroll
;       for (int m = 0; m < 4; ++m)
; #pragma unroll
;         for (int bj = 0; bj < 2; ++bj) {
;           const float* bp = base + (size_t)(row0 + ai * HALF + m * 16) * 2048 + col0 + bj * HALF;
;           bv[m][bj][0] = *(const f32x4*)bp; bv[m][bj][1] = *(const f32x4*)(bp + 4);
;         }
; #pragma unroll
;       for (int m = 0; m < 4; ++m) {
;         const int row = row0 + ai * HALF + m * 16;
;         const size_t off = (size_t)row * 2048 + col0;
;         float ss = 0.f;
; #pragma unroll
;         for (int bj = 0; bj < 2; ++bj) {
;           const f32x4 v0 = acc[ai][bj][m][0] + bv[m][bj][0], v1 = acc[ai][bj][m][1] + bv[m][bj][1];
;           *(f32x4*)(C + off + bj * HALF) = v0; *(f32x4*)(C + off + bj * HALF + 4) = v1;
;           if (xb) {
;             u32x4 w; w.x = pack2(v0[0], v0[1]); w.y = pack2(v0[2], v0[3]); w.z = pack2(v1[0], v1[1]); w.w = pack2(v1[2], v1[3]);
;             *(u32x4*)(xb + off + bj * HALF) = w;
;             ss += v0[0] * v0[0] + v0[1] * v0[1] + v0[2] * v0[2] + v0[3] * v0[3] + v1[0] * v1[0] + v1[1] * v1[1] + v1[2] * v1[2] + v1[3] * v1[3];
;           }
;         }
;         if (xb) {
;           ss += __shfl_xor(ss, 16); ss += __shfl_xor(ss, 32);
;           if (fq == 0) ssq[(size_t)row * 32 + u.pn * 4 + wc] = ss;
;         }
	v_lshl_add_u32 v194, s51, 8, v211
	v_lshl_or_b32 v192, s2, 8, v213
	v_readlane_b32 s52, v243, 3
	v_ashrrev_i32_e32 v193, 31, v192
	v_readlane_b32 s66, v243, 17
	v_readlane_b32 s67, v243, 18
	v_ashrrev_i32_e32 v195, 31, v194
	v_lshlrev_b64 v[128:129], 13, v[194:195]
	v_lshl_add_u64 v[196:197], v[192:193], 2, s[66:67]
	v_lshl_add_u64 v[236:237], v[196:197], 0, v[128:129]
	global_load_dwordx4 v[220:223], v[236:237], off
	global_load_dwordx4 v[224:227], v[236:237], off offset:16
	global_load_dwordx4 v[228:231], v[236:237], off offset:512
	global_load_dwordx4 v[232:235], v[236:237], off offset:528
	v_or_b32_e32 v206, 16, v194
	v_or_b32_e32 v202, 32, v194
	v_or_b32_e32 v198, 48, v194
	v_ashrrev_i32_e32 v207, 31, v206
	v_ashrrev_i32_e32 v203, 31, v202
	v_ashrrev_i32_e32 v199, 31, v198
	v_lshlrev_b64 v[128:129], 13, v[206:207]
	v_lshlrev_b64 v[130:131], 13, v[202:203]
	v_lshlrev_b64 v[132:133], 13, v[198:199]
	v_lshl_add_u64 v[208:209], v[196:197], 0, v[128:129]
	v_lshl_add_u64 v[204:205], v[196:197], 0, v[130:131]
	v_lshl_add_u64 v[200:201], v[196:197], 0, v[132:133]
	global_load_dwordx4 v[168:171], v[208:209], off offset:16
	global_load_dwordx4 v[172:175], v[208:209], off
	global_load_dwordx4 v[160:163], v[208:209], off offset:528
	global_load_dwordx4 v[164:167], v[208:209], off offset:512
	global_load_dwordx4 v[152:155], v[204:205], off offset:16
	global_load_dwordx4 v[156:159], v[204:205], off
	global_load_dwordx4 v[144:147], v[204:205], off offset:528
	global_load_dwordx4 v[148:151], v[204:205], off offset:512
	global_load_dwordx4 v[136:139], v[200:201], off offset:16
	global_load_dwordx4 v[140:143], v[200:201], off
	global_load_dwordx4 v[128:131], v[200:201], off offset:528
	global_load_dwordx4 v[132:135], v[200:201], off offset:512
	v_and_b32_e32 v218, 64, v217
	v_xor_b32_e32 v238, 16, v217
	v_add_u32_e32 v240, 64, v218
	v_xor_b32_e32 v239, 32, v217
	v_cmp_lt_i32_e32 vcc, v238, v240
	v_lshlrev_b64 v[218:219], 11, v[194:195]
	s_lshl_b32 s18, s2, 2
	v_cndmask_b32_e32 v241, v217, v238, vcc
	v_cmp_lt_i32_e32 vcc, v239, v240
	s_ashr_i32 s19, s18, 31
	v_readlane_b32 s53, v243, 4
	v_cndmask_b32_e32 v240, v217, v239, vcc
	v_lshl_add_u64 v[238:239], v[218:219], 0, v[192:193]
	v_lshlrev_b32_e32 v218, 2, v241
	v_lshl_add_u64 v[238:239], v[238:239], 1, s[12:13]
	v_readlane_b32 s54, v243, 5
	v_readlane_b32 s55, v243, 6
	v_readlane_b32 s56, v243, 7
	v_readlane_b32 s57, v243, 8
	v_readlane_b32 s58, v243, 9
	v_readlane_b32 s59, v243, 10
	v_readlane_b32 s60, v243, 11
	v_readlane_b32 s61, v243, 12
	v_readlane_b32 s62, v243, 13
	v_readlane_b32 s63, v243, 14
	v_readlane_b32 s64, v243, 15
	v_readlane_b32 s65, v243, 16
	s_waitcnt vmcnt(0)
	v_pk_add_f32 v[126:127], v[126:127], v[222:223]
	v_pk_add_f32 v[124:125], v[124:125], v[220:221]
	v_pk_add_f32 v[116:117], v[116:117], v[228:229]
	v_pk_add_f32 v[122:123], v[122:123], v[226:227]
	v_pk_add_f32 v[120:121], v[120:121], v[224:225]
	v_pk_add_f32 v[220:221], v[112:113], v[232:233]
	global_store_dwordx4 v[236:237], v[124:127], off
	global_store_dwordx4 v[236:237], v[120:123], off offset:16
	v_cvt_pk_bf16_f32 v112, v124, v125
	v_mul_f32_e32 v125, v125, v125
	v_mul_f32_e32 v219, v117, v117
	v_pk_add_f32 v[118:119], v[118:119], v[230:231]
	v_fmac_f32_e32 v125, v124, v124
	v_fmac_f32_e32 v219, v116, v116
	v_fmac_f32_e32 v125, v126, v126
	v_fmac_f32_e32 v219, v118, v118
	v_fmac_f32_e32 v125, v127, v127
	v_fmac_f32_e32 v219, v119, v119
	v_fmac_f32_e32 v125, v120, v120
	v_fmac_f32_e32 v219, v220, v220
	v_pk_add_f32 v[222:223], v[114:115], v[234:235]
	v_fmac_f32_e32 v125, v121, v121
	v_fmac_f32_e32 v219, v221, v221
	v_fmac_f32_e32 v125, v122, v122
	v_fmac_f32_e32 v219, v222, v222
	v_fmac_f32_e32 v125, v123, v123
	v_fmac_f32_e32 v219, v223, v223
	v_cvt_pk_bf16_f32 v114, v120, v121
	v_add_f32_e32 v121, v125, v219
	v_cvt_pk_bf16_f32 v115, v122, v123
	ds_bpermute_b32 v122, v218, v121
	v_cvt_pk_bf16_f32 v113, v126, v127
	global_store_dwordx4 v[238:239], v[112:115], off
	global_store_dwordx4 v[236:237], v[116:119], off offset:512
	global_store_dwordx4 v[236:237], v[220:223], off offset:528
	v_lshlrev_b32_e32 v126, 2, v240
	v_cvt_pk_bf16_f32 v120, v116, v117
	s_waitcnt lgkmcnt(0)
	v_add_f32_e32 v112, v121, v122
	ds_bpermute_b32 v113, v126, v112
	v_cvt_pk_bf16_f32 v121, v118, v119
	v_cvt_pk_bf16_f32 v122, v220, v221
	v_cvt_pk_bf16_f32 v123, v222, v223
	global_store_dwordx4 v[238:239], v[120:123], off offset:256
	s_and_saveexec_b64 s[20:21], s[0:1]
	s_cbranch_execz .LBB0_964
	s_waitcnt lgkmcnt(0)
	v_add_f32_e32 v114, v112, v113
	v_lshlrev_b64 v[112:113], 7, v[194:195]
	v_lshl_add_u64 v[112:113], s[14:15], 0, v[112:113]
	v_lshl_add_u64 v[112:113], s[18:19], 2, v[112:113]
	s_lshl_b32 s2, s36, 2
	v_lshl_add_u64 v[112:113], v[112:113], 0, s[2:3]
	global_store_dword v[112:113], v114, off

; #define PG8_STAGE(bufoff, gbase, voff) do { _Pragma("unroll") for (int _i = 0; _i < 2; ++_i) \
;     __builtin_amdgcn_global_load_lds((const unsigned*)((const char*)(gbase) + (voff)[_i]), (LAS unsigned*)(lds + (bufoff) + ldsw + _i * 8192), 16, 0, 0); } while (0)
; #define PG8_LDA(dst, b, h) do { _Pragma("unroll") for (int m = 0; m < 4; ++m) _Pragma("unroll") for (int k = 0; k < 2; ++k) dst[m][k] = *(const LAS bf16x8*)(lds + PG8_SA(b, h) + aoff + m * 2048 + k * 1024); } while (0)
; #define PG8_LDB(dst, b, h) do { _Pragma("unroll") for (int n = 0; n < 2; ++n) _Pragma("unroll") for (int k = 0; k < 2; ++k) dst[n][k] = *(const LAS bf16x8*)(lds + PG8_SB(b, h) + boff + n * 2048 + k * 1024); } while (0)
; #define PG8_MMA(ai, bj, At, Bt) do { __builtin_amdgcn_s_setprio(1); _Pragma("unroll") for (int m = 0; m < 4; ++m) _Pragma("unroll") for (int n = 0; n < 2; ++n) _Pragma("unroll") for (int k = 0; k < 2; ++k) \
;     acc[ai][bj][m][n] = __builtin_amdgcn_mfma_f32_16x16x32_bf16(Bt[n][k], At[m][k], acc[ai][bj][m][n], 0, 0, 0); __builtin_amdgcn_s_setprio(0); } while (0)
; #define PG8_WAIT_V(n) asm volatile("s_waitcnt vmcnt(" #n ")" ::: "memory")
; #define PG8_WAIT_L(n) asm volatile("s_waitcnt lgkmcnt(" #n ")" ::: "memory")
; #define PG8_BAR __builtin_amdgcn_s_barrier()
; #define PG8_SCHED __builtin_amdgcn_sched_barrier(0)
; template <class Epi, class Sched = StaticOrder>
; DI void gemm_phase(LAS unsigned char* lds, const Gemm g, const Sched& S, const Epi& E) {
;     ...
;       PG8_LDB(B0, 0, 0); PG8_SCHED; PG8_LDA(At, 0, 0); PG8_STAGE(PG8_SA(1, 1), a1 + hstep, voffA);
;       PG8_WAIT_L(8); PG8_BAR; PG8_WAIT_L(0); PG8_MMA(0, 0, At, B0); PG8_BAR; PG8_SCHED;
;       PG8_LDB(B1, 0, 1); PG8_STAGE(PG8_SB(0, 0), b2, voffB);
;       PG8_BAR; PG8_WAIT_L(0); PG8_MMA(0, 1, At, B1); PG8_BAR;
;       PG8_LDA(At, 0, 1); PG8_STAGE(PG8_SA(0, 0), a2, voffA);
;       PG8_BAR; PG8_WAIT_L(0); PG8_MMA(1, 0, At, B0); PG8_BAR; PG8_SCHED;
;       PG8_STAGE(PG8_SB(0, 1), b2 + hstep, voffB);
;       PG8_WAIT_V(6); PG8_BAR; PG8_MMA(1, 1, At, B1); PG8_BAR;
.LBB0_1052:
	ds_read_b128 v[128:131], v203
	ds_read_b128 v[132:135], v203 offset:1024
	ds_read_b128 v[136:139], v203 offset:2048
	ds_read_b128 v[140:143], v203 offset:3072
	s_add_u32 s12, s10, 0xfff80080
	s_addc_u32 s13, s11, -1
	s_cmp_eq_u32 s52, 28
	s_cselect_b32 s65, s41, s13
	s_cselect_b32 s64, s42, s12
	s_cselect_b32 s13, s43, s49
	s_cselect_b32 s12, s44, s45
	s_add_i32 m0, s61, 0xc000
	ds_read_b128 v[144:147], v204
	ds_read_b128 v[148:151], v204 offset:1024
	ds_read_b128 v[152:155], v204 offset:2048
	ds_read_b128 v[156:159], v204 offset:3072
	ds_read_b128 v[178:181], v204 offset:4096
	ds_read_b128 v[182:185], v204 offset:5120
	ds_read_b128 v[186:189], v204 offset:6144
	ds_read_b128 v[190:193], v204 offset:7168
	global_load_lds_dwordx4 v172, s[10:11]
	s_add_i32 m0, s61, 0xe000
	s_nop 0
	global_load_lds_dwordx4 v174, s[10:11]
	s_waitcnt lgkmcnt(0)
	s_setprio 1
	s_barrier
	v_mfma_f32_16x16x32_bf16 v[124:127], v[128:131], v[144:147], v[124:127]
	v_mfma_f32_16x16x32_bf16 v[120:123], v[136:139], v[144:147], v[120:123]
	v_mfma_f32_16x16x32_bf16 v[116:119], v[128:131], v[152:155], v[116:119]
	v_mfma_f32_16x16x32_bf16 v[104:107], v[136:139], v[152:155], v[104:107]
	v_mfma_f32_16x16x32_bf16 v[92:95], v[128:131], v[178:181], v[92:95]
	v_mfma_f32_16x16x32_bf16 v[88:91], v[136:139], v[178:181], v[88:91]
	v_mfma_f32_16x16x32_bf16 v[84:87], v[128:131], v[186:189], v[84:87]
	v_mfma_f32_16x16x32_bf16 v[72:75], v[136:139], v[186:189], v[72:75]
	v_mfma_f32_16x16x32_bf16 v[124:127], v[132:135], v[148:151], v[124:127]
	v_mfma_f32_16x16x32_bf16 v[120:123], v[140:143], v[148:151], v[120:123]
	v_mfma_f32_16x16x32_bf16 v[116:119], v[132:135], v[156:159], v[116:119]
	v_mfma_f32_16x16x32_bf16 v[104:107], v[140:143], v[156:159], v[104:107]
	v_mfma_f32_16x16x32_bf16 v[92:95], v[132:135], v[182:185], v[92:95]
	v_mfma_f32_16x16x32_bf16 v[88:91], v[140:143], v[182:185], v[88:91]
	v_mfma_f32_16x16x32_bf16 v[84:87], v[132:135], v[190:193], v[84:87]
	v_mfma_f32_16x16x32_bf16 v[72:75], v[140:143], v[190:193], v[72:75]
	s_barrier
	s_setprio 0
	s_add_i32 s53, s80, s70
	s_add_u32 s98, s12, 0x80
	s_addc_u32 s99, s13, 0
	s_add_u32 s100, s64, 0x80
	s_addc_u32 s101, s65, 0
	s_mov_b32 m0, s53
	ds_read_b128 v[194:197], v205
	ds_read_b128 v[212:215], v205 offset:1024
	ds_read_b128 v[216:219], v205 offset:2048
	ds_read_b128 v[220:223], v205 offset:3072
	global_load_lds_dwordx4 v162, s[12:13]
	s_add_i32 m0, s53, 0x2000
	s_nop 0
	global_load_lds_dwordx4 v166, s[12:13]
	s_waitcnt lgkmcnt(0)
	s_setprio 1
	s_barrier
	v_mfma_f32_16x16x32_bf16 v[112:115], v[194:197], v[144:147], v[112:115]
	v_mfma_f32_16x16x32_bf16 v[108:111], v[216:219], v[144:147], v[108:111]
	v_mfma_f32_16x16x32_bf16 v[100:103], v[194:197], v[152:155], v[100:103]
	v_mfma_f32_16x16x32_bf16 v[96:99], v[216:219], v[152:155], v[96:99]
	v_mfma_f32_16x16x32_bf16 v[80:83], v[194:197], v[178:181], v[80:83]
	v_mfma_f32_16x16x32_bf16 v[76:79], v[216:219], v[178:181], v[76:79]
	v_mfma_f32_16x16x32_bf16 v[68:71], v[194:197], v[186:189], v[68:71]
	v_mfma_f32_16x16x32_bf16 v[64:67], v[216:219], v[186:189], v[64:67]
	v_mfma_f32_16x16x32_bf16 v[112:115], v[212:215], v[148:151], v[112:115]
	v_mfma_f32_16x16x32_bf16 v[108:111], v[220:223], v[148:151], v[108:111]
	v_mfma_f32_16x16x32_bf16 v[100:103], v[212:215], v[156:159], v[100:103]
	v_mfma_f32_16x16x32_bf16 v[96:99], v[220:223], v[156:159], v[96:99]
	v_mfma_f32_16x16x32_bf16 v[80:83], v[212:215], v[182:185], v[80:83]
	v_mfma_f32_16x16x32_bf16 v[76:79], v[220:223], v[182:185], v[76:79]
	v_mfma_f32_16x16x32_bf16 v[68:71], v[212:215], v[190:193], v[68:71]
	v_mfma_f32_16x16x32_bf16 v[64:67], v[220:223], v[190:193], v[64:67]
	s_barrier
	s_setprio 0
	s_mov_b32 m0, s61
	ds_read_b128 v[144:147], v204 offset:16384
	ds_read_b128 v[148:151], v204 offset:17408
	ds_read_b128 v[152:155], v204 offset:18432
	ds_read_b128 v[156:159], v204 offset:19456
	ds_read_b128 v[178:181], v204 offset:20480
	ds_read_b128 v[182:185], v204 offset:21504
	ds_read_b128 v[186:189], v204 offset:22528
	ds_read_b128 v[190:193], v204 offset:23552
	global_load_lds_dwordx4 v160, s[64:65]
	s_mov_b32 m0, s63
	s_nop 0
	global_load_lds_dwordx4 v164, s[64:65]
	s_waitcnt lgkmcnt(0)
	s_setprio 1
	s_barrier
	v_mfma_f32_16x16x32_bf16 v[60:63], v[128:131], v[144:147], v[60:63]
	v_mfma_f32_16x16x32_bf16 v[56:59], v[136:139], v[144:147], v[56:59]
	v_mfma_f32_16x16x32_bf16 v[48:51], v[128:131], v[152:155], v[48:51]
	v_mfma_f32_16x16x32_bf16 v[40:43], v[136:139], v[152:155], v[40:43]
	v_mfma_f32_16x16x32_bf16 v[28:31], v[128:131], v[178:181], v[28:31]
	v_mfma_f32_16x16x32_bf16 v[24:27], v[136:139], v[178:181], v[24:27]
	v_mfma_f32_16x16x32_bf16 v[12:15], v[128:131], v[186:189], v[12:15]
	v_mfma_f32_16x16x32_bf16 v[8:11], v[136:139], v[186:189], v[8:11]
	v_mfma_f32_16x16x32_bf16 v[60:63], v[132:135], v[148:151], v[60:63]
	v_mfma_f32_16x16x32_bf16 v[56:59], v[140:143], v[148:151], v[56:59]
	v_mfma_f32_16x16x32_bf16 v[48:51], v[132:135], v[156:159], v[48:51]
	v_mfma_f32_16x16x32_bf16 v[40:43], v[140:143], v[156:159], v[40:43]
	v_mfma_f32_16x16x32_bf16 v[28:31], v[132:135], v[182:185], v[28:31]
	v_mfma_f32_16x16x32_bf16 v[24:27], v[140:143], v[182:185], v[24:27]
	v_mfma_f32_16x16x32_bf16 v[12:15], v[132:135], v[190:193], v[12:15]
	v_mfma_f32_16x16x32_bf16 v[8:11], v[140:143], v[190:193], v[8:11]
	s_barrier
	s_setprio 0
	s_add_u32 s54, s12, 0x80000
	s_addc_u32 s55, s13, 0
	s_add_i32 s53, s81, s70
	s_mov_b32 m0, s53
	s_nop 0
	global_load_lds_dwordx4 v162, s[54:55]
	s_add_i32 m0, s53, 0x2000
	s_nop 0
	global_load_lds_dwordx4 v166, s[54:55]
	s_waitcnt vmcnt(6)
	s_setprio 1
	s_barrier
; #define PG8_STAGE(bufoff, gbase, voff) do { _Pragma("unroll") for (int _i = 0; _i < 2; ++_i) \
;     __builtin_amdgcn_global_load_lds((const unsigned*)((const char*)(gbase) + (voff)[_i]), (LAS unsigned*)(lds + (bufoff) + ldsw + _i * 8192), 16, 0, 0); } while (0)
; #define PG8_LDA(dst, b, h) do { _Pragma("unroll") for (int m = 0; m < 4; ++m) _Pragma("unroll") for (int k = 0; k < 2; ++k) dst[m][k] = *(const LAS bf16x8*)(lds + PG8_SA(b, h) + aoff + m * 2048 + k * 1024); } while (0)
; #define PG8_LDB(dst, b, h) do { _Pragma("unroll") for (int n = 0; n < 2; ++n) _Pragma("unroll") for (int k = 0; k < 2; ++k) dst[n][k] = *(const LAS bf16x8*)(lds + PG8_SB(b, h) + boff + n * 2048 + k * 1024); } while (0)
; #define PG8_MMA(ai, bj, At, Bt) do { __builtin_amdgcn_s_setprio(1); _Pragma("unroll") for (int m = 0; m < 4; ++m) _Pragma("unroll") for (int n = 0; n < 2; ++n) _Pragma("unroll") for (int k = 0; k < 2; ++k) \
;     acc[ai][bj][m][n] = __builtin_amdgcn_mfma_f32_16x16x32_bf16(Bt[n][k], At[m][k], acc[ai][bj][m][n], 0, 0, 0); __builtin_amdgcn_s_setprio(0); } while (0)
; #define PG8_WAIT_V(n) asm volatile("s_waitcnt vmcnt(" #n ")" ::: "memory")
; #define PG8_WAIT_L(n) asm volatile("s_waitcnt lgkmcnt(" #n ")" ::: "memory")
; #define PG8_BAR __builtin_amdgcn_s_barrier()
; #define PG8_SCHED __builtin_amdgcn_sched_barrier(0)
; template <class Epi, class Sched = StaticOrder>
; DI void gemm_phase(LAS unsigned char* lds, const Gemm g, const Sched& S, const Epi& E) {
;     ...
;       PG8_WAIT_V(6); PG8_BAR; PG8_MMA(1, 1, At, B1); PG8_BAR;
;       PG8_LDB(B0, 1, 0); PG8_SCHED; PG8_LDA(At, 1, 0); PG8_STAGE(PG8_SA(0, 1), a2 + hstep, voffA);
;       PG8_WAIT_L(8); PG8_BAR; PG8_WAIT_L(0); PG8_MMA(0, 0, At, B0); PG8_BAR; PG8_SCHED;
;       PG8_LDB(B1, 1, 1); PG8_STAGE(PG8_SB(1, 0), b3, voffB);
;       PG8_BAR; PG8_WAIT_L(0); PG8_MMA(0, 1, At, B1); PG8_BAR;
;       PG8_LDA(At, 1, 1); PG8_STAGE(PG8_SA(1, 0), a3, voffA);
;       PG8_BAR; PG8_WAIT_L(0); PG8_MMA(1, 0, At, B0); PG8_BAR; PG8_SCHED;
	v_mfma_f32_16x16x32_bf16 v[52:55], v[194:197], v[144:147], v[52:55]
	v_mfma_f32_16x16x32_bf16 v[44:47], v[216:219], v[144:147], v[44:47]
	v_mfma_f32_16x16x32_bf16 v[36:39], v[194:197], v[152:155], v[36:39]
	v_mfma_f32_16x16x32_bf16 v[32:35], v[216:219], v[152:155], v[32:35]
	v_mfma_f32_16x16x32_bf16 v[20:23], v[194:197], v[178:181], v[20:23]
	v_mfma_f32_16x16x32_bf16 v[16:19], v[216:219], v[178:181], v[16:19]
	v_mfma_f32_16x16x32_bf16 v[4:7], v[194:197], v[186:189], v[4:7]
	v_mfma_f32_16x16x32_bf16 v[0:3], v[216:219], v[186:189], v[0:3]
	v_mfma_f32_16x16x32_bf16 v[52:55], v[212:215], v[148:151], v[52:55]
	v_mfma_f32_16x16x32_bf16 v[44:47], v[220:223], v[148:151], v[44:47]
	v_mfma_f32_16x16x32_bf16 v[36:39], v[212:215], v[156:159], v[36:39]
	v_mfma_f32_16x16x32_bf16 v[32:35], v[220:223], v[156:159], v[32:35]
	v_mfma_f32_16x16x32_bf16 v[20:23], v[212:215], v[182:185], v[20:23]
	v_mfma_f32_16x16x32_bf16 v[16:19], v[220:223], v[182:185], v[16:19]
	v_mfma_f32_16x16x32_bf16 v[4:7], v[212:215], v[190:193], v[4:7]
	v_mfma_f32_16x16x32_bf16 v[0:3], v[220:223], v[190:193], v[0:3]
	s_barrier
	s_setprio 0
	s_add_i32 s53, 0, 0x18000
	v_add_u32_e32 v140, s53, v199
	ds_read_b128 v[128:131], v140
	ds_read_b128 v[132:135], v140 offset:1024
	ds_read_b128 v[136:139], v140 offset:2048
	ds_read_b128 v[140:143], v140 offset:3072
	s_add_u32 s54, s64, 0x80000
	s_addc_u32 s55, s65, 0
	s_mov_b32 m0, s71
	ds_read_b128 v[144:147], v204 offset:32768
	ds_read_b128 v[148:151], v204 offset:33792
	ds_read_b128 v[152:155], v204 offset:34816
	ds_read_b128 v[156:159], v204 offset:35840
	ds_read_b128 v[178:181], v204 offset:36864
	ds_read_b128 v[182:185], v204 offset:37888
	ds_read_b128 v[186:189], v204 offset:38912
	ds_read_b128 v[190:193], v204 offset:39936
	global_load_lds_dwordx4 v160, s[54:55]
	s_mov_b32 m0, s72
	s_nop 0
	global_load_lds_dwordx4 v164, s[54:55]
	s_waitcnt lgkmcnt(0)
	s_setprio 1
	s_barrier
	v_mfma_f32_16x16x32_bf16 v[124:127], v[128:131], v[144:147], v[124:127]
	v_mfma_f32_16x16x32_bf16 v[120:123], v[136:139], v[144:147], v[120:123]
	v_mfma_f32_16x16x32_bf16 v[116:119], v[128:131], v[152:155], v[116:119]
	v_mfma_f32_16x16x32_bf16 v[104:107], v[136:139], v[152:155], v[104:107]
	v_mfma_f32_16x16x32_bf16 v[92:95], v[128:131], v[178:181], v[92:95]
	v_mfma_f32_16x16x32_bf16 v[88:91], v[136:139], v[178:181], v[88:91]
	v_mfma_f32_16x16x32_bf16 v[84:87], v[128:131], v[186:189], v[84:87]
	v_mfma_f32_16x16x32_bf16 v[72:75], v[136:139], v[186:189], v[72:75]
	v_mfma_f32_16x16x32_bf16 v[124:127], v[132:135], v[148:151], v[124:127]
	v_mfma_f32_16x16x32_bf16 v[120:123], v[140:143], v[148:151], v[120:123]
	v_mfma_f32_16x16x32_bf16 v[116:119], v[132:135], v[156:159], v[116:119]
	v_mfma_f32_16x16x32_bf16 v[104:107], v[140:143], v[156:159], v[104:107]
	v_mfma_f32_16x16x32_bf16 v[92:95], v[132:135], v[182:185], v[92:95]
	v_mfma_f32_16x16x32_bf16 v[88:91], v[140:143], v[182:185], v[88:91]
	v_mfma_f32_16x16x32_bf16 v[84:87], v[132:135], v[190:193], v[84:87]
	v_mfma_f32_16x16x32_bf16 v[72:75], v[140:143], v[190:193], v[72:75]
	s_barrier
	s_setprio 0
	s_add_i32 s54, 0, 0x1c000
	s_add_i32 s53, s53, s70
	v_add_u32_e32 v168, s54, v199
	s_mov_b32 m0, s53
	ds_read_b128 v[194:197], v168
	ds_read_b128 v[212:215], v168 offset:1024
	ds_read_b128 v[216:219], v168 offset:2048
	ds_read_b128 v[220:223], v168 offset:3072
	global_load_lds_dwordx4 v162, s[98:99]
	s_add_i32 m0, s53, 0x2000
	s_nop 0
	global_load_lds_dwordx4 v166, s[98:99]
	s_waitcnt lgkmcnt(0)
	s_setprio 1
	s_barrier
	v_mfma_f32_16x16x32_bf16 v[112:115], v[194:197], v[144:147], v[112:115]
	v_mfma_f32_16x16x32_bf16 v[108:111], v[216:219], v[144:147], v[108:111]
	v_mfma_f32_16x16x32_bf16 v[100:103], v[194:197], v[152:155], v[100:103]
	v_mfma_f32_16x16x32_bf16 v[96:99], v[216:219], v[152:155], v[96:99]
	v_mfma_f32_16x16x32_bf16 v[80:83], v[194:197], v[178:181], v[80:83]
	v_mfma_f32_16x16x32_bf16 v[76:79], v[216:219], v[178:181], v[76:79]
	v_mfma_f32_16x16x32_bf16 v[68:71], v[194:197], v[186:189], v[68:71]
	v_mfma_f32_16x16x32_bf16 v[64:67], v[216:219], v[186:189], v[64:67]
	v_mfma_f32_16x16x32_bf16 v[112:115], v[212:215], v[148:151], v[112:115]
	v_mfma_f32_16x16x32_bf16 v[108:111], v[220:223], v[148:151], v[108:111]
	v_mfma_f32_16x16x32_bf16 v[100:103], v[212:215], v[156:159], v[100:103]
	v_mfma_f32_16x16x32_bf16 v[96:99], v[220:223], v[156:159], v[96:99]
	v_mfma_f32_16x16x32_bf16 v[80:83], v[212:215], v[182:185], v[80:83]
	v_mfma_f32_16x16x32_bf16 v[76:79], v[220:223], v[182:185], v[76:79]
	v_mfma_f32_16x16x32_bf16 v[68:71], v[212:215], v[190:193], v[68:71]
	v_mfma_f32_16x16x32_bf16 v[64:67], v[220:223], v[190:193], v[64:67]
	s_barrier
	s_setprio 0
	s_mov_b32 m0, s76
	ds_read_b128 v[144:147], v204 offset:49152
	ds_read_b128 v[148:151], v204 offset:50176
	ds_read_b128 v[152:155], v204 offset:51200
	ds_read_b128 v[156:159], v204 offset:52224
	ds_read_b128 v[178:181], v204 offset:53248
	ds_read_b128 v[182:185], v204 offset:54272
	ds_read_b128 v[186:189], v204 offset:55296
	ds_read_b128 v[190:193], v204 offset:56320
	global_load_lds_dwordx4 v160, s[100:101]
	s_mov_b32 m0, s77
	s_nop 0
	global_load_lds_dwordx4 v164, s[100:101]
	s_waitcnt lgkmcnt(0)
	s_setprio 1
	s_barrier
; #define PG8_STAGE(bufoff, gbase, voff) do { _Pragma("unroll") for (int _i = 0; _i < 2; ++_i) \
;     __builtin_amdgcn_global_load_lds((const unsigned*)((const char*)(gbase) + (voff)[_i]), (LAS unsigned*)(lds + (bufoff) + ldsw + _i * 8192), 16, 0, 0); } while (0)
; #define PG8_MMA(ai, bj, At, Bt) do { __builtin_amdgcn_s_setprio(1); _Pragma("unroll") for (int m = 0; m < 4; ++m) _Pragma("unroll") for (int n = 0; n < 2; ++n) _Pragma("unroll") for (int k = 0; k < 2; ++k) \
;     acc[ai][bj][m][n] = __builtin_amdgcn_mfma_f32_16x16x32_bf16(Bt[n][k], At[m][k], acc[ai][bj][m][n], 0, 0, 0); __builtin_amdgcn_s_setprio(0); } while (0)
; #define PG8_WAIT_V(n) asm volatile("s_waitcnt vmcnt(" #n ")" ::: "memory")
; #define PG8_WAIT_L(n) asm volatile("s_waitcnt lgkmcnt(" #n ")" ::: "memory")
; #define PG8_BAR __builtin_amdgcn_s_barrier()
; #define PG8_SCHED __builtin_amdgcn_sched_barrier(0)
;   DI void operator()(const f32x4 (&acc)[2][2][4][2], const Unit& u, int wr, int wc, int fr, int fq) const {
;     ...
;     const int col = u.pn * 128 + wc * 32 + 8 * fq;
;     float w0[8], w1[8], w2[8];
; #pragma unroll
;     for (int e = 0; e < 8; ++e) { w0[e] = cw[col + e]; w1[e] = cw[2048 + col + e]; w2[e] = cw[4096 + col + e]; }
; #pragma unroll
;     for (int ai = 0; ai < 2; ++ai) {
;       const int row0 = u.pm * BM + ai * HALF + wr * 64, span = row0 >> 6;
;       float rsv[4];
; #pragma unroll
;       for (int m = 0; m < 4; ++m) rsv[m] = row_rstd(ssq, row0 + 16 * m + fr, fq);
; template <class Epi, class Sched = StaticOrder>
; DI void gemm_phase(LAS unsigned char* lds, const Gemm g, const Sched& S, const Epi& E) {
;     ...
;       PG8_BAR; PG8_WAIT_L(0); PG8_MMA(1, 0, At, B0); PG8_BAR; PG8_SCHED;
;       PG8_STAGE(PG8_SB(1, 1), b3 + hstep, voffB);
;       PG8_WAIT_V(6); PG8_BAR; PG8_MMA(1, 1, At, B1); PG8_BAR;
	v_mfma_f32_16x16x32_bf16 v[60:63], v[128:131], v[144:147], v[60:63]
	v_mfma_f32_16x16x32_bf16 v[56:59], v[136:139], v[144:147], v[56:59]
	v_mfma_f32_16x16x32_bf16 v[48:51], v[128:131], v[152:155], v[48:51]
	v_mfma_f32_16x16x32_bf16 v[40:43], v[136:139], v[152:155], v[40:43]
	v_mfma_f32_16x16x32_bf16 v[28:31], v[128:131], v[178:181], v[28:31]
	v_mfma_f32_16x16x32_bf16 v[24:27], v[136:139], v[178:181], v[24:27]
	v_mfma_f32_16x16x32_bf16 v[12:15], v[128:131], v[186:189], v[12:15]
	v_mfma_f32_16x16x32_bf16 v[8:11], v[136:139], v[186:189], v[8:11]
	v_mfma_f32_16x16x32_bf16 v[60:63], v[132:135], v[148:151], v[60:63]
	v_mfma_f32_16x16x32_bf16 v[56:59], v[140:143], v[148:151], v[56:59]
	v_mfma_f32_16x16x32_bf16 v[48:51], v[132:135], v[156:159], v[48:51]
	v_mfma_f32_16x16x32_bf16 v[40:43], v[140:143], v[156:159], v[40:43]
	v_mfma_f32_16x16x32_bf16 v[28:31], v[132:135], v[182:185], v[28:31]
	v_mfma_f32_16x16x32_bf16 v[24:27], v[140:143], v[182:185], v[24:27]
	v_mfma_f32_16x16x32_bf16 v[12:15], v[132:135], v[190:193], v[12:15]
	v_mfma_f32_16x16x32_bf16 v[8:11], v[140:143], v[190:193], v[8:11]
	s_barrier
	s_setprio 0
	s_add_u32 s12, s12, 0x80080
	s_addc_u32 s13, s13, 0
	s_add_i32 s53, s54, s70
	s_mov_b32 m0, s53
	s_nop 0
	global_load_lds_dwordx4 v162, s[12:13]
	s_add_i32 m0, s53, 0x2000
	s_nop 0
	global_load_lds_dwordx4 v166, s[12:13]
	s_waitcnt vmcnt(6)
	s_add_i32 s52, s52, 2
	s_add_u32 s10, s10, 0x100
	s_addc_u32 s11, s11, 0
	s_add_u32 s45, s45, 0x100
	s_addc_u32 s49, s49, 0
	s_cmp_gt_u32 s52, 29
	s_setprio 1
	s_barrier
	v_mfma_f32_16x16x32_bf16 v[52:55], v[194:197], v[144:147], v[52:55]
	v_mfma_f32_16x16x32_bf16 v[44:47], v[216:219], v[144:147], v[44:47]
	v_mfma_f32_16x16x32_bf16 v[36:39], v[194:197], v[152:155], v[36:39]
	v_mfma_f32_16x16x32_bf16 v[32:35], v[216:219], v[152:155], v[32:35]
	v_mfma_f32_16x16x32_bf16 v[20:23], v[194:197], v[178:181], v[20:23]
	v_mfma_f32_16x16x32_bf16 v[16:19], v[216:219], v[178:181], v[16:19]
	v_mfma_f32_16x16x32_bf16 v[4:7], v[194:197], v[186:189], v[4:7]
	v_mfma_f32_16x16x32_bf16 v[0:3], v[216:219], v[186:189], v[0:3]
	v_mfma_f32_16x16x32_bf16 v[52:55], v[212:215], v[148:151], v[52:55]
	v_mfma_f32_16x16x32_bf16 v[44:47], v[220:223], v[148:151], v[44:47]
	v_mfma_f32_16x16x32_bf16 v[36:39], v[212:215], v[156:159], v[36:39]
	v_mfma_f32_16x16x32_bf16 v[32:35], v[220:223], v[156:159], v[32:35]
	v_mfma_f32_16x16x32_bf16 v[20:23], v[212:215], v[182:185], v[20:23]
	v_mfma_f32_16x16x32_bf16 v[16:19], v[220:223], v[182:185], v[16:19]
	v_mfma_f32_16x16x32_bf16 v[4:7], v[212:215], v[190:193], v[4:7]
	v_mfma_f32_16x16x32_bf16 v[0:3], v[220:223], v[190:193], v[0:3]
	s_barrier
	s_setprio 0
	s_cbranch_scc0 .LBB0_1052
	s_cmp_lt_i32 s62, 16
	s_mov_b64 s[10:11], -1
	s_cbranch_scc0 .LBB0_1067
	s_lshl_b32 s41, s60, 8
	s_add_i32 s41, s41, s75
	v_or_b32_e32 v186, s41, v177
	v_ashrrev_i32_e32 v187, 31, v186
	v_lshlrev_b64 v[128:129], 7, v[186:187]
	v_or_b32_e32 v180, 16, v186
	v_lshl_add_u64 v[128:129], v[170:171], 0, v[128:129]
	v_ashrrev_i32_e32 v181, 31, v180
	global_load_dwordx4 v[152:155], v[128:129], off
	global_load_dwordx4 v[156:159], v[128:129], off offset:16
	v_lshlrev_b64 v[128:129], 7, v[180:181]
	v_lshl_add_u64 v[128:129], v[170:171], 0, v[128:129]
	global_load_dwordx4 v[188:191], v[128:129], off
	global_load_dwordx4 v[192:195], v[128:129], off offset:16
	v_or_b32_e32 v184, 32, v186
	v_ashrrev_i32_e32 v185, 31, v184
	v_lshlrev_b64 v[128:129], 7, v[184:185]
	v_or_b32_e32 v182, 48, v186
	v_lshl_add_u64 v[128:129], v[170:171], 0, v[128:129]
	v_ashrrev_i32_e32 v183, 31, v182
	global_load_dwordx4 v[212:215], v[128:129], off
	global_load_dwordx4 v[216:219], v[128:129], off offset:16
	v_lshlrev_b64 v[128:129], 7, v[182:183]
	v_lshl_add_u64 v[128:129], v[170:171], 0, v[128:129]
	global_load_dwordx4 v[220:223], v[128:129], off
	global_load_dwordx4 v[224:227], v[128:129], off offset:16
	v_and_b32_e32 v129, 64, v206
	v_lshl_or_b32 v178, s62, 7, v200
	v_xor_b32_e32 v128, 16, v206
	v_add_u32_e32 v129, 64, v129
	v_readlane_b32 s44, v243, 3
	v_xor_b32_e32 v130, 32, v206
	v_ashrrev_i32_e32 v179, 31, v178
	v_readlane_b32 s45, v243, 4
	v_cmp_lt_i32_e32 vcc, v128, v129
	s_movk_i32 s10, 0x2000
	v_lshl_add_u64 v[144:145], v[178:179], 2, s[44:45]
	v_cndmask_b32_e32 v134, v206, v128, vcc
	v_cmp_lt_i32_e32 vcc, v130, v129
	v_lshl_add_u64 v[132:133], v[144:145], 0, s[26:27]
	v_lshl_add_u64 v[136:137], v[144:145], 0, s[28:29]
	v_cndmask_b32_e32 v135, v206, v130, vcc
	v_add_co_u32_e32 v146, vcc, s10, v144
	global_load_dwordx4 v[128:131], v[144:145], off offset:16
	global_load_dwordx4 v[140:143], v[144:145], off
	v_addc_co_u32_e32 v147, vcc, 0, v145, vcc
	v_add_co_u32_e32 v148, vcc, s74, v144
	v_lshlrev_b32_e32 v196, 2, v134
	s_nop 0
	v_addc_co_u32_e32 v149, vcc, 0, v145, vcc
	v_lshlrev_b32_e32 v207, 2, v135
	global_load_dwordx4 v[132:135], v[132:133], off offset:16
	s_nop 0
	global_load_dwordx4 v[136:139], v[136:137], off offset:16
	s_nop 0
	global_load_dwordx4 v[144:147], v[146:147], off
	s_nop 0
	global_load_dwordx4 v[148:151], v[148:149], off
	v_mov_b32_e32 v197, 0
	v_mov_b32_e32 v211, 0
	v_readlane_b32 s46, v243, 5
	v_readlane_b32 s47, v243, 6
	v_readlane_b32 s48, v243, 7
	v_readlane_b32 s49, v243, 8
	v_readlane_b32 s50, v243, 9
	v_readlane_b32 s51, v243, 10
	v_readlane_b32 s52, v243, 11
	v_readlane_b32 s53, v243, 12
	v_readlane_b32 s54, v243, 13
	v_readlane_b32 s55, v243, 14
	v_readlane_b32 s56, v243, 15
	v_readlane_b32 s57, v243, 16
	v_readlane_b32 s58, v243, 17
	v_readlane_b32 s59, v243, 18
	s_waitcnt vmcnt(0)
; DI unsigned pack2(float lo, float hi) { f32x2 v = {lo, hi}; bf16v2 r = __builtin_convertvector(v, bf16v2); return __builtin_bit_cast(unsigned, r); }
; DI float dpp_ror1(float v) { return __int_as_float(__builtin_amdgcn_update_dpp(0, __float_as_int(v), 0x121, 0xf, 0xf, false)); }
; DI float dpp_ror2(float v) { return __int_as_float(__builtin_amdgcn_update_dpp(0, __float_as_int(v), 0x122, 0xf, 0xf, false)); }
;   DI void operator()(const f32x4 (&acc)[2][2][4][2], const Unit& u, int wr, int wc, int fr, int fq) const {
;     ...
;       for (int m = 0; m < 4; ++m) rsv[m] = row_rstd(ssq, row0 + 16 * m + fr, fq);
;       float p1[8], p2[8];
; #pragma unroll
;       for (int e = 0; e < 8; ++e) { p1[e] = 0.f; p2[e] = 0.f; }
; #pragma unroll
;       for (int m = 0; m < 4; ++m) {
;         float g[8], a[8];
;         const float rs1 = rsv[m], rs2 = rs1 * rs1;
; #pragma unroll
;         for (int e = 0; e < 4; ++e) { g[e] = acc[ai][0][m][0][e] * acc[ai][1][m][0][e] * rs2; g[4 + e] = acc[ai][0][m][1][e] * acc[ai][1][m][1][e] * rs2; }
; #pragma unroll
;         for (int e = 0; e < 8; ++e) {
;           const float x1 = dpp_ror1(g[e]), x2 = dpp_ror2(g[e]);
;           const float pr1 = (fr == 0) ? p1[e] : x1, pr2 = (fr < 2) ? p2[e] : x2;
;           a[e] = w2[e] * g[e] + w1[e] * pr1 + w0[e] * pr2;
;           p1[e] = x1; p2[e] = x2;
;         }
;         if (m == 0 && fr < 2) {
;           float* hc = headC + (size_t)(span * 2 + fr) * 2048 + col;
;           *(f32x4*)hc = (f32x4){a[0], a[1], a[2], a[3]}; *(f32x4*)(hc + 4) = (f32x4){a[4], a[5], a[6], a[7]};
;         } else {
;           u32x4 w; w.x = pack2(a[0] * rs1, a[1] * rs1); w.y = pack2(a[2] * rs1, a[3] * rs1); w.z = pack2(a[4] * rs1, a[5] * rs1); w.w = pack2(a[6] * rs1, a[7] * rs1);
;           *(u32x4*)(C + (size_t)(row0 + 16 * m + fr) * 2048 + col) = w;
;         }
	v_mov_b32_e32 v208, v152
	v_mov_b32_e32 v209, v156
	v_mov_b32_e32 v156, v153
	v_mov_b32_e32 v152, v154
	v_mov_b32_e32 v153, v158
	v_mov_b32_e32 v158, v155
	v_pk_add_f32 v[154:155], v[208:209], v[156:157]
	v_pk_add_f32 v[152:153], v[152:153], v[158:159]
	v_mov_b32_e32 v156, v188
	v_mov_b32_e32 v157, v192
	v_mov_b32_e32 v192, v189
	v_mov_b32_e32 v158, v190
	v_mov_b32_e32 v159, v194
	v_mov_b32_e32 v194, v191
	v_pk_add_f32 v[152:153], v[154:155], v[152:153]
	v_pk_add_f32 v[154:155], v[156:157], v[192:193]
	v_pk_add_f32 v[156:157], v[158:159], v[194:195]
	v_mov_b32_e32 v188, v212
	v_pk_add_f32 v[154:155], v[154:155], v[156:157]
	v_mov_b32_e32 v157, v152
	v_mov_b32_e32 v156, v154
	v_mov_b32_e32 v152, v155
	v_pk_add_f32 v[152:153], v[156:157], v[152:153]
	ds_bpermute_b32 v155, v196, v153
	ds_bpermute_b32 v154, v196, v152
	v_mov_b32_e32 v189, v216
	v_mov_b32_e32 v216, v213
	v_mov_b32_e32 v190, v214
	v_mov_b32_e32 v191, v218
	s_waitcnt lgkmcnt(0)
	v_pk_add_f32 v[152:153], v[152:153], v[154:155]
	ds_bpermute_b32 v155, v207, v153
	ds_bpermute_b32 v154, v207, v152
	v_mov_b32_e32 v218, v215
	v_mov_b32_e32 v208, v220
	v_mov_b32_e32 v209, v224
	v_mov_b32_e32 v224, v221
	v_mov_b32_e32 v212, v222
	v_mov_b32_e32 v213, v226
	v_mov_b32_e32 v226, v223
	v_pk_add_f32 v[156:157], v[188:189], v[216:217]
	v_pk_add_f32 v[158:159], v[190:191], v[218:219]
	v_pk_add_f32 v[188:189], v[208:209], v[224:225]
	v_pk_add_f32 v[190:191], v[212:213], v[226:227]
	s_waitcnt lgkmcnt(0)
	v_pk_add_f32 v[152:153], v[152:153], v[154:155]
	v_pk_add_f32 v[156:157], v[156:157], v[158:159]
	v_pk_add_f32 v[158:159], v[188:189], v[190:191]
	v_pk_fma_f32 v[188:189], v[152:153], s[30:31], v[176:177] op_sel_hi:[1,0,0]
	v_mov_b32_e32 v153, v156
	v_mul_f32_e32 v152, 0x4b800000, v189
	v_cmp_gt_f32_e64 s[10:11], s84, v189
	v_mov_b32_e32 v156, v159
	v_mov_b32_e32 v194, v123
	v_cndmask_b32_e64 v152, v189, v152, s[10:11]
	v_rsq_f32_e32 v168, v152
	v_mov_b32_e32 v152, v158
	v_pk_add_f32 v[152:153], v[152:153], v[156:157]
	ds_bpermute_b32 v155, v196, v153
	ds_bpermute_b32 v154, v196, v152
	v_mul_f32_e32 v156, 0x45800000, v168
	v_cndmask_b32_e64 v195, v168, v156, s[10:11]
	v_mov_b32_e32 v217, 0
	v_mul_f32_e32 v156, v125, v113
	s_waitcnt lgkmcnt(0)
	v_pk_add_f32 v[190:191], v[152:153], v[154:155]
	v_mov_b32_e32 v152, v111
	v_mov_b32_e32 v153, v195
	v_mul_f32_e32 v154, v124, v112
	v_pk_mul_f32 v[152:153], v[194:195], v[152:153]
	v_mul_f32_e32 v155, v120, v108
	v_mul_f32_e32 v154, v154, v153
	v_pk_mul_f32 v[222:223], v[152:153], v[152:153] op_sel:[0,1] op_sel_hi:[1,0]
	v_mov_b32_e32 v213, 0
	v_mov_b32_dpp v217, v154 row_ror:1 row_mask:0xf bank_mask:0xf
	v_cndmask_b32_e64 v152, v217, 0, s[0:1]
	v_mul_f32_e32 v157, v121, v109
	v_mul_f32_e32 v158, v126, v114
	v_mul_f32_e32 v159, v122, v110
	v_mul_f32_e32 v168, v127, v115
	v_mul_f32_e32 v194, v155, v153
	v_mul_f32_e32 v155, v156, v153
	v_mov_b32_dpp v213, v154 row_ror:2 row_mask:0xf bank_mask:0xf
	v_mov_b32_e32 v221, 0
	v_mul_f32_e32 v152, v144, v152
	v_mul_f32_e32 v208, v157, v153
	v_mul_f32_e32 v156, v158, v153
	v_mul_f32_e32 v159, v159, v153
	v_mul_f32_e32 v157, v168, v153
	v_mov_b32_dpp v221, v155 row_ror:1 row_mask:0xf bank_mask:0xf
	v_cndmask_b32_e64 v153, v213, 0, s[8:9]
	v_fmac_f32_e32 v152, v148, v154
	v_mov_b32_e32 v219, 0
	v_fmac_f32_e32 v152, v140, v153
	v_cndmask_b32_e64 v153, v221, 0, s[0:1]
	v_mov_b32_dpp v219, v155 row_ror:2 row_mask:0xf bank_mask:0xf
	v_mul_f32_e32 v153, v145, v153
	v_mov_b32_e32 v216, 0
	v_cndmask_b32_e64 v154, v219, 0, s[8:9]
	v_fmac_f32_e32 v153, v149, v155
	v_mov_b32_dpp v216, v156 row_ror:1 row_mask:0xf bank_mask:0xf
	v_fmac_f32_e32 v153, v141, v154
	v_mov_b32_e32 v212, 0
	v_cndmask_b32_e64 v154, v216, 0, s[0:1]
	v_mov_b32_e32 v220, 0
	v_mov_b32_dpp v212, v156 row_ror:2 row_mask:0xf bank_mask:0xf
	v_mul_f32_e32 v154, v146, v154
	v_mov_b32_dpp v220, v157 row_ror:1 row_mask:0xf bank_mask:0xf
	v_cndmask_b32_e64 v155, v212, 0, s[8:9]
	v_fmac_f32_e32 v154, v150, v156
	v_mov_b32_e32 v218, 0
	v_fmac_f32_e32 v154, v142, v155
	v_cndmask_b32_e64 v155, v220, 0, s[0:1]
	v_mov_b32_dpp v218, v157 row_ror:2 row_mask:0xf bank_mask:0xf
	v_mul_f32_e32 v155, v147, v155
	v_cndmask_b32_e64 v156, v218, 0, s[8:9]
	v_fmac_f32_e32 v155, v151, v157
	v_mov_b32_dpp v197, v194 row_ror:1 row_mask:0xf bank_mask:0xf
	v_fmac_f32_e32 v155, v143, v156
	v_mov_b32_e32 v189, 0
	v_cndmask_b32_e64 v156, v197, 0, s[0:1]
	v_mov_b32_e32 v214, 0
	v_mov_b32_dpp v189, v194 row_ror:2 row_mask:0xf bank_mask:0xf
	v_mul_f32_e32 v156, v132, v156
	v_mov_b32_dpp v214, v208 row_ror:1 row_mask:0xf bank_mask:0xf
	v_cndmask_b32_e64 v157, v189, 0, s[8:9]
	v_fmac_f32_e32 v156, v136, v194
	v_fmac_f32_e32 v156, v128, v157
	v_cndmask_b32_e64 v157, v214, 0, s[0:1]
	v_mov_b32_e32 v209, 0
	v_mul_f32_e32 v157, v133, v157
	v_fmac_f32_e32 v157, v137, v208
	v_mov_b32_dpp v209, v208 row_ror:2 row_mask:0xf bank_mask:0xf
	v_mov_b32_e32 v208, 0
	v_cndmask_b32_e64 v158, v209, 0, s[8:9]
	v_fmac_f32_e32 v157, v129, v158
	v_mov_b32_dpp v208, v159 row_ror:1 row_mask:0xf bank_mask:0xf
	v_mov_b32_e32 v194, 0
	v_cndmask_b32_e64 v158, v208, 0, s[0:1]
	ds_bpermute_b32 v193, v207, v191
	ds_bpermute_b32 v192, v207, v190
	v_mov_b32_dpp v194, v159 row_ror:2 row_mask:0xf bank_mask:0xf
	v_mov_b32_e32 v215, 0
	v_mul_f32_e32 v158, v134, v158
	v_cndmask_b32_e64 v168, v194, 0, s[8:9]
	v_mov_b32_dpp v215, v222 row_ror:1 row_mask:0xf bank_mask:0xf
	v_fmac_f32_e32 v158, v138, v159
	v_mov_b32_dpp v211, v222 row_ror:2 row_mask:0xf bank_mask:0xf
	v_fmac_f32_e32 v158, v130, v168
	v_cndmask_b32_e64 v168, v215, 0, s[0:1]
	v_mul_f32_e32 v159, v139, v222
	v_cndmask_b32_e64 v223, v211, 0, s[8:9]
	v_fmac_f32_e32 v159, v135, v168
	v_cmp_gt_f32_e32 vcc, s84, v188
	v_fmac_f32_e32 v159, v131, v223
	s_and_saveexec_b64 s[10:11], s[4:5]
	s_xor_b64 s[10:11], exec, s[10:11]
	s_cbranch_execz .LBB0_1056
	v_mul_f32_e32 v152, v195, v152
	v_mul_f32_e32 v153, v195, v153
	v_cvt_pk_bf16_f32 v152, v152, v153
	v_mul_f32_e32 v153, v195, v154
	v_mul_f32_e32 v154, v195, v155
	v_cvt_pk_bf16_f32 v153, v153, v154
	v_mul_f32_e32 v154, v195, v156
	v_mul_f32_e32 v155, v195, v157
	v_cvt_pk_bf16_f32 v154, v154, v155
	v_mul_f32_e32 v155, v195, v158
	v_mul_f32_e32 v156, v195, v159
	v_cvt_pk_bf16_f32 v155, v155, v156
	v_lshlrev_b64 v[156:157], 12, v[186:187]
	v_lshl_add_u64 v[156:157], s[18:19], 0, v[156:157]
	v_lshl_add_u64 v[156:157], v[178:179], 1, v[156:157]
	global_store_dwordx4 v[156:157], v[152:155], off

; #define PG8_STAGE(bufoff, gbase, voff) do { _Pragma("unroll") for (int _i = 0; _i < 2; ++_i) \
;     __builtin_amdgcn_global_load_lds((const unsigned*)((const char*)(gbase) + (voff)[_i]), (LAS unsigned*)(lds + (bufoff) + ldsw + _i * 8192), 16, 0, 0); } while (0)
; #define PG8_LDA(dst, b, h) do { _Pragma("unroll") for (int m = 0; m < 4; ++m) _Pragma("unroll") for (int k = 0; k < 2; ++k) dst[m][k] = *(const LAS bf16x8*)(lds + PG8_SA(b, h) + aoff + m * 2048 + k * 1024); } while (0)
; #define PG8_LDB(dst, b, h) do { _Pragma("unroll") for (int n = 0; n < 2; ++n) _Pragma("unroll") for (int k = 0; k < 2; ++k) dst[n][k] = *(const LAS bf16x8*)(lds + PG8_SB(b, h) + boff + n * 2048 + k * 1024); } while (0)
; #define PG8_MMA(ai, bj, At, Bt) do { __builtin_amdgcn_s_setprio(1); _Pragma("unroll") for (int m = 0; m < 4; ++m) _Pragma("unroll") for (int n = 0; n < 2; ++n) _Pragma("unroll") for (int k = 0; k < 2; ++k) \
;     acc[ai][bj][m][n] = __builtin_amdgcn_mfma_f32_16x16x32_bf16(Bt[n][k], At[m][k], acc[ai][bj][m][n], 0, 0, 0); __builtin_amdgcn_s_setprio(0); } while (0)
; #define PG8_WAIT_V(n) asm volatile("s_waitcnt vmcnt(" #n ")" ::: "memory")
; #define PG8_WAIT_L(n) asm volatile("s_waitcnt lgkmcnt(" #n ")" ::: "memory")
; #define PG8_BAR __builtin_amdgcn_s_barrier()
; #define PG8_SCHED __builtin_amdgcn_sched_barrier(0)
; template <class Epi, class Sched = StaticOrder>
; DI void gemm_phase(LAS unsigned char* lds, const Gemm g, const Sched& S, const Epi& E) {
;     ...
;       PG8_LDB(B0, 0, 0); PG8_SCHED; PG8_LDA(At, 0, 0); PG8_STAGE(PG8_SA(1, 1), a1 + hstep, voffA);
;       PG8_WAIT_L(8); PG8_BAR; PG8_WAIT_L(0); PG8_MMA(0, 0, At, B0); PG8_BAR; PG8_SCHED;
;       PG8_LDB(B1, 0, 1); PG8_STAGE(PG8_SB(0, 0), b2, voffB);
;       PG8_BAR; PG8_WAIT_L(0); PG8_MMA(0, 1, At, B1); PG8_BAR;
;       PG8_LDA(At, 0, 1); PG8_STAGE(PG8_SA(0, 0), a2, voffA);
;       PG8_BAR; PG8_WAIT_L(0); PG8_MMA(1, 0, At, B0); PG8_BAR; PG8_SCHED;
;       PG8_STAGE(PG8_SB(0, 1), b2 + hstep, voffB);
;       PG8_WAIT_V(6); PG8_BAR; PG8_MMA(1, 1, At, B1); PG8_BAR;
.LBB0_1194:
	ds_read_b128 v[128:131], v214
	ds_read_b128 v[132:135], v214 offset:1024
	ds_read_b128 v[136:139], v214 offset:2048
	ds_read_b128 v[140:143], v214 offset:3072
	s_add_u32 s24, s22, 0xfff80080
	s_addc_u32 s25, s23, -1
	s_cmp_eq_u32 s54, 28
	s_cselect_b32 s27, s17, s25
	s_cselect_b32 s26, s43, s24
	s_cselect_b32 s25, s15, s53
	s_cselect_b32 s24, s51, s52
	s_add_i32 m0, s37, 0xc000
	ds_read_b128 v[144:147], v215
	ds_read_b128 v[148:151], v215 offset:1024
	ds_read_b128 v[152:155], v215 offset:2048
	ds_read_b128 v[156:159], v215 offset:3072
	ds_read_b128 v[160:163], v215 offset:4096
	ds_read_b128 v[164:167], v215 offset:5120
	ds_read_b128 v[168:171], v215 offset:6144
	ds_read_b128 v[172:175], v215 offset:7168
	global_load_lds_dwordx4 v184, s[22:23]
	s_add_i32 m0, s37, 0xe000
	s_nop 0
	global_load_lds_dwordx4 v186, s[22:23]
	s_waitcnt lgkmcnt(0)
	s_setprio 1
	s_barrier
	v_mfma_f32_16x16x32_bf16 v[124:127], v[128:131], v[144:147], v[124:127]
	v_mfma_f32_16x16x32_bf16 v[120:123], v[136:139], v[144:147], v[120:123]
	v_mfma_f32_16x16x32_bf16 v[108:111], v[128:131], v[152:155], v[108:111]
	v_mfma_f32_16x16x32_bf16 v[104:107], v[136:139], v[152:155], v[104:107]
	v_mfma_f32_16x16x32_bf16 v[92:95], v[128:131], v[160:163], v[92:95]
	v_mfma_f32_16x16x32_bf16 v[88:91], v[136:139], v[160:163], v[88:91]
	v_mfma_f32_16x16x32_bf16 v[76:79], v[128:131], v[168:171], v[76:79]
	v_mfma_f32_16x16x32_bf16 v[72:75], v[136:139], v[168:171], v[72:75]
	v_mfma_f32_16x16x32_bf16 v[124:127], v[132:135], v[148:151], v[124:127]
	v_mfma_f32_16x16x32_bf16 v[120:123], v[140:143], v[148:151], v[120:123]
	v_mfma_f32_16x16x32_bf16 v[108:111], v[132:135], v[156:159], v[108:111]
	v_mfma_f32_16x16x32_bf16 v[104:107], v[140:143], v[156:159], v[104:107]
	v_mfma_f32_16x16x32_bf16 v[92:95], v[132:135], v[164:167], v[92:95]
	v_mfma_f32_16x16x32_bf16 v[88:91], v[140:143], v[164:167], v[88:91]
	v_mfma_f32_16x16x32_bf16 v[76:79], v[132:135], v[172:175], v[76:79]
	v_mfma_f32_16x16x32_bf16 v[72:75], v[140:143], v[172:175], v[72:75]
	s_barrier
	s_setprio 0
	s_add_i32 s55, s48, s35
	s_add_u32 s98, s24, 0x80
	s_addc_u32 s99, s25, 0
	s_add_u32 s100, s26, 0x80
	s_addc_u32 s101, s27, 0
	s_mov_b32 m0, s55
	ds_read_b128 v[192:195], v216
	ds_read_b128 v[196:199], v216 offset:1024
	ds_read_b128 v[200:203], v216 offset:2048
	ds_read_b128 v[204:207], v216 offset:3072
	global_load_lds_dwordx4 v180, s[24:25]
	s_add_i32 m0, s55, 0x2000
	s_nop 0
	global_load_lds_dwordx4 v176, s[24:25]
	s_waitcnt lgkmcnt(0)
	s_setprio 1
	s_barrier
	v_mfma_f32_16x16x32_bf16 v[116:119], v[192:195], v[144:147], v[116:119]
	v_mfma_f32_16x16x32_bf16 v[112:115], v[200:203], v[144:147], v[112:115]
	v_mfma_f32_16x16x32_bf16 v[100:103], v[192:195], v[152:155], v[100:103]
	v_mfma_f32_16x16x32_bf16 v[96:99], v[200:203], v[152:155], v[96:99]
	v_mfma_f32_16x16x32_bf16 v[84:87], v[192:195], v[160:163], v[84:87]
	v_mfma_f32_16x16x32_bf16 v[80:83], v[200:203], v[160:163], v[80:83]
	v_mfma_f32_16x16x32_bf16 v[68:71], v[192:195], v[168:171], v[68:71]
	v_mfma_f32_16x16x32_bf16 v[64:67], v[200:203], v[168:171], v[64:67]
	v_mfma_f32_16x16x32_bf16 v[116:119], v[196:199], v[148:151], v[116:119]
	v_mfma_f32_16x16x32_bf16 v[112:115], v[204:207], v[148:151], v[112:115]
	v_mfma_f32_16x16x32_bf16 v[100:103], v[196:199], v[156:159], v[100:103]
	v_mfma_f32_16x16x32_bf16 v[96:99], v[204:207], v[156:159], v[96:99]
	v_mfma_f32_16x16x32_bf16 v[84:87], v[196:199], v[164:167], v[84:87]
	v_mfma_f32_16x16x32_bf16 v[80:83], v[204:207], v[164:167], v[80:83]
	v_mfma_f32_16x16x32_bf16 v[68:71], v[196:199], v[172:175], v[68:71]
	v_mfma_f32_16x16x32_bf16 v[64:67], v[204:207], v[172:175], v[64:67]
	s_barrier
	s_setprio 0
	s_mov_b32 m0, s37
	ds_read_b128 v[144:147], v215 offset:16384
	ds_read_b128 v[148:151], v215 offset:17408
	ds_read_b128 v[152:155], v215 offset:18432
	ds_read_b128 v[156:159], v215 offset:19456
	ds_read_b128 v[160:163], v215 offset:20480
	ds_read_b128 v[164:167], v215 offset:21504
	ds_read_b128 v[168:171], v215 offset:22528
	ds_read_b128 v[172:175], v215 offset:23552
	global_load_lds_dwordx4 v182, s[26:27]
	s_mov_b32 m0, s38
	s_nop 0
	global_load_lds_dwordx4 v178, s[26:27]
	s_waitcnt lgkmcnt(0)
	s_setprio 1
	s_barrier
	v_mfma_f32_16x16x32_bf16 v[60:63], v[128:131], v[144:147], v[60:63]
	v_mfma_f32_16x16x32_bf16 v[56:59], v[136:139], v[144:147], v[56:59]
	v_mfma_f32_16x16x32_bf16 v[44:47], v[128:131], v[152:155], v[44:47]
	v_mfma_f32_16x16x32_bf16 v[40:43], v[136:139], v[152:155], v[40:43]
	v_mfma_f32_16x16x32_bf16 v[28:31], v[128:131], v[160:163], v[28:31]
	v_mfma_f32_16x16x32_bf16 v[24:27], v[136:139], v[160:163], v[24:27]
	v_mfma_f32_16x16x32_bf16 v[12:15], v[128:131], v[168:171], v[12:15]
	v_mfma_f32_16x16x32_bf16 v[8:11], v[136:139], v[168:171], v[8:11]
	v_mfma_f32_16x16x32_bf16 v[60:63], v[132:135], v[148:151], v[60:63]
	v_mfma_f32_16x16x32_bf16 v[56:59], v[140:143], v[148:151], v[56:59]
	v_mfma_f32_16x16x32_bf16 v[44:47], v[132:135], v[156:159], v[44:47]
	v_mfma_f32_16x16x32_bf16 v[40:43], v[140:143], v[156:159], v[40:43]
	v_mfma_f32_16x16x32_bf16 v[28:31], v[132:135], v[164:167], v[28:31]
	v_mfma_f32_16x16x32_bf16 v[24:27], v[140:143], v[164:167], v[24:27]
	v_mfma_f32_16x16x32_bf16 v[12:15], v[132:135], v[172:175], v[12:15]
	v_mfma_f32_16x16x32_bf16 v[8:11], v[140:143], v[172:175], v[8:11]
	s_barrier
	s_setprio 0
	s_add_u32 s56, s24, 0x80000
	s_addc_u32 s57, s25, 0
	s_add_i32 s55, s49, s35
	s_mov_b32 m0, s55
	s_nop 0
	global_load_lds_dwordx4 v180, s[56:57]
	s_add_i32 m0, s55, 0x2000
	s_nop 0
	global_load_lds_dwordx4 v176, s[56:57]
	s_waitcnt vmcnt(6)
	s_setprio 1
	s_barrier
; #define PG8_STAGE(bufoff, gbase, voff) do { _Pragma("unroll") for (int _i = 0; _i < 2; ++_i) \
;     __builtin_amdgcn_global_load_lds((const unsigned*)((const char*)(gbase) + (voff)[_i]), (LAS unsigned*)(lds + (bufoff) + ldsw + _i * 8192), 16, 0, 0); } while (0)
; #define PG8_LDA(dst, b, h) do { _Pragma("unroll") for (int m = 0; m < 4; ++m) _Pragma("unroll") for (int k = 0; k < 2; ++k) dst[m][k] = *(const LAS bf16x8*)(lds + PG8_SA(b, h) + aoff + m * 2048 + k * 1024); } while (0)
; #define PG8_LDB(dst, b, h) do { _Pragma("unroll") for (int n = 0; n < 2; ++n) _Pragma("unroll") for (int k = 0; k < 2; ++k) dst[n][k] = *(const LAS bf16x8*)(lds + PG8_SB(b, h) + boff + n * 2048 + k * 1024); } while (0)
; #define PG8_MMA(ai, bj, At, Bt) do { __builtin_amdgcn_s_setprio(1); _Pragma("unroll") for (int m = 0; m < 4; ++m) _Pragma("unroll") for (int n = 0; n < 2; ++n) _Pragma("unroll") for (int k = 0; k < 2; ++k) \
;     acc[ai][bj][m][n] = __builtin_amdgcn_mfma_f32_16x16x32_bf16(Bt[n][k], At[m][k], acc[ai][bj][m][n], 0, 0, 0); __builtin_amdgcn_s_setprio(0); } while (0)
; #define PG8_WAIT_V(n) asm volatile("s_waitcnt vmcnt(" #n ")" ::: "memory")
; #define PG8_WAIT_L(n) asm volatile("s_waitcnt lgkmcnt(" #n ")" ::: "memory")
; #define PG8_BAR __builtin_amdgcn_s_barrier()
; #define PG8_SCHED __builtin_amdgcn_sched_barrier(0)
; template <class Epi, class Sched = StaticOrder>
; DI void gemm_phase(LAS unsigned char* lds, const Gemm g, const Sched& S, const Epi& E) {
;     ...
;       PG8_WAIT_V(6); PG8_BAR; PG8_MMA(1, 1, At, B1); PG8_BAR;
;       PG8_LDB(B0, 1, 0); PG8_SCHED; PG8_LDA(At, 1, 0); PG8_STAGE(PG8_SA(0, 1), a2 + hstep, voffA);
;       PG8_WAIT_L(8); PG8_BAR; PG8_WAIT_L(0); PG8_MMA(0, 0, At, B0); PG8_BAR; PG8_SCHED;
;       PG8_LDB(B1, 1, 1); PG8_STAGE(PG8_SB(1, 0), b3, voffB);
;       PG8_BAR; PG8_WAIT_L(0); PG8_MMA(0, 1, At, B1); PG8_BAR;
;       PG8_LDA(At, 1, 1); PG8_STAGE(PG8_SA(1, 0), a3, voffA);
;       PG8_BAR; PG8_WAIT_L(0); PG8_MMA(1, 0, At, B0); PG8_BAR; PG8_SCHED;
	v_mfma_f32_16x16x32_bf16 v[52:55], v[192:195], v[144:147], v[52:55]
	v_mfma_f32_16x16x32_bf16 v[48:51], v[200:203], v[144:147], v[48:51]
	v_mfma_f32_16x16x32_bf16 v[36:39], v[192:195], v[152:155], v[36:39]
	v_mfma_f32_16x16x32_bf16 v[32:35], v[200:203], v[152:155], v[32:35]
	v_mfma_f32_16x16x32_bf16 v[20:23], v[192:195], v[160:163], v[20:23]
	v_mfma_f32_16x16x32_bf16 v[16:19], v[200:203], v[160:163], v[16:19]
	v_mfma_f32_16x16x32_bf16 v[4:7], v[192:195], v[168:171], v[4:7]
	v_mfma_f32_16x16x32_bf16 v[0:3], v[200:203], v[168:171], v[0:3]
	v_mfma_f32_16x16x32_bf16 v[52:55], v[196:199], v[148:151], v[52:55]
	v_mfma_f32_16x16x32_bf16 v[48:51], v[204:207], v[148:151], v[48:51]
	v_mfma_f32_16x16x32_bf16 v[36:39], v[196:199], v[156:159], v[36:39]
	v_mfma_f32_16x16x32_bf16 v[32:35], v[204:207], v[156:159], v[32:35]
	v_mfma_f32_16x16x32_bf16 v[20:23], v[196:199], v[164:167], v[20:23]
	v_mfma_f32_16x16x32_bf16 v[16:19], v[204:207], v[164:167], v[16:19]
	v_mfma_f32_16x16x32_bf16 v[4:7], v[196:199], v[172:175], v[4:7]
	v_mfma_f32_16x16x32_bf16 v[0:3], v[204:207], v[172:175], v[0:3]
	s_barrier
	s_setprio 0
	s_add_i32 s55, 0, 0x18000
	v_add_u32_e32 v140, s55, v212
	ds_read_b128 v[128:131], v140
	ds_read_b128 v[132:135], v140 offset:1024
	ds_read_b128 v[136:139], v140 offset:2048
	ds_read_b128 v[140:143], v140 offset:3072
	s_add_u32 s26, s26, 0x80000
	s_addc_u32 s27, s27, 0
	s_mov_b32 m0, s39
	ds_read_b128 v[144:147], v215 offset:32768
	ds_read_b128 v[148:151], v215 offset:33792
	ds_read_b128 v[152:155], v215 offset:34816
	ds_read_b128 v[156:159], v215 offset:35840
	ds_read_b128 v[160:163], v215 offset:36864
	ds_read_b128 v[164:167], v215 offset:37888
	ds_read_b128 v[168:171], v215 offset:38912
	ds_read_b128 v[172:175], v215 offset:39936
	global_load_lds_dwordx4 v182, s[26:27]
	s_mov_b32 m0, s40
	s_nop 0
	global_load_lds_dwordx4 v178, s[26:27]
	s_waitcnt lgkmcnt(0)
	s_setprio 1
	s_barrier
	v_mfma_f32_16x16x32_bf16 v[124:127], v[128:131], v[144:147], v[124:127]
	v_mfma_f32_16x16x32_bf16 v[120:123], v[136:139], v[144:147], v[120:123]
	v_mfma_f32_16x16x32_bf16 v[108:111], v[128:131], v[152:155], v[108:111]
	v_mfma_f32_16x16x32_bf16 v[104:107], v[136:139], v[152:155], v[104:107]
	v_mfma_f32_16x16x32_bf16 v[92:95], v[128:131], v[160:163], v[92:95]
	v_mfma_f32_16x16x32_bf16 v[88:91], v[136:139], v[160:163], v[88:91]
	v_mfma_f32_16x16x32_bf16 v[76:79], v[128:131], v[168:171], v[76:79]
	v_mfma_f32_16x16x32_bf16 v[72:75], v[136:139], v[168:171], v[72:75]
	v_mfma_f32_16x16x32_bf16 v[124:127], v[132:135], v[148:151], v[124:127]
	v_mfma_f32_16x16x32_bf16 v[120:123], v[140:143], v[148:151], v[120:123]
	v_mfma_f32_16x16x32_bf16 v[108:111], v[132:135], v[156:159], v[108:111]
	v_mfma_f32_16x16x32_bf16 v[104:107], v[140:143], v[156:159], v[104:107]
	v_mfma_f32_16x16x32_bf16 v[92:95], v[132:135], v[164:167], v[92:95]
	v_mfma_f32_16x16x32_bf16 v[88:91], v[140:143], v[164:167], v[88:91]
	v_mfma_f32_16x16x32_bf16 v[76:79], v[132:135], v[172:175], v[76:79]
	v_mfma_f32_16x16x32_bf16 v[72:75], v[140:143], v[172:175], v[72:75]
	s_barrier
	s_setprio 0
	s_add_i32 s26, 0, 0x1c000
	s_add_i32 s27, s55, s35
	v_add_u32_e32 v204, s26, v212
	s_mov_b32 m0, s27
	ds_read_b128 v[192:195], v204
	ds_read_b128 v[196:199], v204 offset:1024
	ds_read_b128 v[200:203], v204 offset:2048
	ds_read_b128 v[204:207], v204 offset:3072
	global_load_lds_dwordx4 v180, s[98:99]
	s_add_i32 m0, s27, 0x2000
	s_nop 0
	global_load_lds_dwordx4 v176, s[98:99]
	s_waitcnt lgkmcnt(0)
	s_setprio 1
	s_barrier
	v_mfma_f32_16x16x32_bf16 v[116:119], v[192:195], v[144:147], v[116:119]
	v_mfma_f32_16x16x32_bf16 v[112:115], v[200:203], v[144:147], v[112:115]
	v_mfma_f32_16x16x32_bf16 v[100:103], v[192:195], v[152:155], v[100:103]
	v_mfma_f32_16x16x32_bf16 v[96:99], v[200:203], v[152:155], v[96:99]
	v_mfma_f32_16x16x32_bf16 v[84:87], v[192:195], v[160:163], v[84:87]
	v_mfma_f32_16x16x32_bf16 v[80:83], v[200:203], v[160:163], v[80:83]
	v_mfma_f32_16x16x32_bf16 v[68:71], v[192:195], v[168:171], v[68:71]
	v_mfma_f32_16x16x32_bf16 v[64:67], v[200:203], v[168:171], v[64:67]
	v_mfma_f32_16x16x32_bf16 v[116:119], v[196:199], v[148:151], v[116:119]
	v_mfma_f32_16x16x32_bf16 v[112:115], v[204:207], v[148:151], v[112:115]
	v_mfma_f32_16x16x32_bf16 v[100:103], v[196:199], v[156:159], v[100:103]
	v_mfma_f32_16x16x32_bf16 v[96:99], v[204:207], v[156:159], v[96:99]
	v_mfma_f32_16x16x32_bf16 v[84:87], v[196:199], v[164:167], v[84:87]
	v_mfma_f32_16x16x32_bf16 v[80:83], v[204:207], v[164:167], v[80:83]
	v_mfma_f32_16x16x32_bf16 v[68:71], v[196:199], v[172:175], v[68:71]
	v_mfma_f32_16x16x32_bf16 v[64:67], v[204:207], v[172:175], v[64:67]
	s_barrier
	s_setprio 0
	s_mov_b32 m0, s44
	ds_read_b128 v[144:147], v215 offset:49152
	ds_read_b128 v[148:151], v215 offset:50176
	ds_read_b128 v[152:155], v215 offset:51200
	ds_read_b128 v[156:159], v215 offset:52224
	ds_read_b128 v[160:163], v215 offset:53248
	ds_read_b128 v[164:167], v215 offset:54272
	ds_read_b128 v[168:171], v215 offset:55296
	ds_read_b128 v[172:175], v215 offset:56320
	global_load_lds_dwordx4 v182, s[100:101]
	s_mov_b32 m0, s45
	s_nop 0
	global_load_lds_dwordx4 v178, s[100:101]
	s_waitcnt lgkmcnt(0)
	s_setprio 1
	s_barrier
; #define PG8_STAGE(bufoff, gbase, voff) do { _Pragma("unroll") for (int _i = 0; _i < 2; ++_i) \
;     __builtin_amdgcn_global_load_lds((const unsigned*)((const char*)(gbase) + (voff)[_i]), (LAS unsigned*)(lds + (bufoff) + ldsw + _i * 8192), 16, 0, 0); } while (0)
; #define PG8_MMA(ai, bj, At, Bt) do { __builtin_amdgcn_s_setprio(1); _Pragma("unroll") for (int m = 0; m < 4; ++m) _Pragma("unroll") for (int n = 0; n < 2; ++n) _Pragma("unroll") for (int k = 0; k < 2; ++k) \
;     acc[ai][bj][m][n] = __builtin_amdgcn_mfma_f32_16x16x32_bf16(Bt[n][k], At[m][k], acc[ai][bj][m][n], 0, 0, 0); __builtin_amdgcn_s_setprio(0); } while (0)
; #define PG8_WAIT_V(n) asm volatile("s_waitcnt vmcnt(" #n ")" ::: "memory")
; #define PG8_WAIT_L(n) asm volatile("s_waitcnt lgkmcnt(" #n ")" ::: "memory")
; #define PG8_BAR __builtin_amdgcn_s_barrier()
; #define PG8_SCHED __builtin_amdgcn_sched_barrier(0)
; template <class Epi, class Sched = StaticOrder>
; DI void gemm_phase(LAS unsigned char* lds, const Gemm g, const Sched& S, const Epi& E) {
;     ...
;       PG8_BAR; PG8_WAIT_L(0); PG8_MMA(1, 0, At, B0); PG8_BAR; PG8_SCHED;
;       PG8_STAGE(PG8_SB(1, 1), b3 + hstep, voffB);
;       PG8_WAIT_V(6); PG8_BAR; PG8_MMA(1, 1, At, B1); PG8_BAR;
	v_mfma_f32_16x16x32_bf16 v[60:63], v[128:131], v[144:147], v[60:63]
	v_mfma_f32_16x16x32_bf16 v[56:59], v[136:139], v[144:147], v[56:59]
	v_mfma_f32_16x16x32_bf16 v[44:47], v[128:131], v[152:155], v[44:47]
	v_mfma_f32_16x16x32_bf16 v[40:43], v[136:139], v[152:155], v[40:43]
	v_mfma_f32_16x16x32_bf16 v[28:31], v[128:131], v[160:163], v[28:31]
	v_mfma_f32_16x16x32_bf16 v[24:27], v[136:139], v[160:163], v[24:27]
	v_mfma_f32_16x16x32_bf16 v[12:15], v[128:131], v[168:171], v[12:15]
	v_mfma_f32_16x16x32_bf16 v[8:11], v[136:139], v[168:171], v[8:11]
	v_mfma_f32_16x16x32_bf16 v[60:63], v[132:135], v[148:151], v[60:63]
	v_mfma_f32_16x16x32_bf16 v[56:59], v[140:143], v[148:151], v[56:59]
	v_mfma_f32_16x16x32_bf16 v[44:47], v[132:135], v[156:159], v[44:47]
	v_mfma_f32_16x16x32_bf16 v[40:43], v[140:143], v[156:159], v[40:43]
	v_mfma_f32_16x16x32_bf16 v[28:31], v[132:135], v[164:167], v[28:31]
	v_mfma_f32_16x16x32_bf16 v[24:27], v[140:143], v[164:167], v[24:27]
	v_mfma_f32_16x16x32_bf16 v[12:15], v[132:135], v[172:175], v[12:15]
	v_mfma_f32_16x16x32_bf16 v[8:11], v[140:143], v[172:175], v[8:11]
	s_barrier
	s_setprio 0
	s_add_u32 s24, s24, 0x80080
	s_addc_u32 s25, s25, 0
	s_add_i32 s26, s26, s35
	s_mov_b32 m0, s26
	s_nop 0
	global_load_lds_dwordx4 v180, s[24:25]
	s_add_i32 m0, s26, 0x2000
	s_nop 0
	global_load_lds_dwordx4 v176, s[24:25]
	s_waitcnt vmcnt(6)
	s_add_i32 s54, s54, 2
	s_add_u32 s22, s22, 0x100
	s_addc_u32 s23, s23, 0
	s_add_u32 s52, s52, 0x100
	s_addc_u32 s53, s53, 0
	s_cmp_gt_u32 s54, 29
	s_setprio 1
	s_barrier
	v_mfma_f32_16x16x32_bf16 v[52:55], v[192:195], v[144:147], v[52:55]
	v_mfma_f32_16x16x32_bf16 v[48:51], v[200:203], v[144:147], v[48:51]
	v_mfma_f32_16x16x32_bf16 v[36:39], v[192:195], v[152:155], v[36:39]
	v_mfma_f32_16x16x32_bf16 v[32:35], v[200:203], v[152:155], v[32:35]
	v_mfma_f32_16x16x32_bf16 v[20:23], v[192:195], v[160:163], v[20:23]
	v_mfma_f32_16x16x32_bf16 v[16:19], v[200:203], v[160:163], v[16:19]
	v_mfma_f32_16x16x32_bf16 v[4:7], v[192:195], v[168:171], v[4:7]
	v_mfma_f32_16x16x32_bf16 v[0:3], v[200:203], v[168:171], v[0:3]
	v_mfma_f32_16x16x32_bf16 v[52:55], v[196:199], v[148:151], v[52:55]
	v_mfma_f32_16x16x32_bf16 v[48:51], v[204:207], v[148:151], v[48:51]
	v_mfma_f32_16x16x32_bf16 v[36:39], v[196:199], v[156:159], v[36:39]
	v_mfma_f32_16x16x32_bf16 v[32:35], v[204:207], v[156:159], v[32:35]
	v_mfma_f32_16x16x32_bf16 v[20:23], v[196:199], v[164:167], v[20:23]
	v_mfma_f32_16x16x32_bf16 v[16:19], v[204:207], v[164:167], v[16:19]
	v_mfma_f32_16x16x32_bf16 v[4:7], v[196:199], v[172:175], v[4:7]
	v_mfma_f32_16x16x32_bf16 v[0:3], v[204:207], v[172:175], v[0:3]
	s_barrier
	s_setprio 0
	s_cbranch_scc0 .LBB0_1194
; DI unsigned pack2(float lo, float hi) { f32x2 v = {lo, hi}; bf16v2 r = __builtin_convertvector(v, bf16v2); return __builtin_bit_cast(unsigned, r); }
;   DI void operator()(const f32x4 (&acc)[2][2][4][2], const Unit& u, int wr, int wc, int fr, int fq) const {
;     const int row0 = u.pm * BM + wr * 64 + fr, col0 = u.pn * BM + wc * 32 + 8 * fq;
; #pragma unroll
;     for (int ai = 0; ai < 2; ++ai) {
;       f32x4 bv[4][2][2];
; #pragma unroll
;       for (int m = 0; m < 4; ++m)
; #pragma unroll
;         for (int bj = 0; bj < 2; ++bj) {
;           const float* bp = base + (size_t)(row0 + ai * HALF + m * 16) * 2048 + col0 + bj * HALF;
;           bv[m][bj][0] = *(const f32x4*)bp; bv[m][bj][1] = *(const f32x4*)(bp + 4);
;         }
; #pragma unroll
;       for (int m = 0; m < 4; ++m) {
;         const int row = row0 + ai * HALF + m * 16;
;         const size_t off = (size_t)row * 2048 + col0;
;         float ss = 0.f;
; #pragma unroll
;         for (int bj = 0; bj < 2; ++bj) {
;           const f32x4 v0 = acc[ai][bj][m][0] + bv[m][bj][0], v1 = acc[ai][bj][m][1] + bv[m][bj][1];
;           *(f32x4*)(C + off + bj * HALF) = v0; *(f32x4*)(C + off + bj * HALF + 4) = v1;
;           if (xb) {
;             u32x4 w; w.x = pack2(v0[0], v0[1]); w.y = pack2(v0[2], v0[3]); w.z = pack2(v1[0], v1[1]); w.w = pack2(v1[2], v1[3]);
;             *(u32x4*)(xb + off + bj * HALF) = w;
;             ss += v0[0] * v0[0] + v0[1] * v0[1] + v0[2] * v0[2] + v0[3] * v0[3] + v1[0] * v1[0] + v1[1] * v1[1] + v1[2] * v1[2] + v1[3] * v1[3];
;           }
;         }
;         if (xb) {
;           ss += __shfl_xor(ss, 16); ss += __shfl_xor(ss, 32);
;           if (fq == 0) ssq[(size_t)row * 32 + u.pn * 4 + wc] = ss;
;         }
	v_lshl_add_u32 v194, s12, 8, v211
	v_lshl_or_b32 v192, s42, 8, v213
	v_readlane_b32 s52, v243, 3
	v_ashrrev_i32_e32 v193, 31, v192
	v_readlane_b32 s66, v243, 17
	v_readlane_b32 s67, v243, 18
	v_ashrrev_i32_e32 v195, 31, v194
	v_lshlrev_b64 v[128:129], 13, v[194:195]
	v_lshl_add_u64 v[196:197], v[192:193], 2, s[66:67]
	v_lshl_add_u64 v[236:237], v[196:197], 0, v[128:129]
	global_load_dwordx4 v[220:223], v[236:237], off
	global_load_dwordx4 v[224:227], v[236:237], off offset:16
	global_load_dwordx4 v[228:231], v[236:237], off offset:512
	global_load_dwordx4 v[232:235], v[236:237], off offset:528
	v_or_b32_e32 v206, 16, v194
	v_or_b32_e32 v202, 32, v194
	v_or_b32_e32 v198, 48, v194
	v_ashrrev_i32_e32 v207, 31, v206
	v_ashrrev_i32_e32 v203, 31, v202
	v_ashrrev_i32_e32 v199, 31, v198
	v_lshlrev_b64 v[128:129], 13, v[206:207]
	v_lshlrev_b64 v[130:131], 13, v[202:203]
	v_lshlrev_b64 v[132:133], 13, v[198:199]
	v_lshl_add_u64 v[208:209], v[196:197], 0, v[128:129]
	v_lshl_add_u64 v[204:205], v[196:197], 0, v[130:131]
	v_lshl_add_u64 v[200:201], v[196:197], 0, v[132:133]
	global_load_dwordx4 v[168:171], v[208:209], off offset:16
	global_load_dwordx4 v[172:175], v[208:209], off
	global_load_dwordx4 v[160:163], v[208:209], off offset:528
	global_load_dwordx4 v[164:167], v[208:209], off offset:512
	global_load_dwordx4 v[152:155], v[204:205], off offset:16
	global_load_dwordx4 v[156:159], v[204:205], off
	global_load_dwordx4 v[144:147], v[204:205], off offset:528
	global_load_dwordx4 v[148:151], v[204:205], off offset:512
	global_load_dwordx4 v[136:139], v[200:201], off offset:16
	global_load_dwordx4 v[140:143], v[200:201], off
	global_load_dwordx4 v[128:131], v[200:201], off offset:528
	global_load_dwordx4 v[132:135], v[200:201], off offset:512
	v_and_b32_e32 v218, 64, v217
	v_xor_b32_e32 v238, 16, v217
	v_add_u32_e32 v240, 64, v218
	v_xor_b32_e32 v239, 32, v217
	v_cmp_lt_i32_e32 vcc, v238, v240
	v_lshlrev_b64 v[218:219], 11, v[194:195]
	s_lshl_b32 s22, s42, 2
	v_cndmask_b32_e32 v241, v217, v238, vcc
	v_cmp_lt_i32_e32 vcc, v239, v240
	s_ashr_i32 s23, s22, 31
	v_readlane_b32 s53, v243, 4
	v_cndmask_b32_e32 v240, v217, v239, vcc
	v_lshl_add_u64 v[238:239], v[218:219], 0, v[192:193]
	v_lshlrev_b32_e32 v218, 2, v241
	v_lshl_add_u64 v[238:239], v[238:239], 1, s[2:3]
	v_readlane_b32 s54, v243, 5
	v_readlane_b32 s55, v243, 6
	v_readlane_b32 s56, v243, 7
	v_readlane_b32 s57, v243, 8
	v_readlane_b32 s58, v243, 9
	v_readlane_b32 s59, v243, 10
	v_readlane_b32 s60, v243, 11
	v_readlane_b32 s61, v243, 12
	v_readlane_b32 s62, v243, 13
	v_readlane_b32 s63, v243, 14
	v_readlane_b32 s64, v243, 15
	v_readlane_b32 s65, v243, 16
	s_waitcnt vmcnt(0)
	v_pk_add_f32 v[126:127], v[126:127], v[222:223]
	v_pk_add_f32 v[124:125], v[124:125], v[220:221]
	v_pk_add_f32 v[116:117], v[116:117], v[228:229]
	v_pk_add_f32 v[122:123], v[122:123], v[226:227]
	v_pk_add_f32 v[120:121], v[120:121], v[224:225]
	v_pk_add_f32 v[220:221], v[112:113], v[232:233]
	global_store_dwordx4 v[236:237], v[124:127], off
	global_store_dwordx4 v[236:237], v[120:123], off offset:16
	v_cvt_pk_bf16_f32 v112, v124, v125
	v_mul_f32_e32 v125, v125, v125
	v_mul_f32_e32 v219, v117, v117
	v_pk_add_f32 v[118:119], v[118:119], v[230:231]
	v_fmac_f32_e32 v125, v124, v124
	v_fmac_f32_e32 v219, v116, v116
	v_fmac_f32_e32 v125, v126, v126
	v_fmac_f32_e32 v219, v118, v118
	v_fmac_f32_e32 v125, v127, v127
	v_fmac_f32_e32 v219, v119, v119
	v_fmac_f32_e32 v125, v120, v120
	v_fmac_f32_e32 v219, v220, v220
	v_pk_add_f32 v[222:223], v[114:115], v[234:235]
	v_fmac_f32_e32 v125, v121, v121
	v_fmac_f32_e32 v219, v221, v221
	v_fmac_f32_e32 v125, v122, v122
	v_fmac_f32_e32 v219, v222, v222
	v_fmac_f32_e32 v125, v123, v123
	v_fmac_f32_e32 v219, v223, v223
	v_cvt_pk_bf16_f32 v114, v120, v121
	v_add_f32_e32 v121, v125, v219
	v_cvt_pk_bf16_f32 v115, v122, v123
	ds_bpermute_b32 v122, v218, v121
	v_cvt_pk_bf16_f32 v113, v126, v127
	global_store_dwordx4 v[238:239], v[112:115], off
	global_store_dwordx4 v[236:237], v[116:119], off offset:512
	global_store_dwordx4 v[236:237], v[220:223], off offset:528
	v_lshlrev_b32_e32 v126, 2, v240
	v_cvt_pk_bf16_f32 v120, v116, v117
	s_waitcnt lgkmcnt(0)
	v_add_f32_e32 v112, v121, v122
	ds_bpermute_b32 v113, v126, v112
	v_cvt_pk_bf16_f32 v121, v118, v119
	v_cvt_pk_bf16_f32 v122, v220, v221
	v_cvt_pk_bf16_f32 v123, v222, v223
	global_store_dwordx4 v[238:239], v[120:123], off offset:256
	s_and_saveexec_b64 s[24:25], s[0:1]
	s_cbranch_execz .LBB0_1197
	s_waitcnt lgkmcnt(0)
	v_add_f32_e32 v114, v112, v113
	v_lshlrev_b64 v[112:113], 7, v[194:195]
	v_lshl_add_u64 v[112:113], s[8:9], 0, v[112:113]
	v_lshl_add_u64 v[112:113], s[22:23], 2, v[112:113]
	s_lshl_b32 s12, s41, 2
	v_lshl_add_u64 v[112:113], v[112:113], 0, s[12:13]
	global_store_dword v[112:113], v114, off

; #define PG8_STAGE(bufoff, gbase, voff) do { _Pragma("unroll") for (int _i = 0; _i < 2; ++_i) \
;     __builtin_amdgcn_global_load_lds((const unsigned*)((const char*)(gbase) + (voff)[_i]), (LAS unsigned*)(lds + (bufoff) + ldsw + _i * 8192), 16, 0, 0); } while (0)
; #define PG8_LDA(dst, b, h) do { _Pragma("unroll") for (int m = 0; m < 4; ++m) _Pragma("unroll") for (int k = 0; k < 2; ++k) dst[m][k] = *(const LAS bf16x8*)(lds + PG8_SA(b, h) + aoff + m * 2048 + k * 1024); } while (0)
; #define PG8_LDB(dst, b, h) do { _Pragma("unroll") for (int n = 0; n < 2; ++n) _Pragma("unroll") for (int k = 0; k < 2; ++k) dst[n][k] = *(const LAS bf16x8*)(lds + PG8_SB(b, h) + boff + n * 2048 + k * 1024); } while (0)
; #define PG8_MMA(ai, bj, At, Bt) do { __builtin_amdgcn_s_setprio(1); _Pragma("unroll") for (int m = 0; m < 4; ++m) _Pragma("unroll") for (int n = 0; n < 2; ++n) _Pragma("unroll") for (int k = 0; k < 2; ++k) \
;     acc[ai][bj][m][n] = __builtin_amdgcn_mfma_f32_16x16x32_bf16(Bt[n][k], At[m][k], acc[ai][bj][m][n], 0, 0, 0); __builtin_amdgcn_s_setprio(0); } while (0)
; #define PG8_WAIT_V(n) asm volatile("s_waitcnt vmcnt(" #n ")" ::: "memory")
; #define PG8_WAIT_L(n) asm volatile("s_waitcnt lgkmcnt(" #n ")" ::: "memory")
; #define PG8_BAR __builtin_amdgcn_s_barrier()
; #define PG8_SCHED __builtin_amdgcn_sched_barrier(0)
; template <class Epi, class Sched = StaticOrder>
; DI void gemm_phase(LAS unsigned char* lds, const Gemm g, const Sched& S, const Epi& E) {
;     ...
;       PG8_LDB(B0, 0, 0); PG8_SCHED; PG8_LDA(At, 0, 0); PG8_STAGE(PG8_SA(1, 1), a1 + hstep, voffA);
;       PG8_WAIT_L(8); PG8_BAR; PG8_WAIT_L(0); PG8_MMA(0, 0, At, B0); PG8_BAR; PG8_SCHED;
;       PG8_LDB(B1, 0, 1); PG8_STAGE(PG8_SB(0, 0), b2, voffB);
;       PG8_BAR; PG8_WAIT_L(0); PG8_MMA(0, 1, At, B1); PG8_BAR;
;       PG8_LDA(At, 0, 1); PG8_STAGE(PG8_SA(0, 0), a2, voffA);
;       PG8_BAR; PG8_WAIT_L(0); PG8_MMA(1, 0, At, B0); PG8_BAR; PG8_SCHED;
;       PG8_STAGE(PG8_SB(0, 1), b2 + hstep, voffB);
;       PG8_WAIT_V(6); PG8_BAR; PG8_MMA(1, 1, At, B1); PG8_BAR;
.LBB0_1277:
	ds_read_b128 v[64:67], v201
	ds_read_b128 v[68:71], v201 offset:1024
	ds_read_b128 v[72:75], v201 offset:2048
	ds_read_b128 v[76:79], v201 offset:3072
	s_add_u32 s48, s14, 0xfff80080
	s_addc_u32 s49, s15, -1
	s_cmp_eq_u32 s58, 28
	s_cselect_b32 s51, s41, s49
	s_cselect_b32 s50, s42, s48
	s_cselect_b32 s49, s39, s53
	s_cselect_b32 s48, s43, s52
	s_add_i32 m0, s64, 0xc000
	ds_read_b128 v[80:83], v202
	ds_read_b128 v[84:87], v202 offset:1024
	ds_read_b128 v[88:91], v202 offset:2048
	ds_read_b128 v[92:95], v202 offset:3072
	ds_read_b128 v[180:183], v202 offset:4096
	ds_read_b128 v[184:187], v202 offset:5120
	ds_read_b128 v[188:191], v202 offset:6144
	ds_read_b128 v[192:195], v202 offset:7168
	global_load_lds_dwordx4 v170, s[14:15]
	s_add_i32 m0, s64, 0xe000
	s_nop 0
	global_load_lds_dwordx4 v172, s[14:15]
	s_waitcnt lgkmcnt(0)
	s_setprio 1
	s_barrier
	v_mfma_f32_16x16x32_bf16 v[156:159], v[64:67], v[80:83], v[156:159]
	v_mfma_f32_16x16x32_bf16 v[144:147], v[72:75], v[80:83], v[144:147]
	v_mfma_f32_16x16x32_bf16 v[140:143], v[64:67], v[88:91], v[140:143]
	v_mfma_f32_16x16x32_bf16 v[132:135], v[72:75], v[88:91], v[132:135]
	v_mfma_f32_16x16x32_bf16 v[124:127], v[64:67], v[180:183], v[124:127]
	v_mfma_f32_16x16x32_bf16 v[116:119], v[72:75], v[180:183], v[116:119]
	v_mfma_f32_16x16x32_bf16 v[112:115], v[64:67], v[188:191], v[112:115]
	v_mfma_f32_16x16x32_bf16 v[108:111], v[72:75], v[188:191], v[108:111]
	v_mfma_f32_16x16x32_bf16 v[156:159], v[68:71], v[84:87], v[156:159]
	v_mfma_f32_16x16x32_bf16 v[144:147], v[76:79], v[84:87], v[144:147]
	v_mfma_f32_16x16x32_bf16 v[140:143], v[68:71], v[92:95], v[140:143]
	v_mfma_f32_16x16x32_bf16 v[132:135], v[76:79], v[92:95], v[132:135]
	v_mfma_f32_16x16x32_bf16 v[124:127], v[68:71], v[184:187], v[124:127]
	v_mfma_f32_16x16x32_bf16 v[116:119], v[76:79], v[184:187], v[116:119]
	v_mfma_f32_16x16x32_bf16 v[112:115], v[68:71], v[192:195], v[112:115]
	v_mfma_f32_16x16x32_bf16 v[108:111], v[76:79], v[192:195], v[108:111]
	s_barrier
	s_setprio 0
	s_add_i32 s59, s72, s62
	s_add_u32 s98, s48, 0x80
	s_addc_u32 s99, s49, 0
	s_add_u32 s100, s50, 0x80
	s_addc_u32 s101, s51, 0
	s_mov_b32 m0, s59
	ds_read_b128 v[206:209], v203
	ds_read_b128 v[212:215], v203 offset:1024
	ds_read_b128 v[216:219], v203 offset:2048
	ds_read_b128 v[220:223], v203 offset:3072
	global_load_lds_dwordx4 v164, s[48:49]
	s_add_i32 m0, s59, 0x2000
	s_nop 0
	global_load_lds_dwordx4 v160, s[48:49]
	s_waitcnt lgkmcnt(0)
	s_setprio 1
	s_barrier
	v_mfma_f32_16x16x32_bf16 v[152:155], v[206:209], v[80:83], v[152:155]
	v_mfma_f32_16x16x32_bf16 v[80:83], v[216:219], v[80:83], v[148:151]
	v_mfma_f32_16x16x32_bf16 v[152:155], v[212:215], v[84:87], v[152:155]
	v_mfma_f32_16x16x32_bf16 v[80:83], v[220:223], v[84:87], v[80:83]
	v_mfma_f32_16x16x32_bf16 v[84:87], v[206:209], v[88:91], v[136:139]
	v_mfma_f32_16x16x32_bf16 v[88:91], v[216:219], v[88:91], v[128:131]
	v_mfma_f32_16x16x32_bf16 v[104:107], v[216:219], v[180:183], v[104:107]
	v_mfma_f32_16x16x32_bf16 v[100:103], v[206:209], v[188:191], v[100:103]
	v_mfma_f32_16x16x32_bf16 v[96:99], v[216:219], v[188:191], v[96:99]
	v_mfma_f32_16x16x32_bf16 v[84:87], v[212:215], v[92:95], v[84:87]
	v_mfma_f32_16x16x32_bf16 v[88:91], v[220:223], v[92:95], v[88:91]
	v_mfma_f32_16x16x32_bf16 v[92:95], v[206:209], v[180:183], v[120:123]
	v_mfma_f32_16x16x32_bf16 v[104:107], v[220:223], v[184:187], v[104:107]
	v_mfma_f32_16x16x32_bf16 v[100:103], v[212:215], v[192:195], v[100:103]
	v_mfma_f32_16x16x32_bf16 v[96:99], v[220:223], v[192:195], v[96:99]
	v_mfma_f32_16x16x32_bf16 v[92:95], v[212:215], v[184:187], v[92:95]
	s_barrier
	s_setprio 0
	s_mov_b32 m0, s64
	ds_read_b128 v[120:123], v202 offset:16384
	ds_read_b128 v[128:131], v202 offset:17408
	ds_read_b128 v[136:139], v202 offset:18432
	ds_read_b128 v[148:151], v202 offset:19456
	ds_read_b128 v[180:183], v202 offset:20480
	ds_read_b128 v[184:187], v202 offset:21504
	ds_read_b128 v[188:191], v202 offset:22528
	ds_read_b128 v[192:195], v202 offset:23552
	global_load_lds_dwordx4 v166, s[50:51]
	s_mov_b32 m0, s65
	s_nop 0
	global_load_lds_dwordx4 v162, s[50:51]
	s_waitcnt lgkmcnt(0)
	s_setprio 1
	s_barrier
	v_mfma_f32_16x16x32_bf16 v[60:63], v[64:67], v[120:123], v[60:63]
	v_mfma_f32_16x16x32_bf16 v[48:51], v[72:75], v[120:123], v[48:51]
	v_mfma_f32_16x16x32_bf16 v[44:47], v[64:67], v[136:139], v[44:47]
	v_mfma_f32_16x16x32_bf16 v[36:39], v[72:75], v[136:139], v[36:39]
	v_mfma_f32_16x16x32_bf16 v[28:31], v[64:67], v[180:183], v[28:31]
	v_mfma_f32_16x16x32_bf16 v[20:23], v[72:75], v[180:183], v[20:23]
	v_mfma_f32_16x16x32_bf16 v[16:19], v[64:67], v[188:191], v[16:19]
	v_mfma_f32_16x16x32_bf16 v[12:15], v[72:75], v[188:191], v[12:15]
	v_mfma_f32_16x16x32_bf16 v[60:63], v[68:71], v[128:131], v[60:63]
	v_mfma_f32_16x16x32_bf16 v[48:51], v[76:79], v[128:131], v[48:51]
	v_mfma_f32_16x16x32_bf16 v[44:47], v[68:71], v[148:151], v[44:47]
	v_mfma_f32_16x16x32_bf16 v[36:39], v[76:79], v[148:151], v[36:39]
	v_mfma_f32_16x16x32_bf16 v[28:31], v[68:71], v[184:187], v[28:31]
	v_mfma_f32_16x16x32_bf16 v[20:23], v[76:79], v[184:187], v[20:23]
	v_mfma_f32_16x16x32_bf16 v[16:19], v[68:71], v[192:195], v[16:19]
	v_mfma_f32_16x16x32_bf16 v[12:15], v[76:79], v[192:195], v[12:15]
	s_barrier
	s_setprio 0
	s_add_u32 s78, s48, 0x80000
	s_addc_u32 s79, s49, 0
	s_add_i32 s59, s73, s62
	s_mov_b32 m0, s59
	s_nop 0
	global_load_lds_dwordx4 v164, s[78:79]
	s_add_i32 m0, s59, 0x2000
	s_nop 0
	global_load_lds_dwordx4 v160, s[78:79]
	s_waitcnt vmcnt(6)
	s_setprio 1
	s_barrier
; #define PG8_STAGE(bufoff, gbase, voff) do { _Pragma("unroll") for (int _i = 0; _i < 2; ++_i) \
;     __builtin_amdgcn_global_load_lds((const unsigned*)((const char*)(gbase) + (voff)[_i]), (LAS unsigned*)(lds + (bufoff) + ldsw + _i * 8192), 16, 0, 0); } while (0)
; #define PG8_LDA(dst, b, h) do { _Pragma("unroll") for (int m = 0; m < 4; ++m) _Pragma("unroll") for (int k = 0; k < 2; ++k) dst[m][k] = *(const LAS bf16x8*)(lds + PG8_SA(b, h) + aoff + m * 2048 + k * 1024); } while (0)
; #define PG8_LDB(dst, b, h) do { _Pragma("unroll") for (int n = 0; n < 2; ++n) _Pragma("unroll") for (int k = 0; k < 2; ++k) dst[n][k] = *(const LAS bf16x8*)(lds + PG8_SB(b, h) + boff + n * 2048 + k * 1024); } while (0)
; #define PG8_MMA(ai, bj, At, Bt) do { __builtin_amdgcn_s_setprio(1); _Pragma("unroll") for (int m = 0; m < 4; ++m) _Pragma("unroll") for (int n = 0; n < 2; ++n) _Pragma("unroll") for (int k = 0; k < 2; ++k) \
;     acc[ai][bj][m][n] = __builtin_amdgcn_mfma_f32_16x16x32_bf16(Bt[n][k], At[m][k], acc[ai][bj][m][n], 0, 0, 0); __builtin_amdgcn_s_setprio(0); } while (0)
; #define PG8_WAIT_V(n) asm volatile("s_waitcnt vmcnt(" #n ")" ::: "memory")
; #define PG8_WAIT_L(n) asm volatile("s_waitcnt lgkmcnt(" #n ")" ::: "memory")
; #define PG8_BAR __builtin_amdgcn_s_barrier()
; #define PG8_SCHED __builtin_amdgcn_sched_barrier(0)
; template <class Epi, class Sched = StaticOrder>
; DI void gemm_phase(LAS unsigned char* lds, const Gemm g, const Sched& S, const Epi& E) {
;     ...
;       PG8_WAIT_V(6); PG8_BAR; PG8_MMA(1, 1, At, B1); PG8_BAR;
;       PG8_LDB(B0, 1, 0); PG8_SCHED; PG8_LDA(At, 1, 0); PG8_STAGE(PG8_SA(0, 1), a2 + hstep, voffA);
;       PG8_WAIT_L(8); PG8_BAR; PG8_WAIT_L(0); PG8_MMA(0, 0, At, B0); PG8_BAR; PG8_SCHED;
;       PG8_LDB(B1, 1, 1); PG8_STAGE(PG8_SB(1, 0), b3, voffB);
;       PG8_BAR; PG8_WAIT_L(0); PG8_MMA(0, 1, At, B1); PG8_BAR;
;       PG8_LDA(At, 1, 1); PG8_STAGE(PG8_SA(1, 0), a3, voffA);
;       PG8_BAR; PG8_WAIT_L(0); PG8_MMA(1, 0, At, B0); PG8_BAR; PG8_SCHED;
	v_mfma_f32_16x16x32_bf16 v[56:59], v[206:209], v[120:123], v[56:59]
	v_mfma_f32_16x16x32_bf16 v[52:55], v[216:219], v[120:123], v[52:55]
	v_mfma_f32_16x16x32_bf16 v[40:43], v[206:209], v[136:139], v[40:43]
	v_mfma_f32_16x16x32_bf16 v[32:35], v[216:219], v[136:139], v[32:35]
	v_mfma_f32_16x16x32_bf16 v[24:27], v[206:209], v[180:183], v[24:27]
	v_mfma_f32_16x16x32_bf16 v[8:11], v[216:219], v[180:183], v[8:11]
	v_mfma_f32_16x16x32_bf16 v[4:7], v[206:209], v[188:191], v[4:7]
	v_mfma_f32_16x16x32_bf16 v[0:3], v[216:219], v[188:191], v[0:3]
	v_mfma_f32_16x16x32_bf16 v[56:59], v[212:215], v[128:131], v[56:59]
	v_mfma_f32_16x16x32_bf16 v[52:55], v[220:223], v[128:131], v[52:55]
	v_mfma_f32_16x16x32_bf16 v[40:43], v[212:215], v[148:151], v[40:43]
	v_mfma_f32_16x16x32_bf16 v[32:35], v[220:223], v[148:151], v[32:35]
	v_mfma_f32_16x16x32_bf16 v[24:27], v[212:215], v[184:187], v[24:27]
	v_mfma_f32_16x16x32_bf16 v[8:11], v[220:223], v[184:187], v[8:11]
	v_mfma_f32_16x16x32_bf16 v[4:7], v[212:215], v[192:195], v[4:7]
	v_mfma_f32_16x16x32_bf16 v[0:3], v[220:223], v[192:195], v[0:3]
	s_barrier
	s_setprio 0
	s_add_i32 s59, 0, 0x18000
	v_add_u32_e32 v76, s59, v198
	ds_read_b128 v[64:67], v76
	ds_read_b128 v[68:71], v76 offset:1024
	ds_read_b128 v[72:75], v76 offset:2048
	ds_read_b128 v[76:79], v76 offset:3072
	s_add_u32 s50, s50, 0x80000
	s_addc_u32 s51, s51, 0
	s_mov_b32 m0, s66
	ds_read_b128 v[120:123], v202 offset:32768
	ds_read_b128 v[128:131], v202 offset:33792
	ds_read_b128 v[180:183], v202 offset:34816
	ds_read_b128 v[184:187], v202 offset:35840
	ds_read_b128 v[188:191], v202 offset:36864
	ds_read_b128 v[192:195], v202 offset:37888
	ds_read_b128 v[206:209], v202 offset:38912
	ds_read_b128 v[212:215], v202 offset:39936
	global_load_lds_dwordx4 v166, s[50:51]
	s_mov_b32 m0, s67
	s_nop 0
	global_load_lds_dwordx4 v162, s[50:51]
	s_waitcnt lgkmcnt(0)
	s_setprio 1
	s_barrier
	v_mfma_f32_16x16x32_bf16 v[136:139], v[64:67], v[120:123], v[156:159]
	v_mfma_f32_16x16x32_bf16 v[156:159], v[68:71], v[128:131], v[136:139]
	v_mfma_f32_16x16x32_bf16 v[136:139], v[72:75], v[120:123], v[144:147]
	v_mfma_f32_16x16x32_bf16 v[144:147], v[76:79], v[128:131], v[136:139]
	v_mfma_f32_16x16x32_bf16 v[136:139], v[64:67], v[180:183], v[140:143]
	v_mfma_f32_16x16x32_bf16 v[132:135], v[72:75], v[180:183], v[132:135]
	v_mfma_f32_16x16x32_bf16 v[124:127], v[64:67], v[188:191], v[124:127]
	v_mfma_f32_16x16x32_bf16 v[116:119], v[72:75], v[188:191], v[116:119]
	v_mfma_f32_16x16x32_bf16 v[112:115], v[64:67], v[206:209], v[112:115]
	v_mfma_f32_16x16x32_bf16 v[108:111], v[72:75], v[206:209], v[108:111]
	v_mfma_f32_16x16x32_bf16 v[140:143], v[68:71], v[184:187], v[136:139]
	v_mfma_f32_16x16x32_bf16 v[132:135], v[76:79], v[184:187], v[132:135]
	v_mfma_f32_16x16x32_bf16 v[124:127], v[68:71], v[192:195], v[124:127]
	v_mfma_f32_16x16x32_bf16 v[116:119], v[76:79], v[192:195], v[116:119]
	v_mfma_f32_16x16x32_bf16 v[112:115], v[68:71], v[212:215], v[112:115]
	v_mfma_f32_16x16x32_bf16 v[108:111], v[76:79], v[212:215], v[108:111]
	s_barrier
	s_setprio 0
	s_add_i32 s50, 0, 0x1c000
	v_add_u32_e32 v136, s50, v198
	s_add_i32 s51, s59, s62
	ds_read_b128 v[216:219], v136
	ds_read_b128 v[220:223], v136 offset:1024
	ds_read_b128 v[224:227], v136 offset:2048
	ds_read_b128 v[228:231], v136 offset:3072
	s_mov_b32 m0, s51
	s_nop 0
	global_load_lds_dwordx4 v164, s[98:99]
	s_add_i32 m0, s51, 0x2000
	s_nop 0
	global_load_lds_dwordx4 v160, s[98:99]
	s_waitcnt lgkmcnt(0)
	s_setprio 1
	s_barrier
	v_mfma_f32_16x16x32_bf16 v[80:83], v[224:227], v[120:123], v[80:83]
	v_mfma_f32_16x16x32_bf16 v[136:139], v[216:219], v[120:123], v[152:155]
	v_mfma_f32_16x16x32_bf16 v[148:151], v[228:231], v[128:131], v[80:83]
	v_mfma_f32_16x16x32_bf16 v[80:83], v[216:219], v[180:183], v[84:87]
	v_mfma_f32_16x16x32_bf16 v[152:155], v[220:223], v[128:131], v[136:139]
	v_mfma_f32_16x16x32_bf16 v[136:139], v[220:223], v[184:187], v[80:83]
	v_mfma_f32_16x16x32_bf16 v[80:83], v[224:227], v[180:183], v[88:91]
	v_mfma_f32_16x16x32_bf16 v[128:131], v[228:231], v[184:187], v[80:83]
	v_mfma_f32_16x16x32_bf16 v[80:83], v[216:219], v[188:191], v[92:95]
	v_mfma_f32_16x16x32_bf16 v[120:123], v[220:223], v[192:195], v[80:83]
	v_mfma_f32_16x16x32_bf16 v[80:83], v[224:227], v[188:191], v[104:107]
	v_mfma_f32_16x16x32_bf16 v[104:107], v[228:231], v[192:195], v[80:83]
	v_mfma_f32_16x16x32_bf16 v[80:83], v[216:219], v[206:209], v[100:103]
	v_mfma_f32_16x16x32_bf16 v[100:103], v[220:223], v[212:215], v[80:83]
	v_mfma_f32_16x16x32_bf16 v[80:83], v[224:227], v[206:209], v[96:99]
	v_mfma_f32_16x16x32_bf16 v[96:99], v[228:231], v[212:215], v[80:83]
	s_barrier
	s_setprio 0
	s_mov_b32 m0, s55
	s_nop 2
	ds_read_b128 v[80:83], v202 offset:49152
	ds_read_b128 v[84:87], v202 offset:50176
	ds_read_b128 v[88:91], v202 offset:51200
	ds_read_b128 v[92:95], v202 offset:52224
	ds_read_b128 v[180:183], v202 offset:53248
	ds_read_b128 v[184:187], v202 offset:54272
	ds_read_b128 v[188:191], v202 offset:55296
	ds_read_b128 v[192:195], v202 offset:56320
	global_load_lds_dwordx4 v166, s[100:101]
	s_mov_b32 m0, s68
	s_nop 0
	global_load_lds_dwordx4 v162, s[100:101]
	s_waitcnt lgkmcnt(0)
	s_setprio 1
	s_barrier
; #define PG8_STAGE(bufoff, gbase, voff) do { _Pragma("unroll") for (int _i = 0; _i < 2; ++_i) \
;     __builtin_amdgcn_global_load_lds((const unsigned*)((const char*)(gbase) + (voff)[_i]), (LAS unsigned*)(lds + (bufoff) + ldsw + _i * 8192), 16, 0, 0); } while (0)
; #define PG8_MMA(ai, bj, At, Bt) do { __builtin_amdgcn_s_setprio(1); _Pragma("unroll") for (int m = 0; m < 4; ++m) _Pragma("unroll") for (int n = 0; n < 2; ++n) _Pragma("unroll") for (int k = 0; k < 2; ++k) \
;     acc[ai][bj][m][n] = __builtin_amdgcn_mfma_f32_16x16x32_bf16(Bt[n][k], At[m][k], acc[ai][bj][m][n], 0, 0, 0); __builtin_amdgcn_s_setprio(0); } while (0)
; #define PG8_WAIT_V(n) asm volatile("s_waitcnt vmcnt(" #n ")" ::: "memory")
; #define PG8_WAIT_L(n) asm volatile("s_waitcnt lgkmcnt(" #n ")" ::: "memory")
; #define PG8_BAR __builtin_amdgcn_s_barrier()
; #define PG8_SCHED __builtin_amdgcn_sched_barrier(0)
;   DI void operator()(const f32x4 (&acc)[2][2][4][2], const Unit& u, int wr, int wc, int fr, int fq) const {
;     const int col = u.pn * 128 + wc * 32 + 8 * fq;
;     float w0[8], w1[8], w2[8], bb[8];
; #pragma unroll
;     for (int e = 0; e < 8; ++e) { w0[e] = cw[col + e]; w1[e] = cw[5632 + col + e]; w2[e] = cw[2 * 5632 + col + e]; bb[e] = cb[col + e]; }
; #pragma unroll
;     for (int ai = 0; ai < 2; ++ai) {
;       const int row0 = u.pm * BM + ai * HALF + wr * 64, span = row0 >> 6;
;       float rsv[4];
; #pragma unroll
;       for (int m = 0; m < 4; ++m) rsv[m] = row_rstd(ssq, row0 + 16 * m + fr, fq);
; template <class Epi, class Sched = StaticOrder>
; DI void gemm_phase(LAS unsigned char* lds, const Gemm g, const Sched& S, const Epi& E) {
;     ...
;       PG8_BAR; PG8_WAIT_L(0); PG8_MMA(1, 0, At, B0); PG8_BAR; PG8_SCHED;
;       PG8_STAGE(PG8_SB(1, 1), b3 + hstep, voffB);
;       PG8_WAIT_V(6); PG8_BAR; PG8_MMA(1, 1, At, B1); PG8_BAR;
	v_mfma_f32_16x16x32_bf16 v[60:63], v[64:67], v[80:83], v[60:63]
	v_mfma_f32_16x16x32_bf16 v[48:51], v[72:75], v[80:83], v[48:51]
	v_mfma_f32_16x16x32_bf16 v[44:47], v[64:67], v[88:91], v[44:47]
	v_mfma_f32_16x16x32_bf16 v[36:39], v[72:75], v[88:91], v[36:39]
	v_mfma_f32_16x16x32_bf16 v[28:31], v[64:67], v[180:183], v[28:31]
	v_mfma_f32_16x16x32_bf16 v[20:23], v[72:75], v[180:183], v[20:23]
	v_mfma_f32_16x16x32_bf16 v[16:19], v[64:67], v[188:191], v[16:19]
	v_mfma_f32_16x16x32_bf16 v[12:15], v[72:75], v[188:191], v[12:15]
	v_mfma_f32_16x16x32_bf16 v[60:63], v[68:71], v[84:87], v[60:63]
	v_mfma_f32_16x16x32_bf16 v[48:51], v[76:79], v[84:87], v[48:51]
	v_mfma_f32_16x16x32_bf16 v[44:47], v[68:71], v[92:95], v[44:47]
	v_mfma_f32_16x16x32_bf16 v[36:39], v[76:79], v[92:95], v[36:39]
	v_mfma_f32_16x16x32_bf16 v[28:31], v[68:71], v[184:187], v[28:31]
	v_mfma_f32_16x16x32_bf16 v[20:23], v[76:79], v[184:187], v[20:23]
	v_mfma_f32_16x16x32_bf16 v[16:19], v[68:71], v[192:195], v[16:19]
	v_mfma_f32_16x16x32_bf16 v[12:15], v[76:79], v[192:195], v[12:15]
	s_barrier
	s_setprio 0
	s_add_u32 s48, s48, 0x80080
	s_addc_u32 s49, s49, 0
	s_add_i32 s50, s50, s62
	s_mov_b32 m0, s50
	s_nop 0
	global_load_lds_dwordx4 v164, s[48:49]
	s_add_i32 m0, s50, 0x2000
	s_nop 0
	global_load_lds_dwordx4 v160, s[48:49]
	s_waitcnt vmcnt(6)
	s_add_i32 s58, s58, 2
	s_add_u32 s14, s14, 0x100
	s_addc_u32 s15, s15, 0
	s_add_u32 s52, s52, 0x100
	s_addc_u32 s53, s53, 0
	s_cmp_gt_u32 s58, 29
	s_setprio 1
	s_barrier
	v_mfma_f32_16x16x32_bf16 v[56:59], v[216:219], v[80:83], v[56:59]
	v_mfma_f32_16x16x32_bf16 v[52:55], v[224:227], v[80:83], v[52:55]
	v_mfma_f32_16x16x32_bf16 v[40:43], v[216:219], v[88:91], v[40:43]
	v_mfma_f32_16x16x32_bf16 v[32:35], v[224:227], v[88:91], v[32:35]
	v_mfma_f32_16x16x32_bf16 v[24:27], v[216:219], v[180:183], v[24:27]
	v_mfma_f32_16x16x32_bf16 v[8:11], v[224:227], v[180:183], v[8:11]
	v_mfma_f32_16x16x32_bf16 v[4:7], v[216:219], v[188:191], v[4:7]
	v_mfma_f32_16x16x32_bf16 v[0:3], v[224:227], v[188:191], v[0:3]
	v_mfma_f32_16x16x32_bf16 v[56:59], v[220:223], v[84:87], v[56:59]
	v_mfma_f32_16x16x32_bf16 v[52:55], v[228:231], v[84:87], v[52:55]
	v_mfma_f32_16x16x32_bf16 v[40:43], v[220:223], v[92:95], v[40:43]
	v_mfma_f32_16x16x32_bf16 v[32:35], v[228:231], v[92:95], v[32:35]
	v_mfma_f32_16x16x32_bf16 v[24:27], v[220:223], v[184:187], v[24:27]
	v_mfma_f32_16x16x32_bf16 v[8:11], v[228:231], v[184:187], v[8:11]
	v_mfma_f32_16x16x32_bf16 v[4:7], v[220:223], v[192:195], v[4:7]
	v_mfma_f32_16x16x32_bf16 v[0:3], v[228:231], v[192:195], v[0:3]
	s_barrier
	s_setprio 0
	s_cbranch_scc0 .LBB0_1277
	s_lshl_b32 s39, s12, 8
	s_add_i32 s39, s39, s54
	v_or_b32_e32 v190, s39, v179
	v_ashrrev_i32_e32 v191, 31, v190
	v_lshlrev_b64 v[64:65], 7, v[190:191]
	v_or_b32_e32 v188, 16, v190
	v_lshl_add_u64 v[64:65], v[168:169], 0, v[64:65]
	v_ashrrev_i32_e32 v189, 31, v188
	global_load_dwordx4 v[192:195], v[64:65], off
	global_load_dwordx4 v[206:209], v[64:65], off offset:16
	v_lshlrev_b64 v[64:65], 7, v[188:189]
	v_lshl_add_u64 v[64:65], v[168:169], 0, v[64:65]
	global_load_dwordx4 v[212:215], v[64:65], off
	global_load_dwordx4 v[216:219], v[64:65], off offset:16
	v_or_b32_e32 v186, 32, v190
	v_ashrrev_i32_e32 v187, 31, v186
	v_lshlrev_b64 v[64:65], 7, v[186:187]
	v_or_b32_e32 v184, 48, v190
	v_lshl_add_u64 v[64:65], v[168:169], 0, v[64:65]
	v_ashrrev_i32_e32 v185, 31, v184
	global_load_dwordx4 v[220:223], v[64:65], off
	global_load_dwordx4 v[224:227], v[64:65], off offset:16
	v_lshlrev_b64 v[64:65], 7, v[184:185]
	v_lshl_add_u64 v[64:65], v[168:169], 0, v[64:65]
	global_load_dwordx4 v[228:231], v[64:65], off
	global_load_dwordx4 v[232:235], v[64:65], off offset:16
	v_lshl_or_b32 v180, s13, 7, v200
	v_and_b32_e32 v65, 64, v204
	v_xor_b32_e32 v64, 16, v204
	v_ashrrev_i32_e32 v181, 31, v180
	v_add_u32_e32 v65, 64, v65
	v_xor_b32_e32 v66, 32, v204
	v_lshlrev_b64 v[182:183], 2, v[180:181]
	v_cmp_lt_i32_e32 vcc, v64, v65
	v_lshl_add_u64 v[88:89], s[16:17], 0, v[182:183]
	v_lshl_add_u64 v[72:73], s[18:19], 0, v[182:183]
	v_cndmask_b32_e32 v64, v204, v64, vcc
	v_cmp_lt_i32_e32 vcc, v66, v65
	v_lshl_add_u64 v[74:75], v[88:89], 0, s[30:31]
	v_lshl_add_u64 v[76:77], v[88:89], 0, s[34:35]
	v_cndmask_b32_e32 v65, v204, v66, vcc
	v_add_co_u32_e32 v90, vcc, 0x5000, v88
	v_lshlrev_b32_e32 v187, 2, v64
	s_nop 0
	v_addc_co_u32_e32 v91, vcc, 0, v89, vcc
	v_add_co_u32_e32 v92, vcc, 0xb000, v88
	v_lshlrev_b32_e32 v185, 2, v65
	s_nop 0
	v_addc_co_u32_e32 v93, vcc, 0, v89, vcc
	global_load_dwordx4 v[64:67], v[88:89], off offset:16
	global_load_dwordx4 v[80:83], v[88:89], off
	global_load_dwordx4 v[68:71], v[72:73], off offset:16
	global_load_dwordx4 v[84:87], v[72:73], off
	s_nop 0
	global_load_dwordx4 v[72:75], v[74:75], off offset:16
	s_nop 0
	global_load_dwordx4 v[76:79], v[76:77], off offset:16
	s_nop 0
	global_load_dwordx4 v[88:91], v[90:91], off offset:2048
	s_nop 0
	global_load_dwordx4 v[92:95], v[92:93], off
	v_mov_b32_e32 v211, 0
	v_mov_b32_e32 v205, 0
	s_waitcnt vmcnt(0)
	v_mov_b32_e32 v196, v192
	v_mov_b32_e32 v197, v206
	v_mov_b32_e32 v206, v193
	v_mov_b32_e32 v192, v194
	v_mov_b32_e32 v193, v208
	v_mov_b32_e32 v208, v195
	v_pk_add_f32 v[194:195], v[196:197], v[206:207]
	v_pk_add_f32 v[192:193], v[192:193], v[208:209]
	v_mov_b32_e32 v196, v212
	v_mov_b32_e32 v197, v216
	v_mov_b32_e32 v216, v213
	v_mov_b32_e32 v206, v214
	v_mov_b32_e32 v207, v218
	v_mov_b32_e32 v218, v215
	v_pk_add_f32 v[192:193], v[194:195], v[192:193]
	v_pk_add_f32 v[194:195], v[196:197], v[216:217]
	v_pk_add_f32 v[196:197], v[206:207], v[218:219]
	v_mov_b32_e32 v208, v220
	v_pk_add_f32 v[194:195], v[194:195], v[196:197]
	v_mov_b32_e32 v197, v192
	v_mov_b32_e32 v196, v194
	v_mov_b32_e32 v192, v195
	v_pk_add_f32 v[192:193], v[196:197], v[192:193]
	ds_bpermute_b32 v195, v187, v193
	ds_bpermute_b32 v194, v187, v192
	v_mov_b32_e32 v209, v224
	v_mov_b32_e32 v224, v221
	v_mov_b32_e32 v212, v222
	v_mov_b32_e32 v213, v226
	s_waitcnt lgkmcnt(0)
; DI unsigned pack2(float lo, float hi) { f32x2 v = {lo, hi}; bf16v2 r = __builtin_convertvector(v, bf16v2); return __builtin_bit_cast(unsigned, r); }
; DI float silu_f(float x) { return x * sigmoid_f(x); }
; DI float dpp_ror1(float v) { return __int_as_float(__builtin_amdgcn_update_dpp(0, __float_as_int(v), 0x121, 0xf, 0xf, false)); }
; DI float dpp_ror2(float v) { return __int_as_float(__builtin_amdgcn_update_dpp(0, __float_as_int(v), 0x122, 0xf, 0xf, false)); }
;   DI void operator()(const f32x4 (&acc)[2][2][4][2], const Unit& u, int wr, int wc, int fr, int fq) const {
;     ...
;       for (int m = 0; m < 4; ++m) rsv[m] = row_rstd(ssq, row0 + 16 * m + fr, fq);
;       float p1[8], p2[8];
; #pragma unroll
;       for (int e = 0; e < 8; ++e) { p1[e] = 0.f; p2[e] = 0.f; }
; #pragma unroll
;       for (int m = 0; m < 4; ++m) {
;         float g[8], uu[8], a[8];
;         const float rs = rsv[m];
; #pragma unroll
;         for (int e = 0; e < 4; ++e) { g[e] = acc[ai][0][m][0][e] * rs; g[4 + e] = acc[ai][0][m][1][e] * rs; uu[e] = acc[ai][1][m][0][e] * rs; uu[4 + e] = acc[ai][1][m][1][e] * rs; }
; #pragma unroll
;         for (int e = 0; e < 8; ++e) {
;           const float x1 = dpp_ror1(g[e]), x2 = dpp_ror2(g[e]);
;           const float pr1 = (fr == 0) ? p1[e] : x1, pr2 = (fr < 2) ? p2[e] : x2;
;           a[e] = w2[e] * g[e] + w1[e] * pr1 + w0[e] * pr2 + bb[e];
;           p1[e] = x1; p2[e] = x2;
;         }
;         if (m == 0 && fr < 2) {
;           float* ha = headA + (size_t)(span * 2 + fr) * 5632 + col; float* hu = headU + (size_t)(span * 2 + fr) * 5632 + col;
;           *(f32x4*)ha = (f32x4){a[0], a[1], a[2], a[3]}; *(f32x4*)(ha + 4) = (f32x4){a[4], a[5], a[6], a[7]};
;           *(f32x4*)hu = (f32x4){uu[0], uu[1], uu[2], uu[3]}; *(f32x4*)(hu + 4) = (f32x4){uu[4], uu[5], uu[6], uu[7]};
;         } else {
;           u32x4 w;
;           w.x = pack2(silu_f(a[0]) * uu[0], silu_f(a[1]) * uu[1]);
;           w.y = pack2(silu_f(a[2]) * uu[2], silu_f(a[3]) * uu[3]);
;           w.z = pack2(silu_f(a[4]) * uu[4], silu_f(a[5]) * uu[5]);
;           w.w = pack2(silu_f(a[6]) * uu[6], silu_f(a[7]) * uu[7]);
;           *(u32x4*)(H + (size_t)(row0 + 16 * m + fr) * 5632 + col) = w;
;         }
	v_pk_add_f32 v[192:193], v[192:193], v[194:195]
	ds_bpermute_b32 v195, v185, v193
	ds_bpermute_b32 v194, v185, v192
	v_mov_b32_e32 v226, v223
	v_mov_b32_e32 v196, v228
	v_mov_b32_e32 v197, v232
	v_mov_b32_e32 v232, v229
	s_waitcnt lgkmcnt(0)
	v_pk_add_f32 v[192:193], v[192:193], v[194:195]
	v_mov_b32_e32 v206, v230
	v_pk_fma_f32 v[192:193], v[192:193], s[36:37], v[178:179] op_sel_hi:[1,0,0]
	v_mov_b32_e32 v207, v234
	v_mul_f32_e32 v189, 0x4b800000, v193
	v_cmp_gt_f32_e64 s[12:13], s74, v193
	v_mov_b32_e32 v234, v231
	v_pk_add_f32 v[208:209], v[208:209], v[224:225]
	v_cndmask_b32_e64 v189, v193, v189, s[12:13]
	v_rsq_f32_e32 v189, v189
	v_pk_add_f32 v[212:213], v[212:213], v[226:227]
	v_pk_add_f32 v[196:197], v[196:197], v[232:233]
	v_pk_add_f32 v[194:195], v[206:207], v[234:235]
	v_mul_f32_e32 v191, 0x45800000, v189
	v_cndmask_b32_e64 v220, v189, v191, s[12:13]
	v_pk_add_f32 v[208:209], v[208:209], v[212:213]
	v_pk_add_f32 v[194:195], v[196:197], v[194:195]
	v_pk_mul_f32 v[156:157], v[156:157], v[220:221] op_sel_hi:[1,0]
	v_mov_b32_e32 v216, 0
	v_mov_b32_e32 v218, 0
	v_mov_b32_e32 v196, v194
	v_mov_b32_e32 v197, v208
	v_mov_b32_e32 v208, v195
	v_mov_b32_dpp v216, v156 row_ror:1 row_mask:0xf bank_mask:0xf
	v_mov_b32_dpp v218, v157 row_ror:1 row_mask:0xf bank_mask:0xf
	v_pk_add_f32 v[194:195], v[196:197], v[208:209]
	v_cndmask_b32_e64 v207, v218, 0, s[0:1]
	v_cndmask_b32_e64 v206, v216, 0, s[0:1]
	v_pk_mul_f32 v[158:159], v[158:159], v[220:221] op_sel_hi:[1,0]
	v_mov_b32_e32 v212, 0
	v_mov_b32_e32 v214, 0
	ds_bpermute_b32 v197, v187, v195
	ds_bpermute_b32 v196, v187, v194
	v_mov_b32_e32 v215, 0
	v_mov_b32_e32 v217, 0
	v_pk_mul_f32 v[206:207], v[88:89], v[206:207]
	v_mov_b32_dpp v212, v158 row_ror:1 row_mask:0xf bank_mask:0xf
	v_mov_b32_dpp v214, v159 row_ror:1 row_mask:0xf bank_mask:0xf
	v_mov_b32_dpp v215, v156 row_ror:2 row_mask:0xf bank_mask:0xf
	v_mov_b32_dpp v217, v157 row_ror:2 row_mask:0xf bank_mask:0xf
	v_pk_fma_f32 v[156:157], v[92:93], v[156:157], v[206:207]
	v_mov_b32_e32 v213, 0
	v_cndmask_b32_e64 v207, v214, 0, s[0:1]
	v_cndmask_b32_e64 v206, v212, 0, s[0:1]
	v_cndmask_b32_e64 v209, v217, 0, s[4:5]
	v_cndmask_b32_e64 v208, v215, 0, s[4:5]
	v_mov_b32_dpp v211, v158 row_ror:2 row_mask:0xf bank_mask:0xf
	v_mov_b32_dpp v213, v159 row_ror:2 row_mask:0xf bank_mask:0xf
	v_pk_mul_f32 v[206:207], v[90:91], v[206:207]
	v_pk_fma_f32 v[156:157], v[80:81], v[208:209], v[156:157]
	v_cndmask_b32_e64 v209, v213, 0, s[4:5]
	v_cndmask_b32_e64 v208, v211, 0, s[4:5]
	v_pk_fma_f32 v[158:159], v[94:95], v[158:159], v[206:207]
	v_pk_mul_f32 v[144:145], v[144:145], v[220:221] op_sel_hi:[1,0]
	v_pk_fma_f32 v[158:159], v[82:83], v[208:209], v[158:159]
	v_mov_b32_e32 v207, 0
	v_mov_b32_e32 v209, 0
	v_pk_mul_f32 v[146:147], v[146:147], v[220:221] op_sel_hi:[1,0]
	v_mov_b32_e32 v191, 0
	s_waitcnt lgkmcnt(0)
	v_pk_add_f32 v[194:195], v[194:195], v[196:197]
	v_mov_b32_dpp v207, v144 row_ror:1 row_mask:0xf bank_mask:0xf
	v_mov_b32_dpp v209, v145 row_ror:1 row_mask:0xf bank_mask:0xf
	v_mov_b32_dpp v191, v146 row_ror:1 row_mask:0xf bank_mask:0xf
	v_mov_b32_dpp v205, v147 row_ror:1 row_mask:0xf bank_mask:0xf
	ds_bpermute_b32 v197, v185, v195
	ds_bpermute_b32 v196, v185, v194
	v_pk_mul_f32 v[152:153], v[152:153], v[220:221] op_sel_hi:[1,0]
	v_pk_mul_f32 v[148:149], v[148:149], v[220:221] op_sel_hi:[1,0]
	v_pk_mul_f32 v[154:155], v[154:155], v[220:221] op_sel_hi:[1,0]
	v_pk_mul_f32 v[150:151], v[150:151], v[220:221] op_sel_hi:[1,0]
	v_mov_b32_e32 v206, 0
	v_mov_b32_e32 v208, 0
	v_cndmask_b32_e64 v223, v209, 0, s[0:1]
	v_cndmask_b32_e64 v222, v207, 0, s[0:1]
	v_mov_b32_e32 v189, 0
	v_mov_b32_e32 v193, 0
	v_cndmask_b32_e64 v221, v205, 0, s[0:1]
	v_cndmask_b32_e64 v220, v191, 0, s[0:1]
	v_mov_b32_dpp v206, v144 row_ror:2 row_mask:0xf bank_mask:0xf
	v_mov_b32_dpp v208, v145 row_ror:2 row_mask:0xf bank_mask:0xf
	v_pk_mul_f32 v[222:223], v[72:73], v[222:223]
	v_mov_b32_dpp v189, v146 row_ror:2 row_mask:0xf bank_mask:0xf
	v_mov_b32_dpp v193, v147 row_ror:2 row_mask:0xf bank_mask:0xf
	v_pk_mul_f32 v[220:221], v[74:75], v[220:221]
	v_cndmask_b32_e64 v225, v208, 0, s[4:5]
	v_cndmask_b32_e64 v224, v206, 0, s[4:5]
	v_pk_fma_f32 v[144:145], v[76:77], v[144:145], v[222:223]
	v_cndmask_b32_e64 v223, v193, 0, s[4:5]
	v_cndmask_b32_e64 v222, v189, 0, s[4:5]
	v_pk_fma_f32 v[146:147], v[78:79], v[146:147], v[220:221]
	v_pk_fma_f32 v[144:145], v[64:65], v[224:225], v[144:145]
	v_pk_fma_f32 v[146:147], v[66:67], v[222:223], v[146:147]
	v_cmp_gt_f32_e32 vcc, s74, v192
	v_pk_add_f32 v[156:157], v[84:85], v[156:157]
	v_pk_add_f32 v[158:159], v[86:87], v[158:159]
	v_pk_add_f32 v[144:145], v[68:69], v[144:145]
	v_pk_add_f32 v[146:147], v[70:71], v[146:147]
	s_and_saveexec_b64 s[12:13], s[10:11]
	s_xor_b64 s[12:13], exec, s[12:13]
	s_cbranch_execz .LBB0_1280
	v_mul_f32_e32 v219, 0xbfb8aa3b, v156
	v_exp_f32_e32 v219, v219
	v_mul_f32_e32 v220, 0xbfb8aa3b, v157
	v_exp_f32_e32 v220, v220
	v_mul_f32_e32 v222, 0xbfb8aa3b, v159
	v_add_f32_e32 v219, 1.0, v219
	v_exp_f32_e32 v223, v222
	v_add_f32_e32 v221, 1.0, v220
	v_rcp_f32_e32 v220, v219
	v_mul_f32_e32 v219, 0xbfb8aa3b, v158
	v_exp_f32_e32 v219, v219
	v_rcp_f32_e32 v221, v221
	v_add_f32_e32 v219, 1.0, v219
	v_rcp_f32_e32 v222, v219
	v_add_f32_e32 v219, 1.0, v223
	v_rcp_f32_e32 v223, v219
	v_pk_mul_f32 v[156:157], v[156:157], v[220:221]
	s_nop 0
	v_pk_mul_f32 v[152:153], v[152:153], v[156:157]
	v_pk_mul_f32 v[156:157], v[158:159], v[222:223]
	v_cvt_pk_bf16_f32 v152, v152, v153
	v_mul_f32_e32 v153, 0xbfb8aa3b, v144
	v_pk_mul_f32 v[154:155], v[154:155], v[156:157]
	v_exp_f32_e32 v156, v153
	v_mul_f32_e32 v153, 0xbfb8aa3b, v145
	v_exp_f32_e32 v157, v153
	v_cvt_pk_bf16_f32 v153, v154, v155
	v_add_f32_e32 v154, 1.0, v156
	v_mul_f32_e32 v156, 0xbfb8aa3b, v146
	v_add_f32_e32 v155, 1.0, v157
	v_mul_f32_e32 v157, 0xbfb8aa3b, v147
	v_exp_f32_e32 v156, v156
	v_exp_f32_e32 v157, v157
	v_rcp_f32_e32 v154, v154
	v_rcp_f32_e32 v155, v155
	v_add_f32_e32 v156, 1.0, v156
	v_add_f32_e32 v157, 1.0, v157
	v_rcp_f32_e32 v156, v156
	v_rcp_f32_e32 v157, v157
	v_pk_mul_f32 v[144:145], v[144:145], v[154:155]
	s_nop 0
	v_pk_mul_f32 v[144:145], v[148:149], v[144:145]
	s_nop 0
	v_cvt_pk_bf16_f32 v154, v144, v145
	v_pk_mul_f32 v[144:145], v[146:147], v[156:157]
	s_nop 0
	v_pk_mul_f32 v[144:145], v[150:151], v[144:145]
	s_nop 0
	v_cvt_pk_bf16_f32 v155, v144, v145
	v_mov_b64_e32 v[144:145], s[20:21]
	v_mad_i64_i32 v[144:145], s[14:15], v190, s75, v[144:145]
	v_lshl_add_u64 v[144:145], v[180:181], 1, v[144:145]
	global_store_dwordx4 v[144:145], v[152:155], off

; #define PG8_STAGE(bufoff, gbase, voff) do { _Pragma("unroll") for (int _i = 0; _i < 2; ++_i) \
;     __builtin_amdgcn_global_load_lds((const unsigned*)((const char*)(gbase) + (voff)[_i]), (LAS unsigned*)(lds + (bufoff) + ldsw + _i * 8192), 16, 0, 0); } while (0)
; #define PG8_LDA(dst, b, h) do { _Pragma("unroll") for (int m = 0; m < 4; ++m) _Pragma("unroll") for (int k = 0; k < 2; ++k) dst[m][k] = *(const LAS bf16x8*)(lds + PG8_SA(b, h) + aoff + m * 2048 + k * 1024); } while (0)
; #define PG8_LDB(dst, b, h) do { _Pragma("unroll") for (int n = 0; n < 2; ++n) _Pragma("unroll") for (int k = 0; k < 2; ++k) dst[n][k] = *(const LAS bf16x8*)(lds + PG8_SB(b, h) + boff + n * 2048 + k * 1024); } while (0)
; #define PG8_MMA(ai, bj, At, Bt) do { __builtin_amdgcn_s_setprio(1); _Pragma("unroll") for (int m = 0; m < 4; ++m) _Pragma("unroll") for (int n = 0; n < 2; ++n) _Pragma("unroll") for (int k = 0; k < 2; ++k) \
;     acc[ai][bj][m][n] = __builtin_amdgcn_mfma_f32_16x16x32_bf16(Bt[n][k], At[m][k], acc[ai][bj][m][n], 0, 0, 0); __builtin_amdgcn_s_setprio(0); } while (0)
; #define PG8_WAIT_V(n) asm volatile("s_waitcnt vmcnt(" #n ")" ::: "memory")
; #define PG8_WAIT_L(n) asm volatile("s_waitcnt lgkmcnt(" #n ")" ::: "memory")
; #define PG8_BAR __builtin_amdgcn_s_barrier()
; #define PG8_SCHED __builtin_amdgcn_sched_barrier(0)
; template <class Epi, class Sched = StaticOrder>
; DI void gemm_phase(LAS unsigned char* lds, const Gemm g, const Sched& S, const Epi& E) {
;     ...
;       PG8_LDB(B0, 0, 0); PG8_SCHED; PG8_LDA(At, 0, 0); PG8_STAGE(PG8_SA(1, 1), a1 + hstep, voffA);
;       PG8_WAIT_L(8); PG8_BAR; PG8_WAIT_L(0); PG8_MMA(0, 0, At, B0); PG8_BAR; PG8_SCHED;
;       PG8_LDB(B1, 0, 1); PG8_STAGE(PG8_SB(0, 0), b2, voffB);
;       PG8_BAR; PG8_WAIT_L(0); PG8_MMA(0, 1, At, B1); PG8_BAR;
;       PG8_LDA(At, 0, 1); PG8_STAGE(PG8_SA(0, 0), a2, voffA);
;       PG8_BAR; PG8_WAIT_L(0); PG8_MMA(1, 0, At, B0); PG8_BAR; PG8_SCHED;
;       PG8_STAGE(PG8_SB(0, 1), b2 + hstep, voffB);
;       PG8_WAIT_V(6); PG8_BAR; PG8_MMA(1, 1, At, B1); PG8_BAR;
.LBB0_1424:
	ds_read_b128 v[144:147], v159
	ds_read_b128 v[148:151], v159 offset:1024
	ds_read_b128 v[152:155], v159 offset:2048
	ds_read_b128 v[162:165], v159 offset:3072
	s_add_u32 s18, s16, 0xffea0080
	s_addc_u32 s19, s17, -1
	s_cmpk_eq_i32 s47, 0x54
	s_cselect_b32 s21, s3, s19
	s_cselect_b32 s20, s2, s18
	s_cselect_b32 s19, s5, s46
	s_cselect_b32 s18, s4, s45
	s_add_i32 m0, s30, 0xc000
	ds_read_b128 v[166:169], v160
	ds_read_b128 v[170:173], v160 offset:1024
	ds_read_b128 v[174:177], v160 offset:2048
	ds_read_b128 v[178:181], v160 offset:3072
	ds_read_b128 v[182:185], v160 offset:4096
	ds_read_b128 v[186:189], v160 offset:5120
	ds_read_b128 v[190:193], v160 offset:6144
	ds_read_b128 v[194:197], v160 offset:7168
	global_load_lds_dwordx4 v136, s[16:17]
	s_add_i32 m0, s30, 0xe000
	s_nop 0
	global_load_lds_dwordx4 v138, s[16:17]
	s_waitcnt lgkmcnt(0)
	s_setprio 1
	s_barrier
	v_mfma_f32_16x16x32_bf16 v[124:127], v[144:147], v[166:169], v[124:127]
	v_mfma_f32_16x16x32_bf16 v[120:123], v[152:155], v[166:169], v[120:123]
	v_mfma_f32_16x16x32_bf16 v[116:119], v[144:147], v[174:177], v[116:119]
	v_mfma_f32_16x16x32_bf16 v[112:115], v[152:155], v[174:177], v[112:115]
	v_mfma_f32_16x16x32_bf16 v[104:107], v[144:147], v[182:185], v[104:107]
	v_mfma_f32_16x16x32_bf16 v[96:99], v[152:155], v[182:185], v[96:99]
	v_mfma_f32_16x16x32_bf16 v[88:91], v[144:147], v[190:193], v[88:91]
	v_mfma_f32_16x16x32_bf16 v[80:83], v[152:155], v[190:193], v[80:83]
	v_mfma_f32_16x16x32_bf16 v[124:127], v[148:151], v[170:173], v[124:127]
	v_mfma_f32_16x16x32_bf16 v[120:123], v[162:165], v[170:173], v[120:123]
	v_mfma_f32_16x16x32_bf16 v[116:119], v[148:151], v[178:181], v[116:119]
	v_mfma_f32_16x16x32_bf16 v[112:115], v[162:165], v[178:181], v[112:115]
	v_mfma_f32_16x16x32_bf16 v[104:107], v[148:151], v[186:189], v[104:107]
	v_mfma_f32_16x16x32_bf16 v[96:99], v[162:165], v[186:189], v[96:99]
	v_mfma_f32_16x16x32_bf16 v[88:91], v[148:151], v[194:197], v[88:91]
	v_mfma_f32_16x16x32_bf16 v[80:83], v[162:165], v[194:197], v[80:83]
	s_barrier
	s_setprio 0
	s_add_i32 s48, s39, s28
	s_add_u32 s98, s18, 0x80
	s_addc_u32 s99, s19, 0
	s_add_u32 s100, s20, 0x80
	s_addc_u32 s101, s21, 0
	s_mov_b32 m0, s48
	ds_read_b128 v[198:201], v161
	ds_read_b128 v[202:205], v161 offset:1024
	ds_read_b128 v[206:209], v161 offset:2048
	ds_read_b128 v[210:213], v161 offset:3072
	global_load_lds_dwordx4 v132, s[18:19]
	s_add_i32 m0, s48, 0x2000
	s_nop 0
	global_load_lds_dwordx4 v128, s[18:19]
	s_waitcnt lgkmcnt(0)
	s_setprio 1
	s_barrier
	v_mfma_f32_16x16x32_bf16 v[108:111], v[198:201], v[166:169], v[108:111]
	v_mfma_f32_16x16x32_bf16 v[100:103], v[206:209], v[166:169], v[100:103]
	v_mfma_f32_16x16x32_bf16 v[92:95], v[198:201], v[174:177], v[92:95]
	v_mfma_f32_16x16x32_bf16 v[84:87], v[206:209], v[174:177], v[84:87]
	v_mfma_f32_16x16x32_bf16 v[76:79], v[198:201], v[182:185], v[76:79]
	v_mfma_f32_16x16x32_bf16 v[72:75], v[206:209], v[182:185], v[72:75]
	v_mfma_f32_16x16x32_bf16 v[68:71], v[198:201], v[190:193], v[68:71]
	v_mfma_f32_16x16x32_bf16 v[64:67], v[206:209], v[190:193], v[64:67]
	v_mfma_f32_16x16x32_bf16 v[108:111], v[202:205], v[170:173], v[108:111]
	v_mfma_f32_16x16x32_bf16 v[100:103], v[210:213], v[170:173], v[100:103]
	v_mfma_f32_16x16x32_bf16 v[92:95], v[202:205], v[178:181], v[92:95]
	v_mfma_f32_16x16x32_bf16 v[84:87], v[210:213], v[178:181], v[84:87]
	v_mfma_f32_16x16x32_bf16 v[76:79], v[202:205], v[186:189], v[76:79]
	v_mfma_f32_16x16x32_bf16 v[72:75], v[210:213], v[186:189], v[72:75]
	v_mfma_f32_16x16x32_bf16 v[68:71], v[202:205], v[194:197], v[68:71]
	v_mfma_f32_16x16x32_bf16 v[64:67], v[210:213], v[194:197], v[64:67]
	s_barrier
	s_setprio 0
	s_mov_b32 m0, s30
	ds_read_b128 v[166:169], v160 offset:16384
	ds_read_b128 v[170:173], v160 offset:17408
	ds_read_b128 v[174:177], v160 offset:18432
	ds_read_b128 v[178:181], v160 offset:19456
	ds_read_b128 v[182:185], v160 offset:20480
	ds_read_b128 v[186:189], v160 offset:21504
	ds_read_b128 v[190:193], v160 offset:22528
	ds_read_b128 v[194:197], v160 offset:23552
	global_load_lds_dwordx4 v134, s[20:21]
	s_mov_b32 m0, s31
	s_nop 0
	global_load_lds_dwordx4 v130, s[20:21]
	s_waitcnt lgkmcnt(0)
	s_setprio 1
	s_barrier
	v_mfma_f32_16x16x32_bf16 v[60:63], v[144:147], v[166:169], v[60:63]
	v_mfma_f32_16x16x32_bf16 v[56:59], v[152:155], v[166:169], v[56:59]
	v_mfma_f32_16x16x32_bf16 v[52:55], v[144:147], v[174:177], v[52:55]
	v_mfma_f32_16x16x32_bf16 v[44:47], v[152:155], v[174:177], v[44:47]
	v_mfma_f32_16x16x32_bf16 v[36:39], v[144:147], v[182:185], v[36:39]
	v_mfma_f32_16x16x32_bf16 v[28:31], v[152:155], v[182:185], v[28:31]
	v_mfma_f32_16x16x32_bf16 v[20:23], v[144:147], v[190:193], v[20:23]
	v_mfma_f32_16x16x32_bf16 v[12:15], v[152:155], v[190:193], v[12:15]
	v_mfma_f32_16x16x32_bf16 v[60:63], v[148:151], v[170:173], v[60:63]
	v_mfma_f32_16x16x32_bf16 v[56:59], v[162:165], v[170:173], v[56:59]
	v_mfma_f32_16x16x32_bf16 v[52:55], v[148:151], v[178:181], v[52:55]
	v_mfma_f32_16x16x32_bf16 v[44:47], v[162:165], v[178:181], v[44:47]
	v_mfma_f32_16x16x32_bf16 v[36:39], v[148:151], v[186:189], v[36:39]
	v_mfma_f32_16x16x32_bf16 v[28:31], v[162:165], v[186:189], v[28:31]
	v_mfma_f32_16x16x32_bf16 v[20:23], v[148:151], v[194:197], v[20:23]
	v_mfma_f32_16x16x32_bf16 v[12:15], v[162:165], v[194:197], v[12:15]
	s_barrier
	s_setprio 0
	s_add_u32 s48, s18, 0x160000
	s_addc_u32 s49, s19, 0
	s_add_i32 s50, s40, s28
	s_mov_b32 m0, s50
	s_nop 0
	global_load_lds_dwordx4 v132, s[48:49]
	s_add_i32 m0, s50, 0x2000
	s_nop 0
	global_load_lds_dwordx4 v128, s[48:49]
	s_waitcnt vmcnt(6)
	s_setprio 1
	s_barrier
; #define PG8_STAGE(bufoff, gbase, voff) do { _Pragma("unroll") for (int _i = 0; _i < 2; ++_i) \
;     __builtin_amdgcn_global_load_lds((const unsigned*)((const char*)(gbase) + (voff)[_i]), (LAS unsigned*)(lds + (bufoff) + ldsw + _i * 8192), 16, 0, 0); } while (0)
; #define PG8_LDA(dst, b, h) do { _Pragma("unroll") for (int m = 0; m < 4; ++m) _Pragma("unroll") for (int k = 0; k < 2; ++k) dst[m][k] = *(const LAS bf16x8*)(lds + PG8_SA(b, h) + aoff + m * 2048 + k * 1024); } while (0)
; #define PG8_LDB(dst, b, h) do { _Pragma("unroll") for (int n = 0; n < 2; ++n) _Pragma("unroll") for (int k = 0; k < 2; ++k) dst[n][k] = *(const LAS bf16x8*)(lds + PG8_SB(b, h) + boff + n * 2048 + k * 1024); } while (0)
; #define PG8_MMA(ai, bj, At, Bt) do { __builtin_amdgcn_s_setprio(1); _Pragma("unroll") for (int m = 0; m < 4; ++m) _Pragma("unroll") for (int n = 0; n < 2; ++n) _Pragma("unroll") for (int k = 0; k < 2; ++k) \
;     acc[ai][bj][m][n] = __builtin_amdgcn_mfma_f32_16x16x32_bf16(Bt[n][k], At[m][k], acc[ai][bj][m][n], 0, 0, 0); __builtin_amdgcn_s_setprio(0); } while (0)
; #define PG8_WAIT_V(n) asm volatile("s_waitcnt vmcnt(" #n ")" ::: "memory")
; #define PG8_WAIT_L(n) asm volatile("s_waitcnt lgkmcnt(" #n ")" ::: "memory")
; #define PG8_BAR __builtin_amdgcn_s_barrier()
; #define PG8_SCHED __builtin_amdgcn_sched_barrier(0)
; template <class Epi, class Sched = StaticOrder>
; DI void gemm_phase(LAS unsigned char* lds, const Gemm g, const Sched& S, const Epi& E) {
;     ...
;       PG8_WAIT_V(6); PG8_BAR; PG8_MMA(1, 1, At, B1); PG8_BAR;
;       PG8_LDB(B0, 1, 0); PG8_SCHED; PG8_LDA(At, 1, 0); PG8_STAGE(PG8_SA(0, 1), a2 + hstep, voffA);
;       PG8_WAIT_L(8); PG8_BAR; PG8_WAIT_L(0); PG8_MMA(0, 0, At, B0); PG8_BAR; PG8_SCHED;
;       PG8_LDB(B1, 1, 1); PG8_STAGE(PG8_SB(1, 0), b3, voffB);
;       PG8_BAR; PG8_WAIT_L(0); PG8_MMA(0, 1, At, B1); PG8_BAR;
;       PG8_LDA(At, 1, 1); PG8_STAGE(PG8_SA(1, 0), a3, voffA);
;       PG8_BAR; PG8_WAIT_L(0); PG8_MMA(1, 0, At, B0); PG8_BAR; PG8_SCHED;
	v_mfma_f32_16x16x32_bf16 v[48:51], v[198:201], v[166:169], v[48:51]
	v_mfma_f32_16x16x32_bf16 v[40:43], v[206:209], v[166:169], v[40:43]
	v_mfma_f32_16x16x32_bf16 v[32:35], v[198:201], v[174:177], v[32:35]
	v_mfma_f32_16x16x32_bf16 v[24:27], v[206:209], v[174:177], v[24:27]
	v_mfma_f32_16x16x32_bf16 v[16:19], v[198:201], v[182:185], v[16:19]
	v_mfma_f32_16x16x32_bf16 v[8:11], v[206:209], v[182:185], v[8:11]
	v_mfma_f32_16x16x32_bf16 v[4:7], v[198:201], v[190:193], v[4:7]
	v_mfma_f32_16x16x32_bf16 v[0:3], v[206:209], v[190:193], v[0:3]
	v_mfma_f32_16x16x32_bf16 v[48:51], v[202:205], v[170:173], v[48:51]
	v_mfma_f32_16x16x32_bf16 v[40:43], v[210:213], v[170:173], v[40:43]
	v_mfma_f32_16x16x32_bf16 v[32:35], v[202:205], v[178:181], v[32:35]
	v_mfma_f32_16x16x32_bf16 v[24:27], v[210:213], v[178:181], v[24:27]
	v_mfma_f32_16x16x32_bf16 v[16:19], v[202:205], v[186:189], v[16:19]
	v_mfma_f32_16x16x32_bf16 v[8:11], v[210:213], v[186:189], v[8:11]
	v_mfma_f32_16x16x32_bf16 v[4:7], v[202:205], v[194:197], v[4:7]
	v_mfma_f32_16x16x32_bf16 v[0:3], v[210:213], v[194:197], v[0:3]
	s_barrier
	s_setprio 0
	s_add_i32 s48, 0, 0x18000
	v_add_u32_e32 v162, s48, v157
	ds_read_b128 v[144:147], v162
	ds_read_b128 v[148:151], v162 offset:1024
	ds_read_b128 v[152:155], v162 offset:2048
	ds_read_b128 v[162:165], v162 offset:3072
	s_add_u32 s20, s20, 0x160000
	s_addc_u32 s21, s21, 0
	s_mov_b32 m0, s33
	ds_read_b128 v[166:169], v160 offset:32768
	ds_read_b128 v[170:173], v160 offset:33792
	ds_read_b128 v[174:177], v160 offset:34816
	ds_read_b128 v[178:181], v160 offset:35840
	ds_read_b128 v[182:185], v160 offset:36864
	ds_read_b128 v[186:189], v160 offset:37888
	ds_read_b128 v[190:193], v160 offset:38912
	ds_read_b128 v[194:197], v160 offset:39936
	global_load_lds_dwordx4 v134, s[20:21]
	s_mov_b32 m0, s34
	s_nop 0
	global_load_lds_dwordx4 v130, s[20:21]
	s_waitcnt lgkmcnt(0)
	s_setprio 1
	s_barrier
	v_mfma_f32_16x16x32_bf16 v[124:127], v[144:147], v[166:169], v[124:127]
	v_mfma_f32_16x16x32_bf16 v[120:123], v[152:155], v[166:169], v[120:123]
	v_mfma_f32_16x16x32_bf16 v[116:119], v[144:147], v[174:177], v[116:119]
	v_mfma_f32_16x16x32_bf16 v[112:115], v[152:155], v[174:177], v[112:115]
	v_mfma_f32_16x16x32_bf16 v[104:107], v[144:147], v[182:185], v[104:107]
	v_mfma_f32_16x16x32_bf16 v[96:99], v[152:155], v[182:185], v[96:99]
	v_mfma_f32_16x16x32_bf16 v[88:91], v[144:147], v[190:193], v[88:91]
	v_mfma_f32_16x16x32_bf16 v[80:83], v[152:155], v[190:193], v[80:83]
	v_mfma_f32_16x16x32_bf16 v[124:127], v[148:151], v[170:173], v[124:127]
	v_mfma_f32_16x16x32_bf16 v[120:123], v[162:165], v[170:173], v[120:123]
	v_mfma_f32_16x16x32_bf16 v[116:119], v[148:151], v[178:181], v[116:119]
	v_mfma_f32_16x16x32_bf16 v[112:115], v[162:165], v[178:181], v[112:115]
	v_mfma_f32_16x16x32_bf16 v[104:107], v[148:151], v[186:189], v[104:107]
	v_mfma_f32_16x16x32_bf16 v[96:99], v[162:165], v[186:189], v[96:99]
	v_mfma_f32_16x16x32_bf16 v[88:91], v[148:151], v[194:197], v[88:91]
	v_mfma_f32_16x16x32_bf16 v[80:83], v[162:165], v[194:197], v[80:83]
	s_barrier
	s_setprio 0
	s_add_i32 s20, 0, 0x1c000
	s_add_i32 s21, s48, s28
	v_add_u32_e32 v210, s20, v157
	s_mov_b32 m0, s21
	ds_read_b128 v[198:201], v210
	ds_read_b128 v[202:205], v210 offset:1024
	ds_read_b128 v[206:209], v210 offset:2048
	ds_read_b128 v[210:213], v210 offset:3072
	global_load_lds_dwordx4 v132, s[98:99]
	s_add_i32 m0, s21, 0x2000
	s_nop 0
	global_load_lds_dwordx4 v128, s[98:99]
	s_waitcnt lgkmcnt(0)
	s_setprio 1
	s_barrier
	v_mfma_f32_16x16x32_bf16 v[108:111], v[198:201], v[166:169], v[108:111]
	v_mfma_f32_16x16x32_bf16 v[100:103], v[206:209], v[166:169], v[100:103]
	v_mfma_f32_16x16x32_bf16 v[92:95], v[198:201], v[174:177], v[92:95]
	v_mfma_f32_16x16x32_bf16 v[84:87], v[206:209], v[174:177], v[84:87]
	v_mfma_f32_16x16x32_bf16 v[76:79], v[198:201], v[182:185], v[76:79]
	v_mfma_f32_16x16x32_bf16 v[72:75], v[206:209], v[182:185], v[72:75]
	v_mfma_f32_16x16x32_bf16 v[68:71], v[198:201], v[190:193], v[68:71]
	v_mfma_f32_16x16x32_bf16 v[64:67], v[206:209], v[190:193], v[64:67]
	v_mfma_f32_16x16x32_bf16 v[108:111], v[202:205], v[170:173], v[108:111]
	v_mfma_f32_16x16x32_bf16 v[100:103], v[210:213], v[170:173], v[100:103]
	v_mfma_f32_16x16x32_bf16 v[92:95], v[202:205], v[178:181], v[92:95]
	v_mfma_f32_16x16x32_bf16 v[84:87], v[210:213], v[178:181], v[84:87]
	v_mfma_f32_16x16x32_bf16 v[76:79], v[202:205], v[186:189], v[76:79]
	v_mfma_f32_16x16x32_bf16 v[72:75], v[210:213], v[186:189], v[72:75]
	v_mfma_f32_16x16x32_bf16 v[68:71], v[202:205], v[194:197], v[68:71]
	v_mfma_f32_16x16x32_bf16 v[64:67], v[210:213], v[194:197], v[64:67]
	s_barrier
	s_setprio 0
	s_mov_b32 m0, s35
	ds_read_b128 v[166:169], v160 offset:49152
	ds_read_b128 v[170:173], v160 offset:50176
	ds_read_b128 v[174:177], v160 offset:51200
	ds_read_b128 v[178:181], v160 offset:52224
	ds_read_b128 v[182:185], v160 offset:53248
	ds_read_b128 v[186:189], v160 offset:54272
	ds_read_b128 v[190:193], v160 offset:55296
	ds_read_b128 v[194:197], v160 offset:56320
	global_load_lds_dwordx4 v134, s[100:101]
	s_mov_b32 m0, s36
	s_nop 0
	global_load_lds_dwordx4 v130, s[100:101]
	s_waitcnt lgkmcnt(0)
	s_setprio 1
	s_barrier
; #define PG8_STAGE(bufoff, gbase, voff) do { _Pragma("unroll") for (int _i = 0; _i < 2; ++_i) \
;     __builtin_amdgcn_global_load_lds((const unsigned*)((const char*)(gbase) + (voff)[_i]), (LAS unsigned*)(lds + (bufoff) + ldsw + _i * 8192), 16, 0, 0); } while (0)
; #define PG8_MMA(ai, bj, At, Bt) do { __builtin_amdgcn_s_setprio(1); _Pragma("unroll") for (int m = 0; m < 4; ++m) _Pragma("unroll") for (int n = 0; n < 2; ++n) _Pragma("unroll") for (int k = 0; k < 2; ++k) \
;     acc[ai][bj][m][n] = __builtin_amdgcn_mfma_f32_16x16x32_bf16(Bt[n][k], At[m][k], acc[ai][bj][m][n], 0, 0, 0); __builtin_amdgcn_s_setprio(0); } while (0)
; #define PG8_WAIT_V(n) asm volatile("s_waitcnt vmcnt(" #n ")" ::: "memory")
; #define PG8_WAIT_L(n) asm volatile("s_waitcnt lgkmcnt(" #n ")" ::: "memory")
; #define PG8_BAR __builtin_amdgcn_s_barrier()
; #define PG8_SCHED __builtin_amdgcn_sched_barrier(0)
;   DI void operator()(const f32x4 (&acc)[2][2][4][2], const Unit& u, int wr, int wc, int fr, int fq) const {
;     const int row0 = u.pm * BM + wr * 64 + fr, col0 = u.pn * BM + wc * 32 + 8 * fq;
; #pragma unroll
;     for (int ai = 0; ai < 2; ++ai) {
;       f32x4 bv[4][2][2];
; #pragma unroll
;       for (int m = 0; m < 4; ++m)
; #pragma unroll
;         for (int bj = 0; bj < 2; ++bj) {
;           const float* bp = base + (size_t)(row0 + ai * HALF + m * 16) * 2048 + col0 + bj * HALF;
;           bv[m][bj][0] = *(const f32x4*)bp; bv[m][bj][1] = *(const f32x4*)(bp + 4);
;         }
; template <class Epi, class Sched = StaticOrder>
; DI void gemm_phase(LAS unsigned char* lds, const Gemm g, const Sched& S, const Epi& E) {
;     ...
;       PG8_BAR; PG8_WAIT_L(0); PG8_MMA(1, 0, At, B0); PG8_BAR; PG8_SCHED;
;       PG8_STAGE(PG8_SB(1, 1), b3 + hstep, voffB);
;       PG8_WAIT_V(6); PG8_BAR; PG8_MMA(1, 1, At, B1); PG8_BAR;
	v_mfma_f32_16x16x32_bf16 v[60:63], v[144:147], v[166:169], v[60:63]
	v_mfma_f32_16x16x32_bf16 v[56:59], v[152:155], v[166:169], v[56:59]
	v_mfma_f32_16x16x32_bf16 v[52:55], v[144:147], v[174:177], v[52:55]
	v_mfma_f32_16x16x32_bf16 v[44:47], v[152:155], v[174:177], v[44:47]
	v_mfma_f32_16x16x32_bf16 v[36:39], v[144:147], v[182:185], v[36:39]
	v_mfma_f32_16x16x32_bf16 v[28:31], v[152:155], v[182:185], v[28:31]
	v_mfma_f32_16x16x32_bf16 v[20:23], v[144:147], v[190:193], v[20:23]
	v_mfma_f32_16x16x32_bf16 v[12:15], v[152:155], v[190:193], v[12:15]
	v_mfma_f32_16x16x32_bf16 v[60:63], v[148:151], v[170:173], v[60:63]
	v_mfma_f32_16x16x32_bf16 v[56:59], v[162:165], v[170:173], v[56:59]
	v_mfma_f32_16x16x32_bf16 v[52:55], v[148:151], v[178:181], v[52:55]
	v_mfma_f32_16x16x32_bf16 v[44:47], v[162:165], v[178:181], v[44:47]
	v_mfma_f32_16x16x32_bf16 v[36:39], v[148:151], v[186:189], v[36:39]
	v_mfma_f32_16x16x32_bf16 v[28:31], v[162:165], v[186:189], v[28:31]
	v_mfma_f32_16x16x32_bf16 v[20:23], v[148:151], v[194:197], v[20:23]
	v_mfma_f32_16x16x32_bf16 v[12:15], v[162:165], v[194:197], v[12:15]
	s_barrier
	s_setprio 0
	s_add_u32 s18, s18, 0x160080
	s_addc_u32 s19, s19, 0
	s_add_i32 s20, s20, s28
	s_mov_b32 m0, s20
	s_nop 0
	global_load_lds_dwordx4 v132, s[18:19]
	s_add_i32 m0, s20, 0x2000
	s_nop 0
	global_load_lds_dwordx4 v128, s[18:19]
	s_waitcnt vmcnt(6)
	s_add_i32 s47, s47, 2
	s_add_u32 s16, s16, 0x100
	s_addc_u32 s17, s17, 0
	s_add_u32 s45, s45, 0x100
	s_addc_u32 s46, s46, 0
	s_cmpk_gt_u32 s47, 0x55
	s_setprio 1
	s_barrier
	v_mfma_f32_16x16x32_bf16 v[48:51], v[198:201], v[166:169], v[48:51]
	v_mfma_f32_16x16x32_bf16 v[40:43], v[206:209], v[166:169], v[40:43]
	v_mfma_f32_16x16x32_bf16 v[32:35], v[198:201], v[174:177], v[32:35]
	v_mfma_f32_16x16x32_bf16 v[24:27], v[206:209], v[174:177], v[24:27]
	v_mfma_f32_16x16x32_bf16 v[16:19], v[198:201], v[182:185], v[16:19]
	v_mfma_f32_16x16x32_bf16 v[8:11], v[206:209], v[182:185], v[8:11]
	v_mfma_f32_16x16x32_bf16 v[4:7], v[198:201], v[190:193], v[4:7]
	v_mfma_f32_16x16x32_bf16 v[0:3], v[206:209], v[190:193], v[0:3]
	v_mfma_f32_16x16x32_bf16 v[48:51], v[202:205], v[170:173], v[48:51]
	v_mfma_f32_16x16x32_bf16 v[40:43], v[210:213], v[170:173], v[40:43]
	v_mfma_f32_16x16x32_bf16 v[32:35], v[202:205], v[178:181], v[32:35]
	v_mfma_f32_16x16x32_bf16 v[24:27], v[210:213], v[178:181], v[24:27]
	v_mfma_f32_16x16x32_bf16 v[16:19], v[202:205], v[186:189], v[16:19]
	v_mfma_f32_16x16x32_bf16 v[8:11], v[210:213], v[186:189], v[8:11]
	v_mfma_f32_16x16x32_bf16 v[4:7], v[202:205], v[194:197], v[4:7]
	v_mfma_f32_16x16x32_bf16 v[0:3], v[210:213], v[194:197], v[0:3]
	s_barrier
	s_setprio 0
	s_cbranch_scc0 .LBB0_1424
	v_lshl_or_b32 v144, s44, 8, v158
	v_lshl_add_u32 v154, s43, 8, v156
	v_ashrrev_i32_e32 v145, 31, v144
	v_lshlrev_b64 v[144:145], 2, v[144:145]
	v_ashrrev_i32_e32 v155, 31, v154
	v_lshl_add_u64 v[146:147], s[54:55], 0, v[144:145]
	v_lshlrev_b64 v[148:149], 13, v[154:155]
	v_or_b32_e32 v174, 16, v154
	v_lshl_add_u64 v[170:171], v[146:147], 0, v[148:149]
	v_ashrrev_i32_e32 v175, 31, v174
	global_load_dwordx4 v[150:153], v[170:171], off offset:16
	global_load_dwordx4 v[162:165], v[170:171], off
	global_load_dwordx4 v[166:169], v[170:171], off offset:528
	s_nop 0
	global_load_dwordx4 v[170:173], v[170:171], off offset:512
	v_lshlrev_b64 v[222:223], 13, v[174:175]
	v_or_b32_e32 v190, 32, v154
	v_lshl_add_u64 v[186:187], v[146:147], 0, v[222:223]
	v_ashrrev_i32_e32 v191, 31, v190
	global_load_dwordx4 v[174:177], v[186:187], off offset:16
	global_load_dwordx4 v[178:181], v[186:187], off
	global_load_dwordx4 v[182:185], v[186:187], off offset:528
	s_nop 0
	global_load_dwordx4 v[186:189], v[186:187], off offset:512
	v_lshlrev_b64 v[224:225], 13, v[190:191]
	v_or_b32_e32 v154, 48, v154
	v_lshl_add_u64 v[202:203], v[146:147], 0, v[224:225]
	v_ashrrev_i32_e32 v155, 31, v154
	global_load_dwordx4 v[190:193], v[202:203], off offset:16
	global_load_dwordx4 v[194:197], v[202:203], off
	global_load_dwordx4 v[198:201], v[202:203], off offset:528
	s_nop 0
	global_load_dwordx4 v[202:205], v[202:203], off offset:512
	v_lshlrev_b64 v[154:155], 13, v[154:155]
	v_lshl_add_u64 v[218:219], v[146:147], 0, v[154:155]
	global_load_dwordx4 v[206:209], v[218:219], off offset:16
	global_load_dwordx4 v[210:213], v[218:219], off
	global_load_dwordx4 v[214:217], v[218:219], off offset:528
	s_nop 0
	global_load_dwordx4 v[218:221], v[218:219], off offset:512
	s_and_b64 vcc, exec, s[0:1]
	s_mov_b32 s44, s41
	s_mov_b32 s43, s42
	s_mov_b64 s[18:19], s[4:5]
	s_mov_b64 s[16:17], s[2:3]
	s_waitcnt vmcnt(0)
; #define PG8_WAIT_V(n) asm volatile("s_waitcnt vmcnt(" #n ")" ::: "memory")
; #define PG8_BAR __builtin_amdgcn_s_barrier()
;   DI void operator()(const f32x4 (&acc)[2][2][4][2], const Unit& u, int wr, int wc, int fr, int fq) const {
;     ...
;     for (int ai = 0; ai < 2; ++ai) {
;       f32x4 bv[4][2][2];
; #pragma unroll
;       for (int m = 0; m < 4; ++m)
; #pragma unroll
;         for (int bj = 0; bj < 2; ++bj) {
;           const float* bp = base + (size_t)(row0 + ai * HALF + m * 16) * 2048 + col0 + bj * HALF;
;           bv[m][bj][0] = *(const f32x4*)bp; bv[m][bj][1] = *(const f32x4*)(bp + 4);
;         }
; #pragma unroll
;       for (int m = 0; m < 4; ++m) {
;         const int row = row0 + ai * HALF + m * 16;
;         const size_t off = (size_t)row * 2048 + col0;
;         float ss = 0.f;
; #pragma unroll
;         for (int bj = 0; bj < 2; ++bj) {
;           const f32x4 v0 = acc[ai][bj][m][0] + bv[m][bj][0], v1 = acc[ai][bj][m][1] + bv[m][bj][1];
;           *(f32x4*)(C + off + bj * HALF) = v0; *(f32x4*)(C + off + bj * HALF + 4) = v1;
; template <class Epi, class Sched = StaticOrder>
; DI void gemm_phase(LAS unsigned char* lds, const Gemm g, const Sched& S, const Epi& E) {
;     ...
;   PG8_WAIT_V(0);
;   if (wr == 0) PG8_BAR;
;   PG8_BAR;
	v_pk_add_f32 v[120:121], v[120:121], v[150:151]
	v_lshl_add_u64 v[150:151], s[54:55], 0, v[148:149]
	v_pk_add_f32 v[126:127], v[126:127], v[164:165]
	v_pk_add_f32 v[124:125], v[124:125], v[162:163]
	v_lshl_add_u64 v[150:151], v[150:151], 0, v[144:145]
	v_pk_add_f32 v[110:111], v[110:111], v[172:173]
	v_pk_add_f32 v[108:109], v[108:109], v[170:171]
	v_pk_add_f32 v[122:123], v[122:123], v[152:153]
	global_store_dwordx4 v[150:151], v[124:127], off
	global_store_dwordx4 v[150:151], v[120:123], off offset:16
	v_pk_add_f32 v[102:103], v[102:103], v[168:169]
	v_pk_add_f32 v[100:101], v[100:101], v[166:167]
	global_store_dwordx4 v[150:151], v[108:111], off offset:512
	global_store_dwordx4 v[150:151], v[100:103], off offset:528
	v_pk_add_f32 v[94:95], v[94:95], v[188:189]
	v_pk_add_f32 v[108:109], v[112:113], v[174:175]
	v_lshl_add_u64 v[112:113], s[54:55], 0, v[222:223]
	v_pk_add_f32 v[102:103], v[118:119], v[180:181]
	v_pk_add_f32 v[100:101], v[116:117], v[178:179]
	v_lshl_add_u64 v[112:113], v[112:113], 0, v[144:145]
	v_pk_add_f32 v[92:93], v[92:93], v[186:187]
	v_pk_add_f32 v[110:111], v[114:115], v[176:177]
	global_store_dwordx4 v[112:113], v[100:103], off
	global_store_dwordx4 v[112:113], v[108:111], off offset:16
	v_pk_add_f32 v[86:87], v[86:87], v[184:185]
	v_pk_add_f32 v[84:85], v[84:85], v[182:183]
	global_store_dwordx4 v[112:113], v[92:95], off offset:512
	global_store_dwordx4 v[112:113], v[84:87], off offset:528
	v_pk_add_f32 v[78:79], v[78:79], v[204:205]
	v_pk_add_f32 v[92:93], v[96:97], v[190:191]
	v_lshl_add_u64 v[96:97], s[54:55], 0, v[224:225]
	v_pk_add_f32 v[86:87], v[106:107], v[196:197]
	v_pk_add_f32 v[84:85], v[104:105], v[194:195]
	v_lshl_add_u64 v[96:97], v[96:97], 0, v[144:145]
	v_pk_add_f32 v[76:77], v[76:77], v[202:203]
	v_pk_add_f32 v[94:95], v[98:99], v[192:193]
	global_store_dwordx4 v[96:97], v[84:87], off
	global_store_dwordx4 v[96:97], v[92:95], off offset:16
	v_pk_add_f32 v[74:75], v[74:75], v[200:201]
	v_pk_add_f32 v[72:73], v[72:73], v[198:199]
	global_store_dwordx4 v[96:97], v[76:79], off offset:512
	global_store_dwordx4 v[96:97], v[72:75], off offset:528
	v_pk_add_f32 v[70:71], v[70:71], v[220:221]
	v_pk_add_f32 v[76:77], v[80:81], v[206:207]
	v_lshl_add_u64 v[80:81], s[54:55], 0, v[154:155]
	v_pk_add_f32 v[74:75], v[90:91], v[212:213]
	v_pk_add_f32 v[72:73], v[88:89], v[210:211]
	v_lshl_add_u64 v[80:81], v[80:81], 0, v[144:145]
	v_pk_add_f32 v[68:69], v[68:69], v[218:219]
	v_pk_add_f32 v[64:65], v[64:65], v[214:215]
	v_lshl_add_u64 v[154:155], v[148:149], 0, s[10:11]
	v_pk_add_f32 v[78:79], v[82:83], v[208:209]
	global_store_dwordx4 v[80:81], v[72:75], off
	global_store_dwordx4 v[80:81], v[76:79], off offset:16
	v_pk_add_f32 v[66:67], v[66:67], v[216:217]
	global_store_dwordx4 v[80:81], v[68:71], off offset:512
	global_store_dwordx4 v[80:81], v[64:67], off offset:528
	v_lshl_add_u64 v[152:153], v[148:149], 0, s[12:13]
	v_lshl_add_u64 v[150:151], v[148:149], 0, s[14:15]
	v_lshl_add_u64 v[64:65], v[146:147], 0, v[154:155]
	global_load_dwordx4 v[108:111], v[64:65], off offset:16
	global_load_dwordx4 v[120:123], v[64:65], off
	global_load_dwordx4 v[92:95], v[64:65], off offset:528
	global_load_dwordx4 v[100:103], v[64:65], off offset:512
	v_lshl_add_u64 v[64:65], v[146:147], 0, v[152:153]
	global_load_dwordx4 v[88:91], v[64:65], off offset:16
	global_load_dwordx4 v[96:99], v[64:65], off
	global_load_dwordx4 v[76:79], v[64:65], off offset:528
	global_load_dwordx4 v[84:87], v[64:65], off offset:512
	v_lshl_add_u64 v[68:69], v[146:147], 0, v[150:151]
	global_load_dwordx4 v[72:75], v[68:69], off offset:16
	global_load_dwordx4 v[80:83], v[68:69], off
	global_load_dwordx4 v[64:67], v[68:69], off offset:528
	s_nop 0
	global_load_dwordx4 v[68:71], v[68:69], off offset:512
	v_lshl_add_u64 v[148:149], v[148:149], 0, s[6:7]
	v_lshl_add_u64 v[112:113], v[146:147], 0, v[148:149]
	global_load_dwordx4 v[116:119], v[112:113], off offset:16
	global_load_dwordx4 v[124:127], v[112:113], off
	global_load_dwordx4 v[104:107], v[112:113], off offset:528
	s_nop 0
	global_load_dwordx4 v[112:115], v[112:113], off offset:512
	s_waitcnt vmcnt(0)
	v_pk_add_f32 v[56:57], v[56:57], v[108:109]
	v_lshl_add_u64 v[108:109], s[54:55], 0, v[154:155]
	v_pk_add_f32 v[62:63], v[62:63], v[122:123]
	v_pk_add_f32 v[60:61], v[60:61], v[120:121]
	v_lshl_add_u64 v[108:109], v[108:109], 0, v[144:145]
	v_pk_add_f32 v[50:51], v[50:51], v[102:103]
	v_pk_add_f32 v[48:49], v[48:49], v[100:101]
	v_pk_add_f32 v[58:59], v[58:59], v[110:111]
	global_store_dwordx4 v[108:109], v[60:63], off
	global_store_dwordx4 v[108:109], v[56:59], off offset:16
	v_pk_add_f32 v[42:43], v[42:43], v[94:95]
	v_pk_add_f32 v[40:41], v[40:41], v[92:93]
	global_store_dwordx4 v[108:109], v[48:51], off offset:512
	global_store_dwordx4 v[108:109], v[40:43], off offset:528
	v_pk_add_f32 v[34:35], v[34:35], v[86:87]
	v_lshl_add_u64 v[48:49], s[54:55], 0, v[152:153]
	v_pk_add_f32 v[42:43], v[54:55], v[98:99]
	v_pk_add_f32 v[40:41], v[52:53], v[96:97]
	v_lshl_add_u64 v[48:49], v[48:49], 0, v[144:145]
	v_pk_add_f32 v[32:33], v[32:33], v[84:85]
	v_pk_add_f32 v[46:47], v[46:47], v[90:91]
	v_pk_add_f32 v[44:45], v[44:45], v[88:89]
	global_store_dwordx4 v[48:49], v[40:43], off
	global_store_dwordx4 v[48:49], v[44:47], off offset:16
	v_pk_add_f32 v[26:27], v[26:27], v[78:79]
	v_pk_add_f32 v[24:25], v[24:25], v[76:77]
	global_store_dwordx4 v[48:49], v[32:35], off offset:512
	global_store_dwordx4 v[48:49], v[24:27], off offset:528
	v_pk_add_f32 v[18:19], v[18:19], v[70:71]
	v_lshl_add_u64 v[32:33], s[54:55], 0, v[150:151]
	v_pk_add_f32 v[26:27], v[38:39], v[82:83]
	v_pk_add_f32 v[24:25], v[36:37], v[80:81]
	v_lshl_add_u64 v[32:33], v[32:33], 0, v[144:145]
	v_pk_add_f32 v[16:17], v[16:17], v[68:69]
	v_pk_add_f32 v[30:31], v[30:31], v[74:75]
	v_pk_add_f32 v[28:29], v[28:29], v[72:73]
	global_store_dwordx4 v[32:33], v[24:27], off
	global_store_dwordx4 v[32:33], v[28:31], off offset:16
	v_pk_add_f32 v[10:11], v[10:11], v[66:67]
	v_pk_add_f32 v[8:9], v[8:9], v[64:65]
	global_store_dwordx4 v[32:33], v[16:19], off offset:512
	global_store_dwordx4 v[32:33], v[8:11], off offset:528
	v_pk_add_f32 v[6:7], v[6:7], v[114:115]
	v_lshl_add_u64 v[16:17], s[54:55], 0, v[148:149]
	v_pk_add_f32 v[10:11], v[22:23], v[126:127]
	v_pk_add_f32 v[8:9], v[20:21], v[124:125]
	v_lshl_add_u64 v[16:17], v[16:17], 0, v[144:145]
	v_pk_add_f32 v[4:5], v[4:5], v[112:113]
	v_pk_add_f32 v[14:15], v[14:15], v[118:119]
	v_pk_add_f32 v[12:13], v[12:13], v[116:117]
	global_store_dwordx4 v[16:17], v[8:11], off
	global_store_dwordx4 v[16:17], v[12:15], off offset:16
	v_pk_add_f32 v[2:3], v[2:3], v[106:107]
	v_pk_add_f32 v[0:1], v[0:1], v[104:105]
	global_store_dwordx4 v[16:17], v[4:7], off offset:512
	global_store_dwordx4 v[16:17], v[0:3], off offset:528
	s_cbranch_vccz .LBB0_1417
	s_waitcnt vmcnt(0)
	s_cmpk_gt_u32 s23, 0xff
	s_cbranch_scc1 .LBB0_1428
	s_barrier
